# loop-edge rotation (7.11): loop-back barrier becomes the loop head in the 6 GEMM K-loops, back-branch taken before the barrier, exit path gets its own barrier
# baseline (speedup 1.0000x reference)
.LBB0_377:
	s_barrier
	s_add_u32 s75, s46, 0xfff80080
	s_addc_u32 s80, s47, -1
	s_add_i32 s96, 0, 0x10000
	v_add_u32_e32 v76, s96, v239
	ds_read_b128 v[64:67], v76
	ds_read_b128 v[68:71], v76 offset:1024
	ds_read_b128 v[72:75], v76 offset:2048
	ds_read_b128 v[76:79], v76 offset:3072
	s_cmp_eq_u32 s73, 28
	s_cselect_b32 s83, s14, s80
	s_cselect_b32 s82, s15, s75
	s_cselect_b32 s81, s67, s13
	s_cselect_b32 s80, s68, s12
	ds_read_b128 v[80:83], v248
	ds_read_b128 v[84:87], v248 offset:1024
	ds_read_b128 v[88:91], v248 offset:2048
	ds_read_b128 v[92:95], v248 offset:3072
	ds_read_b128 v[184:187], v248 offset:4096
	ds_read_b128 v[188:191], v248 offset:5120
	ds_read_b128 v[192:195], v248 offset:6144
	ds_read_b128 v[196:199], v248 offset:7168
	s_waitcnt lgkmcnt(8)
	s_barrier
	s_waitcnt lgkmcnt(0)
	s_waitcnt lgkmcnt(0)
	v_mfma_f32_16x16x32_bf16 v[156:159], v[64:67], v[80:83], v[156:159]
	v_mfma_f32_16x16x32_bf16 v[152:155], v[72:75], v[80:83], v[152:155]
	v_mfma_f32_16x16x32_bf16 v[148:151], v[64:67], v[88:91], v[148:151]
	v_mfma_f32_16x16x32_bf16 v[140:143], v[72:75], v[88:91], v[140:143]
	v_mfma_f32_16x16x32_bf16 v[132:135], v[64:67], v[184:187], v[132:135]
	v_mfma_f32_16x16x32_bf16 v[124:127], v[72:75], v[184:187], v[124:127]
	v_mfma_f32_16x16x32_bf16 v[116:119], v[64:67], v[192:195], v[116:119]
	v_mfma_f32_16x16x32_bf16 v[108:111], v[72:75], v[192:195], v[108:111]
	v_mfma_f32_16x16x32_bf16 v[156:159], v[68:71], v[84:87], v[156:159]
	v_mfma_f32_16x16x32_bf16 v[152:155], v[76:79], v[84:87], v[152:155]
	v_mfma_f32_16x16x32_bf16 v[148:151], v[68:71], v[92:95], v[148:151]
	v_mfma_f32_16x16x32_bf16 v[140:143], v[76:79], v[92:95], v[140:143]
	v_mfma_f32_16x16x32_bf16 v[132:135], v[68:71], v[188:191], v[132:135]
	v_mfma_f32_16x16x32_bf16 v[124:127], v[76:79], v[188:191], v[124:127]
	v_mfma_f32_16x16x32_bf16 v[116:119], v[68:71], v[196:199], v[116:119]
	v_mfma_f32_16x16x32_bf16 v[108:111], v[76:79], v[196:199], v[108:111]
	s_barrier
	v_lshl_add_u64 v[200:201], s[46:47], 0, v[180:181]
	s_add_i32 m0, s20, 0xc000
	s_nop 0
	global_load_lds_dwordx4 v[200:201], off
	v_lshl_add_u64 v[200:201], s[46:47], 0, v[182:183]
	s_add_i32 m0, s20, 0xe000
	s_nop 0
	global_load_lds_dwordx4 v[200:201], off
	s_add_i32 s75, 0, 0x14000
	s_add_i32 s96, s96, s19
	v_add_u32_e32 v160, s75, v239
	v_lshl_add_u64 v[224:225], s[80:81], 0, v[174:175]
	s_mov_b32 m0, s96
	ds_read_b128 v[200:203], v160
	ds_read_b128 v[204:207], v160 offset:1024
	ds_read_b128 v[208:211], v160 offset:2048
	ds_read_b128 v[212:215], v160 offset:3072
	global_load_lds_dwordx4 v[224:225], off
	v_lshl_add_u64 v[226:227], s[80:81], 0, v[170:171]
	s_add_i32 m0, s96, 0x2000
	s_nop 0
	global_load_lds_dwordx4 v[226:227], off
	s_barrier
	s_waitcnt lgkmcnt(0)
	s_waitcnt lgkmcnt(0)
	v_mfma_f32_16x16x32_bf16 v[144:147], v[200:203], v[80:83], v[144:147]
	v_mfma_f32_16x16x32_bf16 v[80:83], v[208:211], v[80:83], v[136:139]
	v_mfma_f32_16x16x32_bf16 v[144:147], v[204:207], v[84:87], v[144:147]
	v_mfma_f32_16x16x32_bf16 v[80:83], v[212:215], v[84:87], v[80:83]
	v_mfma_f32_16x16x32_bf16 v[84:87], v[200:203], v[88:91], v[128:131]
	v_mfma_f32_16x16x32_bf16 v[88:91], v[208:211], v[88:91], v[120:123]
	v_mfma_f32_16x16x32_bf16 v[104:107], v[208:211], v[184:187], v[104:107]
	v_mfma_f32_16x16x32_bf16 v[100:103], v[200:203], v[192:195], v[100:103]
	v_mfma_f32_16x16x32_bf16 v[96:99], v[208:211], v[192:195], v[96:99]
	v_mfma_f32_16x16x32_bf16 v[84:87], v[204:207], v[92:95], v[84:87]
	v_mfma_f32_16x16x32_bf16 v[88:91], v[212:215], v[92:95], v[88:91]
	v_mfma_f32_16x16x32_bf16 v[92:95], v[200:203], v[184:187], v[112:115]
	v_mfma_f32_16x16x32_bf16 v[104:107], v[212:215], v[188:191], v[104:107]
	v_mfma_f32_16x16x32_bf16 v[100:103], v[204:207], v[196:199], v[100:103]
	v_mfma_f32_16x16x32_bf16 v[96:99], v[212:215], v[196:199], v[96:99]
	v_mfma_f32_16x16x32_bf16 v[92:95], v[204:207], v[188:191], v[92:95]
	s_mov_b32 m0, s20
	v_lshl_add_u64 v[228:229], s[82:83], 0, v[176:177]
	s_barrier
	ds_read_b128 v[112:115], v248 offset:16384
	ds_read_b128 v[120:123], v248 offset:17408
	ds_read_b128 v[128:131], v248 offset:18432
	ds_read_b128 v[136:139], v248 offset:19456
	ds_read_b128 v[184:187], v248 offset:20480
	ds_read_b128 v[188:191], v248 offset:21504
	ds_read_b128 v[192:195], v248 offset:22528
	ds_read_b128 v[196:199], v248 offset:23552
	global_load_lds_dwordx4 v[228:229], off
	v_lshl_add_u64 v[230:231], s[82:83], 0, v[172:173]
	s_mov_b32 m0, s21
	s_nop 0
	global_load_lds_dwordx4 v[230:231], off
	s_barrier
	s_waitcnt lgkmcnt(0)
	s_waitcnt lgkmcnt(0)
	v_mfma_f32_16x16x32_bf16 v[60:63], v[64:67], v[112:115], v[60:63]
	v_mfma_f32_16x16x32_bf16 v[56:59], v[72:75], v[112:115], v[56:59]
	v_mfma_f32_16x16x32_bf16 v[44:47], v[64:67], v[128:131], v[44:47]
	v_mfma_f32_16x16x32_bf16 v[40:43], v[72:75], v[128:131], v[40:43]
	v_mfma_f32_16x16x32_bf16 v[28:31], v[64:67], v[184:187], v[28:31]
	v_mfma_f32_16x16x32_bf16 v[24:27], v[72:75], v[184:187], v[24:27]
	v_mfma_f32_16x16x32_bf16 v[12:15], v[64:67], v[192:195], v[12:15]
	v_mfma_f32_16x16x32_bf16 v[8:11], v[72:75], v[192:195], v[8:11]
	v_mfma_f32_16x16x32_bf16 v[60:63], v[68:71], v[120:123], v[60:63]
	v_mfma_f32_16x16x32_bf16 v[56:59], v[76:79], v[120:123], v[56:59]
	v_mfma_f32_16x16x32_bf16 v[44:47], v[68:71], v[136:139], v[44:47]
	v_mfma_f32_16x16x32_bf16 v[40:43], v[76:79], v[136:139], v[40:43]
	v_mfma_f32_16x16x32_bf16 v[28:31], v[68:71], v[188:191], v[28:31]
	v_mfma_f32_16x16x32_bf16 v[24:27], v[76:79], v[188:191], v[24:27]
	v_mfma_f32_16x16x32_bf16 v[12:15], v[68:71], v[196:199], v[12:15]
	v_mfma_f32_16x16x32_bf16 v[8:11], v[76:79], v[196:199], v[8:11]
	s_barrier
	s_add_u32 s96, s80, 0x80000
	s_addc_u32 s97, s81, 0
	s_add_i32 s75, s75, s19
	v_lshl_add_u64 v[64:65], s[96:97], 0, v[174:175]
	s_mov_b32 m0, s75
	s_nop 0
	global_load_lds_dwordx4 v[64:65], off
	v_lshl_add_u64 v[64:65], s[96:97], 0, v[170:171]
	s_add_i32 m0, s75, 0x2000
	s_nop 0
	global_load_lds_dwordx4 v[64:65], off
	s_waitcnt vmcnt(6)
	s_barrier
	v_mfma_f32_16x16x32_bf16 v[52:55], v[200:203], v[112:115], v[52:55]
	v_mfma_f32_16x16x32_bf16 v[48:51], v[208:211], v[112:115], v[48:51]
	v_mfma_f32_16x16x32_bf16 v[36:39], v[200:203], v[128:131], v[36:39]
	v_mfma_f32_16x16x32_bf16 v[32:35], v[208:211], v[128:131], v[32:35]
	v_mfma_f32_16x16x32_bf16 v[20:23], v[200:203], v[184:187], v[20:23]
	v_mfma_f32_16x16x32_bf16 v[16:19], v[208:211], v[184:187], v[16:19]
	v_mfma_f32_16x16x32_bf16 v[4:7], v[200:203], v[192:195], v[4:7]
	v_mfma_f32_16x16x32_bf16 v[0:3], v[208:211], v[192:195], v[0:3]
	v_mfma_f32_16x16x32_bf16 v[52:55], v[204:207], v[120:123], v[52:55]
	v_mfma_f32_16x16x32_bf16 v[48:51], v[212:215], v[120:123], v[48:51]
	v_mfma_f32_16x16x32_bf16 v[36:39], v[204:207], v[136:139], v[36:39]
	v_mfma_f32_16x16x32_bf16 v[32:35], v[212:215], v[136:139], v[32:35]
	v_mfma_f32_16x16x32_bf16 v[20:23], v[204:207], v[188:191], v[20:23]
	v_mfma_f32_16x16x32_bf16 v[16:19], v[212:215], v[188:191], v[16:19]
	v_mfma_f32_16x16x32_bf16 v[4:7], v[204:207], v[196:199], v[4:7]
	v_mfma_f32_16x16x32_bf16 v[0:3], v[212:215], v[196:199], v[0:3]
	s_add_i32 s75, 0, 0x18000
	v_add_u32_e32 v76, s75, v239
	s_barrier
	ds_read_b128 v[64:67], v76
	ds_read_b128 v[68:71], v76 offset:1024
	ds_read_b128 v[72:75], v76 offset:2048
	ds_read_b128 v[76:79], v76 offset:3072
	ds_read_b128 v[112:115], v248 offset:32768
	ds_read_b128 v[120:123], v248 offset:33792
	ds_read_b128 v[184:187], v248 offset:34816
	ds_read_b128 v[188:191], v248 offset:35840
	ds_read_b128 v[192:195], v248 offset:36864
	ds_read_b128 v[196:199], v248 offset:37888
	ds_read_b128 v[200:203], v248 offset:38912
	ds_read_b128 v[204:207], v248 offset:39936
	s_waitcnt lgkmcnt(8)
	s_barrier
	s_waitcnt lgkmcnt(0)
	s_waitcnt lgkmcnt(0)
	v_mfma_f32_16x16x32_bf16 v[128:131], v[64:67], v[112:115], v[156:159]
	v_mfma_f32_16x16x32_bf16 v[156:159], v[68:71], v[120:123], v[128:131]
	v_mfma_f32_16x16x32_bf16 v[128:131], v[72:75], v[112:115], v[152:155]
	v_mfma_f32_16x16x32_bf16 v[152:155], v[76:79], v[120:123], v[128:131]
	v_mfma_f32_16x16x32_bf16 v[128:131], v[64:67], v[184:187], v[148:151]
	v_mfma_f32_16x16x32_bf16 v[148:151], v[68:71], v[188:191], v[128:131]
	v_mfma_f32_16x16x32_bf16 v[128:131], v[72:75], v[184:187], v[140:143]
	v_mfma_f32_16x16x32_bf16 v[140:143], v[76:79], v[188:191], v[128:131]
	v_mfma_f32_16x16x32_bf16 v[128:131], v[64:67], v[192:195], v[132:135]
	v_mfma_f32_16x16x32_bf16 v[124:127], v[72:75], v[192:195], v[124:127]
	v_mfma_f32_16x16x32_bf16 v[116:119], v[64:67], v[200:203], v[116:119]
	v_mfma_f32_16x16x32_bf16 v[108:111], v[72:75], v[200:203], v[108:111]
	v_mfma_f32_16x16x32_bf16 v[132:135], v[68:71], v[196:199], v[128:131]
	v_mfma_f32_16x16x32_bf16 v[124:127], v[76:79], v[196:199], v[124:127]
	v_mfma_f32_16x16x32_bf16 v[116:119], v[68:71], v[204:207], v[116:119]
	v_mfma_f32_16x16x32_bf16 v[108:111], v[76:79], v[204:207], v[108:111]
	s_barrier
	s_add_u32 s82, s82, 0x80000
	s_addc_u32 s83, s83, 0
	v_lshl_add_u64 v[128:129], s[82:83], 0, v[176:177]
	s_mov_b32 m0, s22
	s_nop 0
	global_load_lds_dwordx4 v[128:129], off
	v_lshl_add_u64 v[128:129], s[82:83], 0, v[172:173]
	s_mov_b32 m0, s23
	s_nop 0
	global_load_lds_dwordx4 v[128:129], off
	s_add_i32 s82, 0, 0x1c000
	v_add_u32_e32 v128, s82, v239
	s_add_i32 s75, s75, s19
	ds_read_b128 v[208:211], v128
	ds_read_b128 v[212:215], v128 offset:1024
	ds_read_b128 v[216:219], v128 offset:2048
	ds_read_b128 v[220:223], v128 offset:3072
	v_lshl_add_u64 v[128:129], v[224:225], 0, s[92:93]
	s_mov_b32 m0, s75
	s_nop 0
	global_load_lds_dwordx4 v[128:129], off
	v_lshl_add_u64 v[128:129], v[226:227], 0, s[92:93]
	s_add_i32 m0, s75, 0x2000
	s_nop 0
	global_load_lds_dwordx4 v[128:129], off
	s_barrier
	s_waitcnt lgkmcnt(0)
	s_waitcnt lgkmcnt(0)
	v_mfma_f32_16x16x32_bf16 v[80:83], v[216:219], v[112:115], v[80:83]
	v_mfma_f32_16x16x32_bf16 v[128:131], v[208:211], v[112:115], v[144:147]
	v_mfma_f32_16x16x32_bf16 v[136:139], v[220:223], v[120:123], v[80:83]
	v_mfma_f32_16x16x32_bf16 v[80:83], v[208:211], v[184:187], v[84:87]
	v_mfma_f32_16x16x32_bf16 v[144:147], v[212:215], v[120:123], v[128:131]
	v_mfma_f32_16x16x32_bf16 v[128:131], v[212:215], v[188:191], v[80:83]
	v_mfma_f32_16x16x32_bf16 v[80:83], v[216:219], v[184:187], v[88:91]
	v_mfma_f32_16x16x32_bf16 v[120:123], v[220:223], v[188:191], v[80:83]
	v_mfma_f32_16x16x32_bf16 v[80:83], v[208:211], v[192:195], v[92:95]
	v_mfma_f32_16x16x32_bf16 v[112:115], v[212:215], v[196:199], v[80:83]
	v_mfma_f32_16x16x32_bf16 v[80:83], v[216:219], v[192:195], v[104:107]
	v_mfma_f32_16x16x32_bf16 v[104:107], v[220:223], v[196:199], v[80:83]
	v_mfma_f32_16x16x32_bf16 v[80:83], v[208:211], v[200:203], v[100:103]
	v_mfma_f32_16x16x32_bf16 v[100:103], v[212:215], v[204:207], v[80:83]
	v_mfma_f32_16x16x32_bf16 v[80:83], v[216:219], v[200:203], v[96:99]
	v_mfma_f32_16x16x32_bf16 v[96:99], v[220:223], v[204:207], v[80:83]
	s_mov_b32 m0, s25
	v_lshl_add_u64 v[200:201], v[228:229], 0, s[92:93]
	s_barrier
	s_nop 2
	ds_read_b128 v[80:83], v248 offset:49152
	ds_read_b128 v[84:87], v248 offset:50176
	ds_read_b128 v[88:91], v248 offset:51200
	ds_read_b128 v[92:95], v248 offset:52224
	ds_read_b128 v[184:187], v248 offset:53248
	ds_read_b128 v[188:191], v248 offset:54272
	ds_read_b128 v[192:195], v248 offset:55296
	ds_read_b128 v[196:199], v248 offset:56320
	global_load_lds_dwordx4 v[200:201], off
	v_lshl_add_u64 v[200:201], v[230:231], 0, s[92:93]
	s_mov_b32 m0, s26
	s_nop 0
	global_load_lds_dwordx4 v[200:201], off
	s_barrier
	s_waitcnt lgkmcnt(0)
	s_waitcnt lgkmcnt(0)
	v_mfma_f32_16x16x32_bf16 v[60:63], v[64:67], v[80:83], v[60:63]
	v_mfma_f32_16x16x32_bf16 v[56:59], v[72:75], v[80:83], v[56:59]
	v_mfma_f32_16x16x32_bf16 v[44:47], v[64:67], v[88:91], v[44:47]
	v_mfma_f32_16x16x32_bf16 v[40:43], v[72:75], v[88:91], v[40:43]
	v_mfma_f32_16x16x32_bf16 v[28:31], v[64:67], v[184:187], v[28:31]
	v_mfma_f32_16x16x32_bf16 v[24:27], v[72:75], v[184:187], v[24:27]
	v_mfma_f32_16x16x32_bf16 v[12:15], v[64:67], v[192:195], v[12:15]
	v_mfma_f32_16x16x32_bf16 v[8:11], v[72:75], v[192:195], v[8:11]
	v_mfma_f32_16x16x32_bf16 v[60:63], v[68:71], v[84:87], v[60:63]
	v_mfma_f32_16x16x32_bf16 v[56:59], v[76:79], v[84:87], v[56:59]
	v_mfma_f32_16x16x32_bf16 v[44:47], v[68:71], v[92:95], v[44:47]
	v_mfma_f32_16x16x32_bf16 v[40:43], v[76:79], v[92:95], v[40:43]
	v_mfma_f32_16x16x32_bf16 v[28:31], v[68:71], v[188:191], v[28:31]
	v_mfma_f32_16x16x32_bf16 v[24:27], v[76:79], v[188:191], v[24:27]
	v_mfma_f32_16x16x32_bf16 v[12:15], v[68:71], v[196:199], v[12:15]
	v_mfma_f32_16x16x32_bf16 v[8:11], v[76:79], v[196:199], v[8:11]
	s_barrier
	s_add_u32 s80, s80, 0x80080
	s_addc_u32 s81, s81, 0
	s_add_i32 s75, s82, s19
	v_lshl_add_u64 v[64:65], s[80:81], 0, v[174:175]
	s_mov_b32 m0, s75
	s_nop 0
	global_load_lds_dwordx4 v[64:65], off
	v_lshl_add_u64 v[64:65], s[80:81], 0, v[170:171]
	s_add_i32 m0, s75, 0x2000
	s_nop 0
	global_load_lds_dwordx4 v[64:65], off
	s_waitcnt vmcnt(6)
	s_barrier
	v_mfma_f32_16x16x32_bf16 v[52:55], v[208:211], v[80:83], v[52:55]
	v_mfma_f32_16x16x32_bf16 v[48:51], v[216:219], v[80:83], v[48:51]
	v_mfma_f32_16x16x32_bf16 v[36:39], v[208:211], v[88:91], v[36:39]
	v_mfma_f32_16x16x32_bf16 v[32:35], v[216:219], v[88:91], v[32:35]
	v_mfma_f32_16x16x32_bf16 v[20:23], v[208:211], v[184:187], v[20:23]
	v_mfma_f32_16x16x32_bf16 v[16:19], v[216:219], v[184:187], v[16:19]
	v_mfma_f32_16x16x32_bf16 v[4:7], v[208:211], v[192:195], v[4:7]
	v_mfma_f32_16x16x32_bf16 v[0:3], v[216:219], v[192:195], v[0:3]
	v_mfma_f32_16x16x32_bf16 v[52:55], v[212:215], v[84:87], v[52:55]
	v_mfma_f32_16x16x32_bf16 v[48:51], v[220:223], v[84:87], v[48:51]
	v_mfma_f32_16x16x32_bf16 v[36:39], v[212:215], v[92:95], v[36:39]
	v_mfma_f32_16x16x32_bf16 v[32:35], v[220:223], v[92:95], v[32:35]
	v_mfma_f32_16x16x32_bf16 v[20:23], v[212:215], v[188:191], v[20:23]
	v_mfma_f32_16x16x32_bf16 v[16:19], v[220:223], v[188:191], v[16:19]
	v_mfma_f32_16x16x32_bf16 v[4:7], v[212:215], v[196:199], v[4:7]
	v_mfma_f32_16x16x32_bf16 v[0:3], v[220:223], v[196:199], v[0:3]
	s_add_i32 s73, s73, 2
	s_add_u32 s46, s46, 0x100
	s_addc_u32 s47, s47, 0
	s_add_u32 s12, s12, 0x100
	s_addc_u32 s13, s13, 0
	s_cmp_gt_u32 s73, 29
	s_cbranch_scc0 .LBB0_377
	s_barrier
	s_lshl_b32 s14, s45, 8
	v_or_b32_e32 v64, s14, v240
	v_ashrrev_i32_e32 v65, 31, v64
	v_readlane_b32 s12, v255, 15
	v_lshl_add_u32 v184, s66, 8, v238
	v_lshlrev_b64 v[66:67], 2, v[64:65]
	v_readlane_b32 s13, v255, 16
	v_or_b32_e32 v64, 0x80, v64
	v_ashrrev_i32_e32 v65, 31, v64
	v_lshl_add_u64 v[76:77], s[12:13], 0, v[66:67]
	v_lshl_add_u64 v[66:67], s[84:85], 0, v[66:67]
	v_ashrrev_i32_e32 v185, 31, v184
	global_load_dwordx4 v[80:83], v[76:77], off offset:16
	global_load_dwordx4 v[92:95], v[76:77], off
	global_load_dwordx4 v[72:75], v[66:67], off offset:16
	global_load_dwordx4 v[88:91], v[66:67], off
	global_load_dwordx4 v[68:71], v[76:77], off offset:528
	global_load_dwordx4 v[84:87], v[76:77], off offset:512
	v_lshl_add_u64 v[76:77], v[64:65], 2, s[84:85]
	v_lshl_add_u64 v[196:197], v[184:185], 3, s[34:35]
	global_load_dwordx4 v[64:67], v[76:77], off offset:16
	s_nop 0
	global_load_dwordx4 v[76:79], v[76:77], off
	v_add_co_u32_e32 v194, vcc, s89, v196
	global_load_dwordx2 v[186:187], v[196:197], off
	s_nop 0
	v_addc_co_u32_e32 v195, vcc, 0, v197, vcc
	global_load_dwordx2 v[188:189], v[194:195], off
	global_load_dwordx2 v[198:199], v[196:197], off offset:128
	global_load_dwordx2 v[200:201], v[194:195], off offset:128
	global_load_dwordx2 v[202:203], v[196:197], off offset:256
	global_load_dwordx2 v[204:205], v[194:195], off offset:256
	global_load_dwordx2 v[206:207], v[196:197], off offset:384
	global_load_dwordx2 v[208:209], v[194:195], off offset:384
	v_readlane_b32 s96, v255, 3
	s_mov_b64 s[12:13], -1
	s_cmp_gt_i32 s45, 3
	v_readlane_b32 s97, v255, 4
	v_readlane_b32 s82, v255, 5
	v_readlane_b32 s83, v255, 6
	s_waitcnt vmcnt(0)
	v_xor_b32_e32 v231, 0x80000000, v83
	v_xor_b32_e32 v230, 0x80000000, v82
	v_xor_b32_e32 v227, 0x80000000, v71
	v_xor_b32_e32 v226, 0x80000000, v70
	v_xor_b32_e32 v233, 0x80000000, v95
	v_xor_b32_e32 v232, 0x80000000, v94
	v_cvt_f32_u32_e32 v190, v188
	v_xor_b32_e32 v229, 0x80000000, v87
	v_xor_b32_e32 v228, 0x80000000, v86
	v_cvt_f32_u32_e32 v191, v186
	v_cvt_f32_i32_e32 v186, v189
	v_cvt_f32_i32_e32 v187, v187
	v_pk_fma_f32 v[186:187], v[190:191], s[88:89], v[186:187] op_sel_hi:[1,0,1]
	s_nop 0
	v_pk_mul_f32 v[210:211], v[186:187], s[94:95] op_sel_hi:[1,0]
	s_nop 0
	v_fma_f32 v160, -v211, v211, v210
	v_add_f32_e32 v160, 0x3727c5ac, v160
	v_rsq_f32_e32 v160, v160
	v_pk_fma_f32 v[82:83], v[230:231], v[210:211], v[154:155] op_sel:[0,1,0]
	v_pk_fma_f32 v[156:157], v[92:93], v[210:211], v[156:157] op_sel:[0,1,0] neg_lo:[1,0,0] neg_hi:[1,0,0]
	v_pk_fma_f32 v[70:71], v[226:227], v[210:211], v[138:139] op_sel:[0,1,0]
	v_pk_fma_f32 v[190:191], v[82:83], v[160:161], v[74:75] op_sel_hi:[1,0,1]
	v_pk_fma_f32 v[82:83], v[84:85], v[210:211], v[144:145] op_sel:[0,1,0] neg_lo:[1,0,0] neg_hi:[1,0,0]
	v_pk_fma_f32 v[94:95], v[232:233], v[210:211], v[158:159] op_sel:[0,1,0]
	v_pk_fma_f32 v[154:155], v[82:83], v[160:161], v[76:77] op_sel_hi:[1,0,1]
	v_pk_fma_f32 v[82:83], v[68:69], v[210:211], v[136:137] op_sel:[0,1,0] neg_lo:[1,0,0] neg_hi:[1,0,0]
	v_pk_fma_f32 v[188:189], v[156:157], v[160:161], v[88:89] op_sel_hi:[1,0,1]
	v_pk_fma_f32 v[156:157], v[70:71], v[160:161], v[66:67] op_sel_hi:[1,0,1]
	v_pk_fma_f32 v[158:159], v[82:83], v[160:161], v[64:65] op_sel_hi:[1,0,1]
	v_cvt_f32_u32_e32 v70, v200
	v_cvt_f32_u32_e32 v71, v198
	v_cvt_f32_i32_e32 v82, v201
	v_cvt_f32_i32_e32 v83, v199
	v_pk_fma_f32 v[86:87], v[228:229], v[210:211], v[146:147] op_sel:[0,1,0]
	v_pk_fma_f32 v[186:187], v[94:95], v[160:161], v[90:91] op_sel_hi:[1,0,1]
	v_pk_fma_f32 v[94:95], v[80:81], v[210:211], v[152:153] op_sel:[0,1,0] neg_lo:[1,0,0] neg_hi:[1,0,0]
	v_pk_fma_f32 v[70:71], v[70:71], s[88:89], v[82:83] op_sel_hi:[1,0,1]
	v_pk_fma_f32 v[152:153], v[86:87], v[160:161], v[78:79] op_sel_hi:[1,0,1]
	v_pk_mul_f32 v[70:71], v[70:71], s[94:95] op_sel_hi:[1,0]
	v_pk_fma_f32 v[192:193], v[94:95], v[160:161], v[72:73] op_sel_hi:[1,0,1]
	v_fma_f32 v82, -v71, v71, v70
	v_add_f32_e32 v82, 0x3727c5ac, v82
	v_rsq_f32_e32 v82, v82
	v_pk_fma_f32 v[86:87], v[92:93], v[70:71], v[148:149] op_sel:[0,1,0] neg_lo:[1,0,0] neg_hi:[1,0,0]
	v_pk_fma_f32 v[94:95], v[232:233], v[70:71], v[150:151] op_sel:[0,1,0]
	v_pk_fma_f32 v[148:149], v[86:87], v[82:83], v[88:89] op_sel_hi:[1,0,1]
	v_pk_fma_f32 v[86:87], v[80:81], v[70:71], v[140:141] op_sel:[0,1,0] neg_lo:[1,0,0] neg_hi:[1,0,0]
	v_pk_fma_f32 v[144:145], v[94:95], v[82:83], v[90:91] op_sel_hi:[1,0,1]
	v_pk_fma_f32 v[94:95], v[230:231], v[70:71], v[142:143] op_sel:[0,1,0]
	v_pk_fma_f32 v[150:151], v[86:87], v[82:83], v[72:73] op_sel_hi:[1,0,1]
	v_pk_fma_f32 v[86:87], v[84:85], v[70:71], v[128:129] op_sel:[0,1,0] neg_lo:[1,0,0] neg_hi:[1,0,0]
	v_pk_fma_f32 v[146:147], v[94:95], v[82:83], v[74:75] op_sel_hi:[1,0,1]
	v_pk_fma_f32 v[94:95], v[228:229], v[70:71], v[130:131] op_sel:[0,1,0]
	v_pk_fma_f32 v[140:141], v[86:87], v[82:83], v[76:77] op_sel_hi:[1,0,1]
	v_pk_fma_f32 v[86:87], v[68:69], v[70:71], v[120:121] op_sel:[0,1,0] neg_lo:[1,0,0] neg_hi:[1,0,0]
	v_pk_fma_f32 v[70:71], v[226:227], v[70:71], v[122:123] op_sel:[0,1,0]
	v_pk_fma_f32 v[136:137], v[94:95], v[82:83], v[78:79] op_sel_hi:[1,0,1]
	v_pk_fma_f32 v[138:139], v[70:71], v[82:83], v[66:67] op_sel_hi:[1,0,1]
	v_pk_fma_f32 v[142:143], v[86:87], v[82:83], v[64:65] op_sel_hi:[1,0,1]
	v_cvt_f32_u32_e32 v70, v204
	v_cvt_f32_u32_e32 v71, v202
	v_cvt_f32_i32_e32 v82, v205
	v_cvt_f32_i32_e32 v83, v203
	v_pk_fma_f32 v[70:71], v[70:71], s[88:89], v[82:83] op_sel_hi:[1,0,1]
	s_nop 0
	v_pk_mul_f32 v[70:71], v[70:71], s[94:95] op_sel_hi:[1,0]
	s_nop 0
	v_fma_f32 v82, -v71, v71, v70
	v_add_f32_e32 v82, 0x3727c5ac, v82
	v_rsq_f32_e32 v82, v82
	v_pk_fma_f32 v[86:87], v[92:93], v[70:71], v[132:133] op_sel:[0,1,0] neg_lo:[1,0,0] neg_hi:[1,0,0]
	v_pk_fma_f32 v[94:95], v[232:233], v[70:71], v[134:135] op_sel:[0,1,0]
	v_pk_fma_f32 v[130:131], v[86:87], v[82:83], v[88:89] op_sel_hi:[1,0,1]
	v_pk_fma_f32 v[86:87], v[80:81], v[70:71], v[124:125] op_sel:[0,1,0] neg_lo:[1,0,0] neg_hi:[1,0,0]
	v_pk_fma_f32 v[128:129], v[94:95], v[82:83], v[90:91] op_sel_hi:[1,0,1]
	v_pk_fma_f32 v[94:95], v[230:231], v[70:71], v[126:127] op_sel:[0,1,0]
	v_pk_fma_f32 v[132:133], v[86:87], v[82:83], v[72:73] op_sel_hi:[1,0,1]
	v_pk_fma_f32 v[86:87], v[84:85], v[70:71], v[112:113] op_sel:[0,1,0] neg_lo:[1,0,0] neg_hi:[1,0,0]
	v_pk_fma_f32 v[126:127], v[94:95], v[82:83], v[74:75] op_sel_hi:[1,0,1]
	v_pk_fma_f32 v[94:95], v[228:229], v[70:71], v[114:115] op_sel:[0,1,0]
	v_pk_fma_f32 v[122:123], v[86:87], v[82:83], v[76:77] op_sel_hi:[1,0,1]
	v_pk_fma_f32 v[86:87], v[68:69], v[70:71], v[104:105] op_sel:[0,1,0] neg_lo:[1,0,0] neg_hi:[1,0,0]
	v_pk_fma_f32 v[70:71], v[226:227], v[70:71], v[106:107] op_sel:[0,1,0]
	v_pk_fma_f32 v[114:115], v[94:95], v[82:83], v[78:79] op_sel_hi:[1,0,1]
	v_pk_fma_f32 v[120:121], v[70:71], v[82:83], v[66:67] op_sel_hi:[1,0,1]
	v_pk_fma_f32 v[124:125], v[86:87], v[82:83], v[64:65] op_sel_hi:[1,0,1]
	v_cvt_f32_u32_e32 v70, v208
	v_cvt_f32_u32_e32 v71, v206
	v_cvt_f32_i32_e32 v82, v209
	v_cvt_f32_i32_e32 v83, v207
	v_pk_fma_f32 v[70:71], v[70:71], s[88:89], v[82:83] op_sel_hi:[1,0,1]
	s_nop 0
	v_pk_mul_f32 v[82:83], v[70:71], s[94:95] op_sel_hi:[1,0]
	s_nop 0
	v_fma_f32 v70, -v83, v83, v82
	v_add_f32_e32 v70, 0x3727c5ac, v70
	v_rsq_f32_e32 v94, v70
	v_pk_fma_f32 v[70:71], v[92:93], v[82:83], v[116:117] op_sel:[0,1,0] neg_lo:[1,0,0] neg_hi:[1,0,0]
	v_pk_fma_f32 v[86:87], v[232:233], v[82:83], v[118:119] op_sel:[0,1,0]
	v_pk_fma_f32 v[96:97], v[68:69], v[82:83], v[96:97] op_sel:[0,1,0] neg_lo:[1,0,0] neg_hi:[1,0,0]
	v_pk_fma_f32 v[104:105], v[86:87], v[94:95], v[90:91] op_sel_hi:[1,0,1]
	v_pk_fma_f32 v[112:113], v[70:71], v[94:95], v[88:89] op_sel_hi:[1,0,1]
	v_pk_fma_f32 v[70:71], v[80:81], v[82:83], v[108:109] op_sel:[0,1,0] neg_lo:[1,0,0] neg_hi:[1,0,0]
	v_pk_fma_f32 v[86:87], v[230:231], v[82:83], v[110:111] op_sel:[0,1,0]
	v_pk_fma_f32 v[108:109], v[70:71], v[94:95], v[72:73] op_sel_hi:[1,0,1]
	v_pk_fma_f32 v[106:107], v[86:87], v[94:95], v[74:75] op_sel_hi:[1,0,1]
	v_pk_fma_f32 v[86:87], v[84:85], v[82:83], v[100:101] op_sel:[0,1,0] neg_lo:[1,0,0] neg_hi:[1,0,0]
	v_pk_fma_f32 v[70:71], v[228:229], v[82:83], v[102:103] op_sel:[0,1,0]
	v_pk_fma_f32 v[82:83], v[226:227], v[82:83], v[98:99] op_sel:[0,1,0]
	v_pk_fma_f32 v[70:71], v[70:71], v[94:95], v[78:79] op_sel_hi:[1,0,1]
	v_pk_fma_f32 v[86:87], v[86:87], v[94:95], v[76:77] op_sel_hi:[1,0,1]
	v_pk_fma_f32 v[82:83], v[82:83], v[94:95], v[66:67] op_sel_hi:[1,0,1]
	v_pk_fma_f32 v[94:95], v[96:97], v[94:95], v[64:65] op_sel_hi:[1,0,1]
	global_load_dwordx2 v[102:103], v[196:197], off offset:1024
	global_load_dwordx2 v[110:111], v[194:195], off offset:1024
	global_load_dwordx2 v[98:99], v[196:197], off offset:1152
	global_load_dwordx2 v[100:101], v[194:195], off offset:1152
	global_load_dwordx2 v[96:97], v[196:197], off offset:1280
	global_load_dwordx2 v[116:117], v[194:195], off offset:1280
	global_load_dwordx2 v[234:235], v[196:197], off offset:1408
	global_load_dwordx2 v[236:237], v[194:195], off offset:1408
	s_waitcnt vmcnt(0)
	v_cvt_f32_u32_e32 v119, v102
	v_cvt_f32_u32_e32 v118, v110
	v_cvt_f32_i32_e32 v102, v111
	v_cvt_f32_i32_e32 v103, v103
	v_pk_fma_f32 v[102:103], v[118:119], s[88:89], v[102:103] op_sel_hi:[1,0,1]
	s_nop 0
	v_pk_mul_f32 v[102:103], v[102:103], s[94:95] op_sel_hi:[1,0]
	s_nop 0
	v_fma_f32 v110, -v103, v103, v102
	v_add_f32_e32 v110, 0x3727c5ac, v110
	v_rsq_f32_e32 v110, v110
	v_pk_fma_f32 v[48:49], v[68:69], v[102:103], v[48:49] op_sel:[0,1,0] neg_lo:[1,0,0] neg_hi:[1,0,0]
	v_pk_fma_f32 v[50:51], v[226:227], v[102:103], v[50:51] op_sel:[0,1,0]
	v_pk_fma_f32 v[60:61], v[92:93], v[102:103], v[60:61] op_sel:[0,1,0] neg_lo:[1,0,0] neg_hi:[1,0,0]
	v_pk_fma_f32 v[212:213], v[50:51], v[110:111], v[66:67] op_sel_hi:[1,0,1]
	v_pk_fma_f32 v[216:217], v[48:49], v[110:111], v[64:65] op_sel_hi:[1,0,1]
	v_cvt_f32_u32_e32 v48, v100
	v_cvt_f32_u32_e32 v49, v98
	v_cvt_f32_i32_e32 v50, v101
	v_cvt_f32_i32_e32 v51, v99
	v_pk_fma_f32 v[62:63], v[232:233], v[102:103], v[62:63] op_sel:[0,1,0]
	v_pk_fma_f32 v[56:57], v[80:81], v[102:103], v[56:57] op_sel:[0,1,0] neg_lo:[1,0,0] neg_hi:[1,0,0]
	v_pk_fma_f32 v[58:59], v[230:231], v[102:103], v[58:59] op_sel:[0,1,0]
	v_pk_fma_f32 v[48:49], v[48:49], s[88:89], v[50:51] op_sel_hi:[1,0,1]
	v_pk_fma_f32 v[52:53], v[84:85], v[102:103], v[52:53] op_sel:[0,1,0] neg_lo:[1,0,0] neg_hi:[1,0,0]
	v_pk_mul_f32 v[48:49], v[48:49], s[94:95] op_sel_hi:[1,0]
	v_pk_fma_f32 v[54:55], v[228:229], v[102:103], v[54:55] op_sel:[0,1,0]
	v_fma_f32 v50, -v49, v49, v48
	v_add_f32_e32 v50, 0x3727c5ac, v50
	v_rsq_f32_e32 v50, v50
	v_pk_fma_f32 v[32:33], v[68:69], v[48:49], v[32:33] op_sel:[0,1,0] neg_lo:[1,0,0] neg_hi:[1,0,0]
	v_pk_fma_f32 v[34:35], v[226:227], v[48:49], v[34:35] op_sel:[0,1,0]
	v_pk_fma_f32 v[44:45], v[92:93], v[48:49], v[44:45] op_sel:[0,1,0] neg_lo:[1,0,0] neg_hi:[1,0,0]
	v_pk_fma_f32 v[196:197], v[34:35], v[50:51], v[66:67] op_sel_hi:[1,0,1]
	v_pk_fma_f32 v[200:201], v[32:33], v[50:51], v[64:65] op_sel_hi:[1,0,1]
	v_cvt_f32_u32_e32 v32, v116
	v_cvt_f32_u32_e32 v33, v96
	v_cvt_f32_i32_e32 v34, v117
	v_cvt_f32_i32_e32 v35, v97
	v_pk_fma_f32 v[46:47], v[232:233], v[48:49], v[46:47] op_sel:[0,1,0]
	v_pk_fma_f32 v[40:41], v[80:81], v[48:49], v[40:41] op_sel:[0,1,0] neg_lo:[1,0,0] neg_hi:[1,0,0]
	v_pk_fma_f32 v[42:43], v[230:231], v[48:49], v[42:43] op_sel:[0,1,0]
	v_pk_fma_f32 v[32:33], v[32:33], s[88:89], v[34:35] op_sel_hi:[1,0,1]
	v_pk_fma_f32 v[36:37], v[84:85], v[48:49], v[36:37] op_sel:[0,1,0] neg_lo:[1,0,0] neg_hi:[1,0,0]
	v_pk_mul_f32 v[32:33], v[32:33], s[94:95] op_sel_hi:[1,0]
	v_pk_fma_f32 v[38:39], v[228:229], v[48:49], v[38:39] op_sel:[0,1,0]
	v_fma_f32 v34, -v33, v33, v32
	v_add_f32_e32 v34, 0x3727c5ac, v34
	v_rsq_f32_e32 v34, v34
	v_pk_fma_f32 v[16:17], v[68:69], v[32:33], v[16:17] op_sel:[0,1,0] neg_lo:[1,0,0] neg_hi:[1,0,0]
	v_pk_fma_f32 v[18:19], v[226:227], v[32:33], v[18:19] op_sel:[0,1,0]
	v_pk_fma_f32 v[28:29], v[92:93], v[32:33], v[28:29] op_sel:[0,1,0] neg_lo:[1,0,0] neg_hi:[1,0,0]
	v_pk_fma_f32 v[98:99], v[18:19], v[34:35], v[66:67] op_sel_hi:[1,0,1]
	v_pk_fma_f32 v[102:103], v[16:17], v[34:35], v[64:65] op_sel_hi:[1,0,1]
	v_cvt_f32_u32_e32 v16, v236
	v_cvt_f32_u32_e32 v17, v234
	v_cvt_f32_i32_e32 v18, v237
	v_cvt_f32_i32_e32 v19, v235
	v_pk_fma_f32 v[30:31], v[232:233], v[32:33], v[30:31] op_sel:[0,1,0]
	v_pk_fma_f32 v[24:25], v[80:81], v[32:33], v[24:25] op_sel:[0,1,0] neg_lo:[1,0,0] neg_hi:[1,0,0]
	v_pk_fma_f32 v[26:27], v[230:231], v[32:33], v[26:27] op_sel:[0,1,0]
	v_pk_fma_f32 v[16:17], v[16:17], s[88:89], v[18:19] op_sel_hi:[1,0,1]
	v_pk_fma_f32 v[20:21], v[84:85], v[32:33], v[20:21] op_sel:[0,1,0] neg_lo:[1,0,0] neg_hi:[1,0,0]
	v_pk_mul_f32 v[16:17], v[16:17], s[94:95] op_sel_hi:[1,0]
	v_pk_fma_f32 v[22:23], v[228:229], v[32:33], v[22:23] op_sel:[0,1,0]
	v_fma_f32 v18, -v17, v17, v16
	v_add_f32_e32 v18, 0x3727c5ac, v18
	v_rsq_f32_e32 v18, v18
	v_pk_fma_f32 v[12:13], v[92:93], v[16:17], v[12:13] op_sel:[0,1,0] neg_lo:[1,0,0] neg_hi:[1,0,0]
	v_pk_fma_f32 v[14:15], v[232:233], v[16:17], v[14:15] op_sel:[0,1,0]
	v_pk_fma_f32 v[8:9], v[80:81], v[16:17], v[8:9] op_sel:[0,1,0] neg_lo:[1,0,0] neg_hi:[1,0,0]
	v_pk_fma_f32 v[10:11], v[230:231], v[16:17], v[10:11] op_sel:[0,1,0]
	v_pk_fma_f32 v[4:5], v[84:85], v[16:17], v[4:5] op_sel:[0,1,0] neg_lo:[1,0,0] neg_hi:[1,0,0]
	v_pk_fma_f32 v[6:7], v[228:229], v[16:17], v[6:7] op_sel:[0,1,0]
	v_pk_fma_f32 v[0:1], v[68:69], v[16:17], v[0:1] op_sel:[0,1,0] neg_lo:[1,0,0] neg_hi:[1,0,0]
	v_pk_fma_f32 v[2:3], v[226:227], v[16:17], v[2:3] op_sel:[0,1,0]
	v_pk_fma_f32 v[218:219], v[62:63], v[110:111], v[90:91] op_sel_hi:[1,0,1]
	v_pk_fma_f32 v[220:221], v[60:61], v[110:111], v[88:89] op_sel_hi:[1,0,1]
	v_pk_fma_f32 v[222:223], v[58:59], v[110:111], v[74:75] op_sel_hi:[1,0,1]
	v_pk_fma_f32 v[224:225], v[56:57], v[110:111], v[72:73] op_sel_hi:[1,0,1]
	v_pk_fma_f32 v[210:211], v[54:55], v[110:111], v[78:79] op_sel_hi:[1,0,1]
	v_pk_fma_f32 v[214:215], v[52:53], v[110:111], v[76:77] op_sel_hi:[1,0,1]
	v_pk_fma_f32 v[202:203], v[46:47], v[50:51], v[90:91] op_sel_hi:[1,0,1]
	v_pk_fma_f32 v[204:205], v[44:45], v[50:51], v[88:89] op_sel_hi:[1,0,1]
	v_pk_fma_f32 v[206:207], v[42:43], v[50:51], v[74:75] op_sel_hi:[1,0,1]
	v_pk_fma_f32 v[208:209], v[40:41], v[50:51], v[72:73] op_sel_hi:[1,0,1]
	v_pk_fma_f32 v[194:195], v[38:39], v[50:51], v[78:79] op_sel_hi:[1,0,1]
	v_pk_fma_f32 v[198:199], v[36:37], v[50:51], v[76:77] op_sel_hi:[1,0,1]
	v_pk_fma_f32 v[110:111], v[30:31], v[34:35], v[90:91] op_sel_hi:[1,0,1]
	v_pk_fma_f32 v[116:117], v[28:29], v[34:35], v[88:89] op_sel_hi:[1,0,1]
	v_pk_fma_f32 v[118:119], v[26:27], v[34:35], v[74:75] op_sel_hi:[1,0,1]
	v_pk_fma_f32 v[134:135], v[24:25], v[34:35], v[72:73] op_sel_hi:[1,0,1]
	v_pk_fma_f32 v[96:97], v[22:23], v[34:35], v[78:79] op_sel_hi:[1,0,1]
	v_pk_fma_f32 v[100:101], v[20:21], v[34:35], v[76:77] op_sel_hi:[1,0,1]
	v_pk_fma_f32 v[90:91], v[14:15], v[18:19], v[90:91] op_sel_hi:[1,0,1]
	v_pk_fma_f32 v[88:89], v[12:13], v[18:19], v[88:89] op_sel_hi:[1,0,1]
	v_pk_fma_f32 v[74:75], v[10:11], v[18:19], v[74:75] op_sel_hi:[1,0,1]
	v_pk_fma_f32 v[72:73], v[8:9], v[18:19], v[72:73] op_sel_hi:[1,0,1]
	v_pk_fma_f32 v[60:61], v[6:7], v[18:19], v[78:79] op_sel_hi:[1,0,1]
	v_pk_fma_f32 v[62:63], v[4:5], v[18:19], v[76:77] op_sel_hi:[1,0,1]
	v_pk_fma_f32 v[66:67], v[2:3], v[18:19], v[66:67] op_sel_hi:[1,0,1]
	v_pk_fma_f32 v[64:65], v[0:1], v[18:19], v[64:65] op_sel_hi:[1,0,1]
	s_cbranch_scc0 .LBB0_390
	s_cmp_gt_u32 s45, 7
	s_cbranch_scc0 .LBB0_387
	s_cmp_gt_u32 s45, 11
	s_cbranch_scc0 .LBB0_384
	s_andn2_b64 vcc, exec, s[70:71]
	s_cbranch_vccnz .LBB0_383
	v_lshlrev_b64 v[68:69], 7, v[184:185]
	v_readlane_b32 s42, v252, 2
	v_readlane_b32 s40, v252, 4
	v_or_b32_e32 v0, v68, v249
	v_mov_b32_e32 v1, v69
	v_readlane_b32 s43, v252, 3
	v_readlane_b32 s41, v252, 5
	s_mov_b64 s[12:13], 0x4800
	v_lshl_add_u64 v[2:3], s[42:43], 0, v[0:1]
	v_lshl_add_u64 v[0:1], s[40:41], 0, v[0:1]
	global_load_dwordx4 v[48:51], v[2:3], off offset:16
	global_load_dwordx4 v[52:55], v[2:3], off
	global_load_dwordx4 v[56:59], v[0:1], off offset:16
	global_load_dwordx4 v[226:229], v[0:1], off
	v_or_b32_e32 v0, 16, v184
	v_ashrrev_i32_e32 v1, 31, v0
	v_lshlrev_b64 v[80:81], 7, v[0:1]
	v_or_b32_e32 v0, v80, v249
	v_mov_b32_e32 v1, v81
	v_lshl_add_u64 v[2:3], s[42:43], 0, v[0:1]
	v_lshl_add_u64 v[0:1], s[40:41], 0, v[0:1]
	global_load_dwordx4 v[28:31], v[2:3], off offset:16
	global_load_dwordx4 v[36:39], v[2:3], off
	global_load_dwordx4 v[40:43], v[0:1], off offset:16
	global_load_dwordx4 v[44:47], v[0:1], off
	v_or_b32_e32 v0, 32, v184
	v_ashrrev_i32_e32 v1, 31, v0
	v_lshlrev_b64 v[78:79], 7, v[0:1]
	v_or_b32_e32 v0, v78, v249
	v_mov_b32_e32 v1, v79
	v_lshl_add_u64 v[2:3], s[42:43], 0, v[0:1]
	v_lshl_add_u64 v[0:1], s[40:41], 0, v[0:1]
	global_load_dwordx4 v[16:19], v[2:3], off offset:16
	global_load_dwordx4 v[20:23], v[2:3], off
	global_load_dwordx4 v[24:27], v[0:1], off offset:16
	global_load_dwordx4 v[32:35], v[0:1], off
	v_or_b32_e32 v0, 48, v184
	v_ashrrev_i32_e32 v1, 31, v0
	v_lshlrev_b64 v[76:77], 7, v[0:1]
	v_or_b32_e32 v8, v76, v249
	v_mov_b32_e32 v9, v77
	v_lshl_add_u64 v[4:5], s[42:43], 0, v[8:9]
	v_lshl_add_u64 v[12:13], s[40:41], 0, v[8:9]
	global_load_dwordx4 v[0:3], v[4:5], off offset:16
	s_nop 0
	global_load_dwordx4 v[4:7], v[4:5], off
	s_nop 0
	global_load_dwordx4 v[8:11], v[12:13], off offset:16
	s_nop 0
	global_load_dwordx4 v[12:15], v[12:13], off
	s_waitcnt vmcnt(0)
	v_pk_mul_f32 v[230:231], v[156:157], v[58:59]
	v_pk_mul_f32 v[84:85], v[152:153], v[228:229]
	v_pk_mul_f32 v[92:93], v[154:155], v[226:227]
	v_pk_fma_f32 v[84:85], v[186:187], v[54:55], v[84:85] neg_lo:[0,0,1] neg_hi:[0,0,1]
	v_pk_fma_f32 v[92:93], v[188:189], v[52:53], v[92:93] neg_lo:[0,0,1] neg_hi:[0,0,1]
	v_pk_mul_f32 v[232:233], v[158:159], v[56:57]
	v_pk_mul_f32 v[58:59], v[190:191], v[58:59]
	v_pk_mul_f32 v[56:57], v[192:193], v[56:57]
	v_pk_fma_f32 v[234:235], v[190:191], v[50:51], v[230:231] neg_lo:[0,0,1] neg_hi:[0,0,1]
	v_pk_fma_f32 v[232:233], v[192:193], v[48:49], v[232:233] neg_lo:[0,0,1] neg_hi:[0,0,1]
	v_cvt_pk_bf16_f32 v230, v92, v93
	v_cvt_pk_bf16_f32 v231, v84, v85
	v_lshl_add_u64 v[84:85], v[178:179], 0, v[68:69]
	v_pk_mul_f32 v[92:93], v[186:187], v[228:229]
	v_pk_mul_f32 v[226:227], v[188:189], v[226:227]
	v_pk_fma_f32 v[58:59], v[156:157], v[50:51], v[58:59]
	v_pk_fma_f32 v[50:51], v[158:159], v[48:49], v[56:57]
	v_cvt_pk_bf16_f32 v232, v232, v233
	v_cvt_pk_bf16_f32 v233, v234, v235
	global_store_dwordx4 v[84:85], v[230:233], off
	v_pk_fma_f32 v[54:55], v[152:153], v[54:55], v[92:93]
	v_pk_fma_f32 v[52:53], v[154:155], v[52:53], v[226:227]
	s_nop 0
	v_cvt_pk_bf16_f32 v48, v52, v53
	v_cvt_pk_bf16_f32 v49, v54, v55
	v_cvt_pk_bf16_f32 v50, v50, v51
	v_cvt_pk_bf16_f32 v51, v58, v59
	global_store_dwordx4 v[84:85], v[48:51], off offset:64
	v_pk_mul_f32 v[54:55], v[142:143], v[40:41]
	v_pk_mul_f32 v[40:41], v[150:151], v[40:41]
	v_pk_mul_f32 v[48:49], v[136:137], v[46:47]
	v_pk_mul_f32 v[50:51], v[140:141], v[44:45]
	v_pk_fma_f32 v[52:53], v[144:145], v[38:39], v[48:49] neg_lo:[0,0,1] neg_hi:[0,0,1]
	v_pk_fma_f32 v[48:49], v[148:149], v[36:37], v[50:51] neg_lo:[0,0,1] neg_hi:[0,0,1]
	v_pk_mul_f32 v[50:51], v[138:139], v[42:43]
	v_pk_mul_f32 v[42:43], v[146:147], v[42:43]
	v_pk_fma_f32 v[56:57], v[146:147], v[30:31], v[50:51] neg_lo:[0,0,1] neg_hi:[0,0,1]
	v_pk_fma_f32 v[50:51], v[150:151], v[28:29], v[54:55] neg_lo:[0,0,1] neg_hi:[0,0,1]
	v_cvt_pk_bf16_f32 v48, v48, v49
	v_cvt_pk_bf16_f32 v49, v52, v53
	v_lshl_add_u64 v[52:53], v[178:179], 0, v[80:81]
	v_pk_mul_f32 v[46:47], v[144:145], v[46:47]
	v_pk_mul_f32 v[44:45], v[148:149], v[44:45]
	v_pk_fma_f32 v[42:43], v[138:139], v[30:31], v[42:43]
	v_pk_fma_f32 v[30:31], v[142:143], v[28:29], v[40:41]
	v_cvt_pk_bf16_f32 v50, v50, v51
	v_cvt_pk_bf16_f32 v51, v56, v57
	global_store_dwordx4 v[52:53], v[48:51], off
	v_pk_fma_f32 v[38:39], v[136:137], v[38:39], v[46:47]
	v_pk_fma_f32 v[36:37], v[140:141], v[36:37], v[44:45]
	v_lshl_add_u64 v[58:59], v[68:69], 0, s[10:11]
	v_cvt_pk_bf16_f32 v28, v36, v37
	v_cvt_pk_bf16_f32 v29, v38, v39
	v_cvt_pk_bf16_f32 v30, v30, v31
	v_cvt_pk_bf16_f32 v31, v42, v43
	global_store_dwordx4 v[52:53], v[28:31], off offset:64
	v_pk_mul_f32 v[38:39], v[124:125], v[24:25]
	v_pk_mul_f32 v[24:25], v[132:133], v[24:25]
	v_pk_mul_f32 v[28:29], v[114:115], v[34:35]
	v_pk_mul_f32 v[30:31], v[122:123], v[32:33]
	v_pk_fma_f32 v[36:37], v[128:129], v[22:23], v[28:29] neg_lo:[0,0,1] neg_hi:[0,0,1]
	v_pk_fma_f32 v[28:29], v[130:131], v[20:21], v[30:31] neg_lo:[0,0,1] neg_hi:[0,0,1]
	v_pk_mul_f32 v[30:31], v[120:121], v[26:27]
	v_cvt_pk_bf16_f32 v28, v28, v29
	v_cvt_pk_bf16_f32 v29, v36, v37
	v_lshl_add_u64 v[36:37], v[178:179], 0, v[78:79]
	v_pk_fma_f32 v[40:41], v[126:127], v[18:19], v[30:31] neg_lo:[0,0,1] neg_hi:[0,0,1]
	v_pk_fma_f32 v[30:31], v[132:133], v[16:17], v[38:39] neg_lo:[0,0,1] neg_hi:[0,0,1]
	v_pk_mul_f32 v[26:27], v[126:127], v[26:27]
	v_cvt_pk_bf16_f32 v30, v30, v31
	v_cvt_pk_bf16_f32 v31, v40, v41
	global_store_dwordx4 v[36:37], v[28:31], off
	v_pk_fma_f32 v[26:27], v[120:121], v[18:19], v[26:27]
	v_pk_fma_f32 v[18:19], v[124:125], v[16:17], v[24:25]
	v_pk_mul_f32 v[28:29], v[128:129], v[34:35]
	v_pk_mul_f32 v[30:31], v[130:131], v[32:33]
	v_pk_fma_f32 v[22:23], v[114:115], v[22:23], v[28:29]
	v_pk_fma_f32 v[20:21], v[122:123], v[20:21], v[30:31]
	v_lshl_add_u64 v[80:81], v[68:69], 0, s[12:13]
	v_cvt_pk_bf16_f32 v16, v20, v21
	v_cvt_pk_bf16_f32 v17, v22, v23
	v_cvt_pk_bf16_f32 v18, v18, v19
	v_cvt_pk_bf16_f32 v19, v26, v27
	global_store_dwordx4 v[36:37], v[16:19], off offset:64
	v_pk_mul_f32 v[22:23], v[94:95], v[8:9]
	v_pk_mul_f32 v[8:9], v[108:109], v[8:9]
	v_pk_mul_f32 v[16:17], v[70:71], v[14:15]
	v_pk_mul_f32 v[18:19], v[86:87], v[12:13]
	v_pk_fma_f32 v[20:21], v[104:105], v[6:7], v[16:17] neg_lo:[0,0,1] neg_hi:[0,0,1]
	v_pk_fma_f32 v[16:17], v[112:113], v[4:5], v[18:19] neg_lo:[0,0,1] neg_hi:[0,0,1]
	v_pk_mul_f32 v[18:19], v[82:83], v[10:11]
	v_cvt_pk_bf16_f32 v16, v16, v17
	v_cvt_pk_bf16_f32 v17, v20, v21
	v_lshl_add_u64 v[20:21], v[178:179], 0, v[76:77]
	v_pk_fma_f32 v[24:25], v[106:107], v[2:3], v[18:19] neg_lo:[0,0,1] neg_hi:[0,0,1]
	v_pk_fma_f32 v[18:19], v[108:109], v[0:1], v[22:23] neg_lo:[0,0,1] neg_hi:[0,0,1]
	v_pk_mul_f32 v[14:15], v[104:105], v[14:15]
	v_pk_mul_f32 v[12:13], v[112:113], v[12:13]
	v_pk_mul_f32 v[10:11], v[106:107], v[10:11]
	v_cvt_pk_bf16_f32 v18, v18, v19
	v_cvt_pk_bf16_f32 v19, v24, v25
	global_store_dwordx4 v[20:21], v[16:19], off
	v_pk_fma_f32 v[6:7], v[70:71], v[6:7], v[14:15]
	v_pk_fma_f32 v[4:5], v[86:87], v[4:5], v[12:13]
	v_pk_fma_f32 v[10:11], v[82:83], v[2:3], v[10:11]
	v_pk_fma_f32 v[2:3], v[94:95], v[0:1], v[8:9]
	v_cvt_pk_bf16_f32 v0, v4, v5
	v_cvt_pk_bf16_f32 v1, v6, v7
	s_mov_b64 s[12:13], 0x5000
	v_cvt_pk_bf16_f32 v2, v2, v3
	v_cvt_pk_bf16_f32 v3, v10, v11
	global_store_dwordx4 v[20:21], v[0:3], off offset:64
	v_lshl_add_u64 v[84:85], v[68:69], 0, s[12:13]
	s_mov_b64 s[12:13], 0x5800
	v_or_b32_e32 v0, v58, v249
	v_mov_b32_e32 v1, v59
	v_lshl_add_u64 v[2:3], s[42:43], 0, v[0:1]
	v_lshl_add_u64 v[0:1], s[40:41], 0, v[0:1]
	global_load_dwordx4 v[10:13], v[2:3], off offset:16
	global_load_dwordx4 v[14:17], v[2:3], off
	global_load_dwordx4 v[18:21], v[0:1], off offset:16
	global_load_dwordx4 v[22:25], v[0:1], off
	v_or_b32_e32 v0, v80, v249
	v_mov_b32_e32 v1, v81
	v_lshl_add_u64 v[2:3], s[42:43], 0, v[0:1]
	v_lshl_add_u64 v[0:1], s[40:41], 0, v[0:1]
	global_load_dwordx4 v[26:29], v[2:3], off offset:16
	global_load_dwordx4 v[30:33], v[2:3], off
	global_load_dwordx4 v[34:37], v[0:1], off offset:16
	global_load_dwordx4 v[38:41], v[0:1], off
	v_or_b32_e32 v0, v84, v249
	v_mov_b32_e32 v1, v85
	v_lshl_add_u64 v[2:3], s[42:43], 0, v[0:1]
	v_lshl_add_u64 v[0:1], s[40:41], 0, v[0:1]
	global_load_dwordx4 v[42:45], v[2:3], off offset:16
	global_load_dwordx4 v[46:49], v[2:3], off
	global_load_dwordx4 v[50:53], v[0:1], off offset:16
	global_load_dwordx4 v[54:57], v[0:1], off
	v_lshl_add_u64 v[8:9], v[68:69], 0, s[12:13]
	v_or_b32_e32 v68, v8, v249
	v_mov_b32_e32 v69, v9
	v_lshl_add_u64 v[4:5], s[42:43], 0, v[68:69]
	v_lshl_add_u64 v[68:69], s[40:41], 0, v[68:69]
	global_load_dwordx4 v[0:3], v[4:5], off offset:16
	s_nop 0
	global_load_dwordx4 v[4:7], v[4:5], off
	s_nop 0
	global_load_dwordx4 v[76:79], v[68:69], off offset:16
	global_load_dwordx4 v[226:229], v[68:69], off
	v_lshl_add_u64 v[58:59], v[178:179], 0, v[58:59]
	v_lshl_add_u64 v[8:9], v[178:179], 0, v[8:9]
	s_waitcnt vmcnt(0)
	v_pk_mul_f32 v[230:231], v[212:213], v[20:21]
	v_pk_mul_f32 v[232:233], v[216:217], v[18:19]
	v_pk_mul_f32 v[20:21], v[222:223], v[20:21]
	v_pk_mul_f32 v[18:19], v[224:225], v[18:19]
	v_pk_mul_f32 v[68:69], v[210:211], v[24:25]
	v_pk_mul_f32 v[92:93], v[214:215], v[22:23]
	v_pk_fma_f32 v[234:235], v[222:223], v[12:13], v[230:231] neg_lo:[0,0,1] neg_hi:[0,0,1]
	v_pk_fma_f32 v[232:233], v[224:225], v[10:11], v[232:233] neg_lo:[0,0,1] neg_hi:[0,0,1]
	v_pk_mul_f32 v[24:25], v[218:219], v[24:25]
	v_pk_mul_f32 v[22:23], v[220:221], v[22:23]
	v_pk_fma_f32 v[20:21], v[212:213], v[12:13], v[20:21]
	v_pk_fma_f32 v[12:13], v[216:217], v[10:11], v[18:19]
	v_pk_fma_f32 v[68:69], v[218:219], v[16:17], v[68:69] neg_lo:[0,0,1] neg_hi:[0,0,1]
	v_pk_fma_f32 v[92:93], v[220:221], v[14:15], v[92:93] neg_lo:[0,0,1] neg_hi:[0,0,1]
	v_pk_fma_f32 v[16:17], v[210:211], v[16:17], v[24:25]
	v_cvt_pk_bf16_f32 v230, v92, v93
	v_cvt_pk_bf16_f32 v231, v68, v69
	v_cvt_pk_bf16_f32 v232, v232, v233
	v_cvt_pk_bf16_f32 v233, v234, v235
	global_store_dwordx4 v[58:59], v[230:233], off
	v_pk_fma_f32 v[14:15], v[214:215], v[14:15], v[22:23]
	s_nop 0
	v_cvt_pk_bf16_f32 v10, v14, v15
	v_cvt_pk_bf16_f32 v11, v16, v17
	v_cvt_pk_bf16_f32 v12, v12, v13
	v_cvt_pk_bf16_f32 v13, v20, v21
	global_store_dwordx4 v[58:59], v[10:13], off offset:64
	v_pk_mul_f32 v[16:17], v[200:201], v[34:35]
	s_nop 0
	v_pk_mul_f32 v[10:11], v[194:195], v[40:41]
	v_pk_mul_f32 v[12:13], v[198:199], v[38:39]
	v_pk_fma_f32 v[14:15], v[202:203], v[32:33], v[10:11] neg_lo:[0,0,1] neg_hi:[0,0,1]
	v_pk_fma_f32 v[10:11], v[204:205], v[30:31], v[12:13] neg_lo:[0,0,1] neg_hi:[0,0,1]
	v_pk_mul_f32 v[12:13], v[196:197], v[36:37]
	v_cvt_pk_bf16_f32 v10, v10, v11
	v_cvt_pk_bf16_f32 v11, v14, v15
	v_lshl_add_u64 v[14:15], v[178:179], 0, v[80:81]
	v_pk_fma_f32 v[18:19], v[206:207], v[28:29], v[12:13] neg_lo:[0,0,1] neg_hi:[0,0,1]
	v_pk_fma_f32 v[12:13], v[208:209], v[26:27], v[16:17] neg_lo:[0,0,1] neg_hi:[0,0,1]
	s_nop 0
	v_cvt_pk_bf16_f32 v12, v12, v13
	v_cvt_pk_bf16_f32 v13, v18, v19
	global_store_dwordx4 v[14:15], v[10:13], off
	v_pk_mul_f32 v[18:19], v[208:209], v[34:35]
	s_nop 0
	v_pk_mul_f32 v[10:11], v[202:203], v[40:41]
	v_pk_mul_f32 v[12:13], v[204:205], v[38:39]
	v_pk_fma_f32 v[16:17], v[194:195], v[32:33], v[10:11]
	v_pk_fma_f32 v[10:11], v[198:199], v[30:31], v[12:13]
	v_pk_mul_f32 v[12:13], v[206:207], v[36:37]
	v_cvt_pk_bf16_f32 v10, v10, v11
	v_cvt_pk_bf16_f32 v11, v16, v17
	v_pk_mul_f32 v[16:17], v[102:103], v[50:51]
	v_pk_fma_f32 v[20:21], v[196:197], v[28:29], v[12:13]
	v_pk_fma_f32 v[12:13], v[200:201], v[26:27], v[18:19]
	s_nop 0
	v_cvt_pk_bf16_f32 v12, v12, v13
	v_cvt_pk_bf16_f32 v13, v20, v21
	global_store_dwordx4 v[14:15], v[10:13], off offset:64
	s_nop 1
	v_pk_mul_f32 v[10:11], v[96:97], v[56:57]
	v_pk_mul_f32 v[12:13], v[100:101], v[54:55]
	v_pk_fma_f32 v[14:15], v[110:111], v[48:49], v[10:11] neg_lo:[0,0,1] neg_hi:[0,0,1]
	v_pk_fma_f32 v[10:11], v[116:117], v[46:47], v[12:13] neg_lo:[0,0,1] neg_hi:[0,0,1]
	v_pk_mul_f32 v[12:13], v[98:99], v[52:53]
	v_cvt_pk_bf16_f32 v10, v10, v11
	v_cvt_pk_bf16_f32 v11, v14, v15
	v_lshl_add_u64 v[14:15], v[178:179], 0, v[84:85]
	v_pk_fma_f32 v[18:19], v[118:119], v[44:45], v[12:13] neg_lo:[0,0,1] neg_hi:[0,0,1]
	v_pk_fma_f32 v[12:13], v[134:135], v[42:43], v[16:17] neg_lo:[0,0,1] neg_hi:[0,0,1]
	s_nop 0
	v_cvt_pk_bf16_f32 v12, v12, v13
	v_cvt_pk_bf16_f32 v13, v18, v19
	global_store_dwordx4 v[14:15], v[10:13], off
	v_pk_mul_f32 v[18:19], v[134:135], v[50:51]
	s_nop 0
	v_pk_mul_f32 v[10:11], v[110:111], v[56:57]
	v_pk_mul_f32 v[12:13], v[116:117], v[54:55]
	v_pk_fma_f32 v[16:17], v[96:97], v[48:49], v[10:11]
	v_pk_fma_f32 v[10:11], v[100:101], v[46:47], v[12:13]
	v_pk_mul_f32 v[12:13], v[118:119], v[52:53]
	v_cvt_pk_bf16_f32 v10, v10, v11
	v_cvt_pk_bf16_f32 v11, v16, v17
	v_pk_mul_f32 v[16:17], v[64:65], v[76:77]
	v_pk_fma_f32 v[20:21], v[98:99], v[44:45], v[12:13]
	v_pk_fma_f32 v[12:13], v[102:103], v[42:43], v[18:19]
	s_nop 0
	v_cvt_pk_bf16_f32 v12, v12, v13
	v_cvt_pk_bf16_f32 v13, v20, v21
	global_store_dwordx4 v[14:15], v[10:13], off offset:64
	s_nop 1
	v_pk_mul_f32 v[10:11], v[60:61], v[228:229]
	v_pk_mul_f32 v[12:13], v[62:63], v[226:227]
	v_pk_fma_f32 v[14:15], v[90:91], v[6:7], v[10:11] neg_lo:[0,0,1] neg_hi:[0,0,1]
	v_pk_fma_f32 v[10:11], v[88:89], v[4:5], v[12:13] neg_lo:[0,0,1] neg_hi:[0,0,1]
	v_pk_mul_f32 v[12:13], v[66:67], v[78:79]
	v_cvt_pk_bf16_f32 v10, v10, v11
	v_cvt_pk_bf16_f32 v11, v14, v15
	s_nop 0
	v_pk_fma_f32 v[18:19], v[74:75], v[2:3], v[12:13] neg_lo:[0,0,1] neg_hi:[0,0,1]
	v_pk_fma_f32 v[12:13], v[72:73], v[0:1], v[16:17] neg_lo:[0,0,1] neg_hi:[0,0,1]
	s_nop 0
	v_cvt_pk_bf16_f32 v12, v12, v13
	v_cvt_pk_bf16_f32 v13, v18, v19
	global_store_dwordx4 v[8:9], v[10:13], off
	s_nop 1
	v_pk_mul_f32 v[10:11], v[90:91], v[228:229]
	v_pk_mul_f32 v[12:13], v[88:89], v[226:227]
	v_pk_fma_f32 v[6:7], v[60:61], v[6:7], v[10:11]
	v_pk_fma_f32 v[4:5], v[62:63], v[4:5], v[12:13]
	v_pk_mul_f32 v[10:11], v[74:75], v[78:79]
	v_pk_mul_f32 v[12:13], v[72:73], v[76:77]
	v_pk_fma_f32 v[10:11], v[66:67], v[2:3], v[10:11]
	v_pk_fma_f32 v[2:3], v[64:65], v[0:1], v[12:13]
	v_cvt_pk_bf16_f32 v0, v4, v5
	v_cvt_pk_bf16_f32 v1, v6, v7
	s_nop 0
	v_cvt_pk_bf16_f32 v2, v2, v3
	v_cvt_pk_bf16_f32 v3, v10, v11
	global_store_dwordx4 v[8:9], v[0:3], off offset:64

.LBB0_474:
	s_barrier
	s_add_u32 s68, s72, 0xfffe0080
	s_addc_u32 s74, s73, -1
	s_add_i32 s78, 0, 0x10000
	v_add_u32_e32 v140, s78, v173
	ds_read_b128 v[128:131], v140
	ds_read_b128 v[132:135], v140 offset:1024
	ds_read_b128 v[136:139], v140 offset:2048
	ds_read_b128 v[140:143], v140 offset:3072
	s_cmp_eq_u32 s67, 4
	s_cselect_b32 s77, s5, s74
	s_cselect_b32 s76, s12, s68
	s_cselect_b32 s75, s13, s66
	s_cselect_b32 s74, s45, s47
	ds_read_b128 v[174:177], v185
	ds_read_b128 v[180:183], v185 offset:1024
	ds_read_b128 v[186:189], v185 offset:2048
	ds_read_b128 v[190:193], v185 offset:3072
	ds_read_b128 v[194:197], v185 offset:4096
	ds_read_b128 v[198:201], v185 offset:5120
	ds_read_b128 v[202:205], v185 offset:6144
	ds_read_b128 v[206:209], v185 offset:7168
	s_waitcnt lgkmcnt(8)
	s_barrier
	s_waitcnt lgkmcnt(0)
	s_waitcnt lgkmcnt(0)
	v_mfma_f32_16x16x32_bf16 v[124:127], v[128:131], v[174:177], v[124:127]
	v_mfma_f32_16x16x32_bf16 v[120:123], v[136:139], v[174:177], v[120:123]
	v_mfma_f32_16x16x32_bf16 v[112:115], v[128:131], v[186:189], v[112:115]
	v_mfma_f32_16x16x32_bf16 v[104:107], v[136:139], v[186:189], v[104:107]
	v_mfma_f32_16x16x32_bf16 v[96:99], v[128:131], v[194:197], v[96:99]
	v_mfma_f32_16x16x32_bf16 v[88:91], v[136:139], v[194:197], v[88:91]
	v_mfma_f32_16x16x32_bf16 v[80:83], v[128:131], v[202:205], v[80:83]
	v_mfma_f32_16x16x32_bf16 v[72:75], v[136:139], v[202:205], v[72:75]
	v_mfma_f32_16x16x32_bf16 v[124:127], v[132:135], v[180:183], v[124:127]
	v_mfma_f32_16x16x32_bf16 v[120:123], v[140:143], v[180:183], v[120:123]
	v_mfma_f32_16x16x32_bf16 v[112:115], v[132:135], v[190:193], v[112:115]
	v_mfma_f32_16x16x32_bf16 v[104:107], v[140:143], v[190:193], v[104:107]
	v_mfma_f32_16x16x32_bf16 v[96:99], v[132:135], v[198:201], v[96:99]
	v_mfma_f32_16x16x32_bf16 v[88:91], v[140:143], v[198:201], v[88:91]
	v_mfma_f32_16x16x32_bf16 v[80:83], v[132:135], v[206:209], v[80:83]
	v_mfma_f32_16x16x32_bf16 v[72:75], v[140:143], v[206:209], v[72:75]
	s_barrier
	v_lshl_add_u64 v[158:159], s[72:73], 0, v[154:155]
	s_add_i32 m0, s18, 0xc000
	s_nop 0
	global_load_lds_dwordx4 v[158:159], off
	v_lshl_add_u64 v[158:159], s[72:73], 0, v[156:157]
	s_add_i32 m0, s18, 0xe000
	s_nop 0
	global_load_lds_dwordx4 v[158:159], off
	s_add_i32 s68, 0, 0x14000
	v_add_u32_e32 v158, s68, v173
	s_add_i32 s78, s78, s17
	ds_read_b128 v[210:213], v158
	ds_read_b128 v[214:217], v158 offset:1024
	ds_read_b128 v[218:221], v158 offset:2048
	ds_read_b128 v[222:225], v158 offset:3072
	v_lshl_add_u64 v[158:159], s[74:75], 0, v[148:149]
	s_mov_b32 m0, s78
	v_lshl_add_u64 v[170:171], s[74:75], 0, v[144:145]
	global_load_lds_dwordx4 v[158:159], off
	s_add_i32 m0, s78, 0x2000
	s_nop 0
	global_load_lds_dwordx4 v[170:171], off
	s_barrier
	s_waitcnt lgkmcnt(0)
	s_waitcnt lgkmcnt(0)
	v_mfma_f32_16x16x32_bf16 v[116:119], v[210:213], v[174:177], v[116:119]
	v_mfma_f32_16x16x32_bf16 v[108:111], v[218:221], v[174:177], v[108:111]
	v_mfma_f32_16x16x32_bf16 v[100:103], v[210:213], v[186:189], v[100:103]
	v_mfma_f32_16x16x32_bf16 v[92:95], v[218:221], v[186:189], v[92:95]
	v_mfma_f32_16x16x32_bf16 v[84:87], v[210:213], v[194:197], v[84:87]
	v_mfma_f32_16x16x32_bf16 v[76:79], v[218:221], v[194:197], v[76:79]
	v_mfma_f32_16x16x32_bf16 v[68:71], v[210:213], v[202:205], v[68:71]
	v_mfma_f32_16x16x32_bf16 v[64:67], v[218:221], v[202:205], v[64:67]
	v_mfma_f32_16x16x32_bf16 v[116:119], v[214:217], v[180:183], v[116:119]
	v_mfma_f32_16x16x32_bf16 v[108:111], v[222:225], v[180:183], v[108:111]
	v_mfma_f32_16x16x32_bf16 v[100:103], v[214:217], v[190:193], v[100:103]
	v_mfma_f32_16x16x32_bf16 v[92:95], v[222:225], v[190:193], v[92:95]
	v_mfma_f32_16x16x32_bf16 v[84:87], v[214:217], v[198:201], v[84:87]
	v_mfma_f32_16x16x32_bf16 v[76:79], v[222:225], v[198:201], v[76:79]
	v_mfma_f32_16x16x32_bf16 v[68:71], v[214:217], v[206:209], v[68:71]
	v_mfma_f32_16x16x32_bf16 v[64:67], v[222:225], v[206:209], v[64:67]
	s_mov_b32 m0, s18
	v_lshl_add_u64 v[226:227], s[76:77], 0, v[150:151]
	s_barrier
	ds_read_b128 v[174:177], v185 offset:16384
	ds_read_b128 v[180:183], v185 offset:17408
	ds_read_b128 v[186:189], v185 offset:18432
	ds_read_b128 v[190:193], v185 offset:19456
	ds_read_b128 v[194:197], v185 offset:20480
	ds_read_b128 v[198:201], v185 offset:21504
	ds_read_b128 v[202:205], v185 offset:22528
	ds_read_b128 v[206:209], v185 offset:23552
	global_load_lds_dwordx4 v[226:227], off
	v_lshl_add_u64 v[228:229], s[76:77], 0, v[146:147]
	s_mov_b32 m0, s19
	s_nop 0
	global_load_lds_dwordx4 v[228:229], off
	s_barrier
	s_waitcnt lgkmcnt(0)
	s_waitcnt lgkmcnt(0)
	v_mfma_f32_16x16x32_bf16 v[60:63], v[128:131], v[174:177], v[60:63]
	v_mfma_f32_16x16x32_bf16 v[56:59], v[136:139], v[174:177], v[56:59]
	v_mfma_f32_16x16x32_bf16 v[48:51], v[128:131], v[186:189], v[48:51]
	v_mfma_f32_16x16x32_bf16 v[40:43], v[136:139], v[186:189], v[40:43]
	v_mfma_f32_16x16x32_bf16 v[32:35], v[128:131], v[194:197], v[32:35]
	v_mfma_f32_16x16x32_bf16 v[24:27], v[136:139], v[194:197], v[24:27]
	v_mfma_f32_16x16x32_bf16 v[16:19], v[128:131], v[202:205], v[16:19]
	v_mfma_f32_16x16x32_bf16 v[8:11], v[136:139], v[202:205], v[8:11]
	v_mfma_f32_16x16x32_bf16 v[60:63], v[132:135], v[180:183], v[60:63]
	v_mfma_f32_16x16x32_bf16 v[56:59], v[140:143], v[180:183], v[56:59]
	v_mfma_f32_16x16x32_bf16 v[48:51], v[132:135], v[190:193], v[48:51]
	v_mfma_f32_16x16x32_bf16 v[40:43], v[140:143], v[190:193], v[40:43]
	v_mfma_f32_16x16x32_bf16 v[32:35], v[132:135], v[198:201], v[32:35]
	v_mfma_f32_16x16x32_bf16 v[24:27], v[140:143], v[198:201], v[24:27]
	v_mfma_f32_16x16x32_bf16 v[16:19], v[132:135], v[206:209], v[16:19]
	v_mfma_f32_16x16x32_bf16 v[8:11], v[140:143], v[206:209], v[8:11]
	s_barrier
	s_add_u32 s78, s74, 0x20000
	s_addc_u32 s79, s75, 0
	s_add_i32 s68, s68, s17
	v_lshl_add_u64 v[128:129], s[78:79], 0, v[148:149]
	s_mov_b32 m0, s68
	s_nop 0
	global_load_lds_dwordx4 v[128:129], off
	v_lshl_add_u64 v[128:129], s[78:79], 0, v[144:145]
	s_add_i32 m0, s68, 0x2000
	s_nop 0
	global_load_lds_dwordx4 v[128:129], off
	s_waitcnt vmcnt(6)
	s_barrier
	v_mfma_f32_16x16x32_bf16 v[52:55], v[210:213], v[174:177], v[52:55]
	v_mfma_f32_16x16x32_bf16 v[44:47], v[218:221], v[174:177], v[44:47]
	v_mfma_f32_16x16x32_bf16 v[36:39], v[210:213], v[186:189], v[36:39]
	v_mfma_f32_16x16x32_bf16 v[28:31], v[218:221], v[186:189], v[28:31]
	v_mfma_f32_16x16x32_bf16 v[20:23], v[210:213], v[194:197], v[20:23]
	v_mfma_f32_16x16x32_bf16 v[12:15], v[218:221], v[194:197], v[12:15]
	v_mfma_f32_16x16x32_bf16 v[4:7], v[210:213], v[202:205], v[4:7]
	v_mfma_f32_16x16x32_bf16 v[0:3], v[218:221], v[202:205], v[0:3]
	v_mfma_f32_16x16x32_bf16 v[52:55], v[214:217], v[180:183], v[52:55]
	v_mfma_f32_16x16x32_bf16 v[44:47], v[222:225], v[180:183], v[44:47]
	v_mfma_f32_16x16x32_bf16 v[36:39], v[214:217], v[190:193], v[36:39]
	v_mfma_f32_16x16x32_bf16 v[28:31], v[222:225], v[190:193], v[28:31]
	v_mfma_f32_16x16x32_bf16 v[20:23], v[214:217], v[198:201], v[20:23]
	v_mfma_f32_16x16x32_bf16 v[12:15], v[222:225], v[198:201], v[12:15]
	v_mfma_f32_16x16x32_bf16 v[4:7], v[214:217], v[206:209], v[4:7]
	v_mfma_f32_16x16x32_bf16 v[0:3], v[222:225], v[206:209], v[0:3]
	s_add_i32 s68, 0, 0x18000
	v_add_u32_e32 v140, s68, v173
	s_barrier
	ds_read_b128 v[128:131], v140
	ds_read_b128 v[132:135], v140 offset:1024
	ds_read_b128 v[136:139], v140 offset:2048
	ds_read_b128 v[140:143], v140 offset:3072
	ds_read_b128 v[174:177], v185 offset:32768
	ds_read_b128 v[180:183], v185 offset:33792
	ds_read_b128 v[186:189], v185 offset:34816
	ds_read_b128 v[190:193], v185 offset:35840
	ds_read_b128 v[194:197], v185 offset:36864
	ds_read_b128 v[198:201], v185 offset:37888
	ds_read_b128 v[202:205], v185 offset:38912
	ds_read_b128 v[206:209], v185 offset:39936
	s_waitcnt lgkmcnt(8)
	s_barrier
	s_waitcnt lgkmcnt(0)
	s_waitcnt lgkmcnt(0)
	v_mfma_f32_16x16x32_bf16 v[124:127], v[128:131], v[174:177], v[124:127]
	v_mfma_f32_16x16x32_bf16 v[120:123], v[136:139], v[174:177], v[120:123]
	v_mfma_f32_16x16x32_bf16 v[112:115], v[128:131], v[186:189], v[112:115]
	v_mfma_f32_16x16x32_bf16 v[104:107], v[136:139], v[186:189], v[104:107]
	v_mfma_f32_16x16x32_bf16 v[96:99], v[128:131], v[194:197], v[96:99]
	v_mfma_f32_16x16x32_bf16 v[88:91], v[136:139], v[194:197], v[88:91]
	v_mfma_f32_16x16x32_bf16 v[80:83], v[128:131], v[202:205], v[80:83]
	v_mfma_f32_16x16x32_bf16 v[72:75], v[136:139], v[202:205], v[72:75]
	v_mfma_f32_16x16x32_bf16 v[124:127], v[132:135], v[180:183], v[124:127]
	v_mfma_f32_16x16x32_bf16 v[120:123], v[140:143], v[180:183], v[120:123]
	v_mfma_f32_16x16x32_bf16 v[112:115], v[132:135], v[190:193], v[112:115]
	v_mfma_f32_16x16x32_bf16 v[104:107], v[140:143], v[190:193], v[104:107]
	v_mfma_f32_16x16x32_bf16 v[96:99], v[132:135], v[198:201], v[96:99]
	v_mfma_f32_16x16x32_bf16 v[88:91], v[140:143], v[198:201], v[88:91]
	v_mfma_f32_16x16x32_bf16 v[80:83], v[132:135], v[206:209], v[80:83]
	v_mfma_f32_16x16x32_bf16 v[72:75], v[140:143], v[206:209], v[72:75]
	s_barrier
	s_add_u32 s76, s76, 0x20000
	s_addc_u32 s77, s77, 0
	v_lshl_add_u64 v[210:211], s[76:77], 0, v[150:151]
	s_mov_b32 m0, s20
	s_nop 0
	global_load_lds_dwordx4 v[210:211], off
	v_lshl_add_u64 v[210:211], s[76:77], 0, v[146:147]
	s_mov_b32 m0, s21
	s_nop 0
	global_load_lds_dwordx4 v[210:211], off
	s_add_i32 s76, 0, 0x1c000
	s_add_i32 s68, s68, s17
	v_add_u32_e32 v160, s76, v173
	v_lshl_add_u64 v[158:159], v[158:159], 0, s[92:93]
	s_mov_b32 m0, s68
	ds_read_b128 v[210:213], v160
	ds_read_b128 v[214:217], v160 offset:1024
	ds_read_b128 v[218:221], v160 offset:2048
	ds_read_b128 v[222:225], v160 offset:3072
	global_load_lds_dwordx4 v[158:159], off
	v_lshl_add_u64 v[158:159], v[170:171], 0, s[92:93]
	s_add_i32 m0, s68, 0x2000
	s_nop 0
	global_load_lds_dwordx4 v[158:159], off
	s_barrier
	s_waitcnt lgkmcnt(0)
	s_waitcnt lgkmcnt(0)
	v_mfma_f32_16x16x32_bf16 v[116:119], v[210:213], v[174:177], v[116:119]
	v_mfma_f32_16x16x32_bf16 v[108:111], v[218:221], v[174:177], v[108:111]
	v_mfma_f32_16x16x32_bf16 v[100:103], v[210:213], v[186:189], v[100:103]
	v_mfma_f32_16x16x32_bf16 v[92:95], v[218:221], v[186:189], v[92:95]
	v_mfma_f32_16x16x32_bf16 v[84:87], v[210:213], v[194:197], v[84:87]
	v_mfma_f32_16x16x32_bf16 v[76:79], v[218:221], v[194:197], v[76:79]
	v_mfma_f32_16x16x32_bf16 v[68:71], v[210:213], v[202:205], v[68:71]
	v_mfma_f32_16x16x32_bf16 v[64:67], v[218:221], v[202:205], v[64:67]
	v_mfma_f32_16x16x32_bf16 v[116:119], v[214:217], v[180:183], v[116:119]
	v_mfma_f32_16x16x32_bf16 v[108:111], v[222:225], v[180:183], v[108:111]
	v_mfma_f32_16x16x32_bf16 v[100:103], v[214:217], v[190:193], v[100:103]
	v_mfma_f32_16x16x32_bf16 v[92:95], v[222:225], v[190:193], v[92:95]
	v_mfma_f32_16x16x32_bf16 v[84:87], v[214:217], v[198:201], v[84:87]
	v_mfma_f32_16x16x32_bf16 v[76:79], v[222:225], v[198:201], v[76:79]
	v_mfma_f32_16x16x32_bf16 v[68:71], v[214:217], v[206:209], v[68:71]
	v_mfma_f32_16x16x32_bf16 v[64:67], v[222:225], v[206:209], v[64:67]
	s_mov_b32 m0, s22
	v_lshl_add_u64 v[158:159], v[226:227], 0, s[92:93]
	s_barrier
	ds_read_b128 v[174:177], v185 offset:49152
	ds_read_b128 v[180:183], v185 offset:50176
	ds_read_b128 v[186:189], v185 offset:51200
	ds_read_b128 v[190:193], v185 offset:52224
	ds_read_b128 v[194:197], v185 offset:53248
	ds_read_b128 v[198:201], v185 offset:54272
	ds_read_b128 v[202:205], v185 offset:55296
	ds_read_b128 v[206:209], v185 offset:56320
	global_load_lds_dwordx4 v[158:159], off
	v_lshl_add_u64 v[158:159], v[228:229], 0, s[92:93]
	s_mov_b32 m0, s23
	s_nop 0
	global_load_lds_dwordx4 v[158:159], off
	s_barrier
	s_waitcnt lgkmcnt(0)
	s_waitcnt lgkmcnt(0)
	v_mfma_f32_16x16x32_bf16 v[60:63], v[128:131], v[174:177], v[60:63]
	v_mfma_f32_16x16x32_bf16 v[56:59], v[136:139], v[174:177], v[56:59]
	v_mfma_f32_16x16x32_bf16 v[48:51], v[128:131], v[186:189], v[48:51]
	v_mfma_f32_16x16x32_bf16 v[40:43], v[136:139], v[186:189], v[40:43]
	v_mfma_f32_16x16x32_bf16 v[32:35], v[128:131], v[194:197], v[32:35]
	v_mfma_f32_16x16x32_bf16 v[24:27], v[136:139], v[194:197], v[24:27]
	v_mfma_f32_16x16x32_bf16 v[16:19], v[128:131], v[202:205], v[16:19]
	v_mfma_f32_16x16x32_bf16 v[8:11], v[136:139], v[202:205], v[8:11]
	v_mfma_f32_16x16x32_bf16 v[60:63], v[132:135], v[180:183], v[60:63]
	v_mfma_f32_16x16x32_bf16 v[56:59], v[140:143], v[180:183], v[56:59]
	v_mfma_f32_16x16x32_bf16 v[48:51], v[132:135], v[190:193], v[48:51]
	v_mfma_f32_16x16x32_bf16 v[40:43], v[140:143], v[190:193], v[40:43]
	v_mfma_f32_16x16x32_bf16 v[32:35], v[132:135], v[198:201], v[32:35]
	v_mfma_f32_16x16x32_bf16 v[24:27], v[140:143], v[198:201], v[24:27]
	v_mfma_f32_16x16x32_bf16 v[16:19], v[132:135], v[206:209], v[16:19]
	v_mfma_f32_16x16x32_bf16 v[8:11], v[140:143], v[206:209], v[8:11]
	s_barrier
	s_add_u32 s74, s74, 0x20080
	s_addc_u32 s75, s75, 0
	s_add_i32 s68, s76, s17
	v_lshl_add_u64 v[128:129], s[74:75], 0, v[148:149]
	s_mov_b32 m0, s68
	s_nop 0
	global_load_lds_dwordx4 v[128:129], off
	v_lshl_add_u64 v[128:129], s[74:75], 0, v[144:145]
	s_add_i32 m0, s68, 0x2000
	s_nop 0
	global_load_lds_dwordx4 v[128:129], off
	s_waitcnt vmcnt(6)
	s_barrier
	v_mfma_f32_16x16x32_bf16 v[52:55], v[210:213], v[174:177], v[52:55]
	v_mfma_f32_16x16x32_bf16 v[44:47], v[218:221], v[174:177], v[44:47]
	v_mfma_f32_16x16x32_bf16 v[36:39], v[210:213], v[186:189], v[36:39]
	v_mfma_f32_16x16x32_bf16 v[28:31], v[218:221], v[186:189], v[28:31]
	v_mfma_f32_16x16x32_bf16 v[20:23], v[210:213], v[194:197], v[20:23]
	v_mfma_f32_16x16x32_bf16 v[12:15], v[218:221], v[194:197], v[12:15]
	v_mfma_f32_16x16x32_bf16 v[4:7], v[210:213], v[202:205], v[4:7]
	v_mfma_f32_16x16x32_bf16 v[0:3], v[218:221], v[202:205], v[0:3]
	v_mfma_f32_16x16x32_bf16 v[52:55], v[214:217], v[180:183], v[52:55]
	v_mfma_f32_16x16x32_bf16 v[44:47], v[222:225], v[180:183], v[44:47]
	v_mfma_f32_16x16x32_bf16 v[36:39], v[214:217], v[190:193], v[36:39]
	v_mfma_f32_16x16x32_bf16 v[28:31], v[222:225], v[190:193], v[28:31]
	v_mfma_f32_16x16x32_bf16 v[20:23], v[214:217], v[198:201], v[20:23]
	v_mfma_f32_16x16x32_bf16 v[12:15], v[222:225], v[198:201], v[12:15]
	v_mfma_f32_16x16x32_bf16 v[4:7], v[214:217], v[206:209], v[4:7]
	v_mfma_f32_16x16x32_bf16 v[0:3], v[222:225], v[206:209], v[0:3]
	s_add_i32 s67, s67, 2
	s_add_u32 s72, s72, 0x100
	s_addc_u32 s73, s73, 0
	s_add_u32 s47, s47, 0x100
	s_addc_u32 s66, s66, 0
	s_cmp_gt_u32 s67, 5
	s_cbranch_scc0 .LBB0_474
	s_barrier
	v_lshl_add_u32 v188, s27, 8, v153
	v_ashrrev_i32_e32 v189, 31, v188
	v_lshlrev_b64 v[128:129], 6, v[188:189]
	v_lshl_add_u64 v[132:133], s[6:7], 0, v[128:129]
	global_load_dwordx4 v[128:131], v[132:133], off offset:16
	s_nop 0
	global_load_dwordx4 v[132:135], v[132:133], off
	v_or_b32_e32 v180, 16, v188
	v_ashrrev_i32_e32 v181, 31, v180
	v_lshlrev_b64 v[136:137], 6, v[180:181]
	v_lshl_add_u64 v[140:141], s[6:7], 0, v[136:137]
	global_load_dwordx4 v[136:139], v[140:141], off offset:16
	s_nop 0
	global_load_dwordx4 v[140:143], v[140:141], off
	v_or_b32_e32 v174, 32, v188
	v_ashrrev_i32_e32 v175, 31, v174
	v_lshlrev_b64 v[158:159], 6, v[174:175]
	v_lshl_add_u64 v[158:159], s[6:7], 0, v[158:159]
	global_load_dwordx4 v[192:195], v[158:159], off offset:16
	global_load_dwordx4 v[196:199], v[158:159], off
	v_or_b32_e32 v158, 48, v188
	v_ashrrev_i32_e32 v159, 31, v158
	v_lshlrev_b64 v[170:171], 6, v[158:159]
	v_lshl_add_u64 v[170:171], s[6:7], 0, v[170:171]
	global_load_dwordx4 v[200:203], v[170:171], off offset:16
	global_load_dwordx4 v[204:207], v[170:171], off
	v_add_u32_e32 v186, 0x80, v188
	v_ashrrev_i32_e32 v187, 31, v186
	v_add_u32_e32 v182, 0x90, v188
	v_ashrrev_i32_e32 v183, 31, v182
	v_add_u32_e32 v176, 0xa0, v188
	v_ashrrev_i32_e32 v177, 31, v176
	v_lshlrev_b64 v[170:171], 6, v[176:177]
	v_lshl_add_u64 v[170:171], s[6:7], 0, v[170:171]
	s_lshl_b32 s5, s26, 8
	s_cmp_gt_i32 s26, 3
	s_mov_b64 s[12:13], -1
	s_waitcnt vmcnt(0)
	v_add_f32_e32 v128, v128, v129
	v_add_f32_e32 v132, v132, v133
	v_add_f32_e32 v133, v134, v135
	v_add_f32_e32 v129, v130, v131
	v_add_f32_e32 v132, v132, v133
	v_add_f32_e32 v128, v128, v129
	v_add_f32_e32 v128, v132, v128
	v_fmamk_f32 v128, v128, 0x3b000000, v246
	v_rsq_f32_e32 v190, v128
	v_add_f32_e32 v128, v140, v141
	v_add_f32_e32 v129, v142, v143
	v_add_f32_e32 v128, v128, v129
	v_add_f32_e32 v129, v136, v137
	v_add_f32_e32 v130, v138, v139
	v_add_f32_e32 v129, v129, v130
	v_add_f32_e32 v128, v128, v129
	v_fmamk_f32 v128, v128, 0x3b000000, v246
	v_rsq_f32_e32 v184, v128
	v_add_f32_e32 v128, v196, v197
	v_add_f32_e32 v129, v198, v199
	v_add_f32_e32 v128, v128, v129
	v_add_f32_e32 v129, v192, v193
	v_add_f32_e32 v130, v194, v195
	v_add_f32_e32 v129, v129, v130
	v_add_f32_e32 v128, v128, v129
	v_fmamk_f32 v128, v128, 0x3b000000, v246
	v_rsq_f32_e32 v178, v128
	v_add_f32_e32 v128, v204, v205
	v_add_f32_e32 v129, v206, v207
	v_add_f32_e32 v128, v128, v129
	v_add_f32_e32 v129, v200, v201
	v_add_f32_e32 v130, v202, v203
	v_add_f32_e32 v129, v129, v130
	v_add_f32_e32 v128, v128, v129
	v_fmamk_f32 v128, v128, 0x3b000000, v246
	v_rsq_f32_e32 v172, v128
	v_lshlrev_b64 v[128:129], 6, v[186:187]
	v_lshl_add_u64 v[132:133], s[6:7], 0, v[128:129]
	global_load_dwordx4 v[128:131], v[132:133], off offset:16
	s_nop 0
	global_load_dwordx4 v[132:135], v[132:133], off
	v_lshlrev_b64 v[136:137], 6, v[182:183]
	v_lshl_add_u64 v[140:141], s[6:7], 0, v[136:137]
	global_load_dwordx4 v[136:139], v[140:141], off offset:16
	s_nop 0
	global_load_dwordx4 v[140:143], v[140:141], off
	s_nop 0
	global_load_dwordx4 v[192:195], v[170:171], off offset:16
	global_load_dwordx4 v[200:203], v[170:171], off
	v_add_u32_e32 v170, 0xb0, v188
	v_ashrrev_i32_e32 v171, 31, v170
	v_lshlrev_b64 v[196:197], 6, v[170:171]
	v_lshl_add_u64 v[196:197], s[6:7], 0, v[196:197]
	global_load_dwordx4 v[204:207], v[196:197], off offset:16
	global_load_dwordx4 v[208:211], v[196:197], off
	s_waitcnt vmcnt(0)
	v_add_f32_e32 v128, v128, v129
	v_add_f32_e32 v132, v132, v133
	v_add_f32_e32 v133, v134, v135
	v_add_f32_e32 v129, v130, v131
	v_add_f32_e32 v132, v132, v133
	v_add_f32_e32 v128, v128, v129
	v_add_f32_e32 v128, v132, v128
	v_fmamk_f32 v128, v128, 0x3b000000, v246
	v_rsq_f32_e32 v198, v128
	v_add_f32_e32 v128, v140, v141
	v_add_f32_e32 v129, v142, v143
	v_add_f32_e32 v128, v128, v129
	v_add_f32_e32 v129, v136, v137
	v_add_f32_e32 v130, v138, v139
	v_add_f32_e32 v129, v129, v130
	v_add_f32_e32 v128, v128, v129
	v_fmamk_f32 v128, v128, 0x3b000000, v246
	v_rsq_f32_e32 v196, v128
	v_add_f32_e32 v128, v200, v201
	v_add_f32_e32 v129, v202, v203
	v_add_f32_e32 v128, v128, v129
	v_add_f32_e32 v129, v192, v193
	v_add_f32_e32 v130, v194, v195
	v_add_f32_e32 v129, v129, v130
	v_add_f32_e32 v128, v128, v129
	v_fmamk_f32 v128, v128, 0x3b000000, v246
	v_rsq_f32_e32 v194, v128
	v_add_f32_e32 v128, v208, v209
	v_add_f32_e32 v129, v210, v211
	v_add_f32_e32 v128, v128, v129
	v_add_f32_e32 v129, v204, v205
	v_add_f32_e32 v130, v206, v207
	v_add_f32_e32 v129, v129, v130
	v_add_f32_e32 v128, v128, v129
	v_fmamk_f32 v128, v128, 0x3b000000, v246
	v_rsq_f32_e32 v192, v128
	s_cbranch_scc0 .LBB0_477
	v_lshlrev_b64 v[128:129], 7, v[188:189]
	v_lshlrev_b32_e32 v189, 2, v152
	v_readlane_b32 s26, v252, 4
	v_or_b32_e32 v128, v128, v189
	v_readlane_b32 s27, v252, 5
	v_lshl_add_u64 v[130:131], s[42:43], 0, v[128:129]
	global_load_dwordx4 v[202:205], v[130:131], off offset:16
	global_load_dwordx4 v[206:209], v[130:131], off
	v_lshl_add_u64 v[128:129], s[26:27], 0, v[128:129]
	global_load_dwordx4 v[210:213], v[128:129], off offset:16
	global_load_dwordx4 v[214:217], v[128:129], off
	v_lshlrev_b64 v[132:133], 7, v[180:181]
	v_or_b32_e32 v132, v132, v189
	v_lshl_add_u64 v[134:135], s[42:43], 0, v[132:133]
	v_lshl_add_u64 v[140:141], s[26:27], 0, v[132:133]
	global_load_dwordx4 v[128:131], v[134:135], off offset:16
	global_load_dwordx4 v[136:139], v[134:135], off
	s_nop 0
	global_load_dwordx4 v[132:135], v[140:141], off offset:16
	s_nop 0
	global_load_dwordx4 v[140:143], v[140:141], off
	v_pk_mul_f32 v[230:231], v[118:119], v[190:191] op_sel_hi:[1,0]
	v_pk_mul_f32 v[232:233], v[116:117], v[190:191] op_sel_hi:[1,0]
	v_pk_mul_f32 v[222:223], v[126:127], v[190:191] op_sel_hi:[1,0]
	v_pk_mul_f32 v[224:225], v[124:125], v[190:191] op_sel_hi:[1,0]
	v_readlane_b32 s72, v254, 50
	v_pk_mul_f32 v[234:235], v[110:111], v[190:191] op_sel_hi:[1,0]
	v_pk_mul_f32 v[236:237], v[108:109], v[190:191] op_sel_hi:[1,0]
	v_readlane_b32 s73, v254, 51
	v_pk_mul_f32 v[226:227], v[122:123], v[190:191] op_sel_hi:[1,0]
	v_pk_mul_f32 v[228:229], v[120:121], v[190:191] op_sel_hi:[1,0]
	s_mov_b32 s57, s73
	s_add_i32 s56, s24, s5
	v_lshlrev_b32_e32 v160, 1, v152
	v_readlane_b32 s74, v254, 52
	v_readlane_b32 s75, v254, 53
	v_readlane_b32 s76, v254, 54
	v_readlane_b32 s77, v254, 55
	v_readlane_b32 s78, v254, 56
	v_readlane_b32 s79, v254, 57
	v_readlane_b32 s80, v254, 58
	v_readlane_b32 s81, v254, 59
	v_readlane_b32 s82, v254, 60
	v_readlane_b32 s83, v254, 61
	v_readlane_b32 s84, v254, 62
	v_readlane_b32 s85, v254, 63
	v_readlane_b32 s86, v255, 0
	v_readlane_b32 s87, v255, 1
	s_waitcnt vmcnt(0)
	v_pk_mul_f32 v[220:221], v[234:235], v[212:213]
	v_pk_mul_f32 v[200:201], v[230:231], v[216:217]
	v_pk_mul_f32 v[218:219], v[232:233], v[214:215]
	v_pk_fma_f32 v[200:201], v[222:223], v[208:209], v[200:201] neg_lo:[0,0,1] neg_hi:[0,0,1]
	v_pk_fma_f32 v[218:219], v[224:225], v[206:207], v[218:219] neg_lo:[0,0,1] neg_hi:[0,0,1]
	v_pk_mul_f32 v[238:239], v[236:237], v[210:211]
	v_cvt_pk_bf16_f32 v218, v218, v219
	v_cvt_pk_bf16_f32 v219, v200, v201
	v_mov_b64_e32 v[200:201], s[48:49]
	v_pk_fma_f32 v[240:241], v[226:227], v[204:205], v[220:221] neg_lo:[0,0,1] neg_hi:[0,0,1]
	v_pk_fma_f32 v[220:221], v[228:229], v[202:203], v[238:239] neg_lo:[0,0,1] neg_hi:[0,0,1]
	v_mad_i64_i32 v[238:239], s[12:13], v188, s91, v[200:201]
	s_mov_b32 s13, s73
	s_lshl_b64 s[72:73], s[56:57], 1
	v_lshl_add_u64 v[238:239], v[238:239], 0, s[72:73]
	v_cvt_pk_bf16_f32 v220, v220, v221
	v_cvt_pk_bf16_f32 v221, v240, v241
	v_lshl_add_u64 v[238:239], v[238:239], 0, v[160:161]
	v_pk_mul_f32 v[216:217], v[222:223], v[216:217]
	v_pk_mul_f32 v[212:213], v[226:227], v[212:213]
	v_pk_mul_f32 v[210:211], v[228:229], v[210:211]
	global_store_dwordx4 v[238:239], v[218:221], off offset:2048
	v_pk_mul_f32 v[214:215], v[224:225], v[214:215]
	v_pk_fma_f32 v[208:209], v[230:231], v[208:209], v[216:217]
	v_pk_fma_f32 v[212:213], v[234:235], v[204:205], v[212:213]
	v_pk_fma_f32 v[204:205], v[236:237], v[202:203], v[210:211]
	v_pk_mul_f32 v[218:219], v[102:103], v[184:185] op_sel_hi:[1,0]
	v_pk_mul_f32 v[220:221], v[100:101], v[184:185] op_sel_hi:[1,0]
	v_pk_fma_f32 v[206:207], v[232:233], v[206:207], v[214:215]
	v_pk_mul_f32 v[214:215], v[112:113], v[184:185] op_sel_hi:[1,0]
	v_cvt_pk_bf16_f32 v202, v206, v207
	v_cvt_pk_bf16_f32 v203, v208, v209
	v_cvt_pk_bf16_f32 v204, v204, v205
	v_cvt_pk_bf16_f32 v205, v212, v213
	v_pk_mul_f32 v[212:213], v[114:115], v[184:185] op_sel_hi:[1,0]
	v_pk_mul_f32 v[208:209], v[218:219], v[142:143]
	v_pk_mul_f32 v[210:211], v[220:221], v[140:141]
	v_writelane_b32 v254, s12, 50
	v_pk_fma_f32 v[222:223], v[212:213], v[138:139], v[208:209] neg_lo:[0,0,1] neg_hi:[0,0,1]
	v_pk_fma_f32 v[208:209], v[214:215], v[136:137], v[210:211] neg_lo:[0,0,1] neg_hi:[0,0,1]
	v_writelane_b32 v255, s26, 0
	v_writelane_b32 v254, s13, 51
	v_writelane_b32 v255, s27, 1
	global_store_dwordx4 v[238:239], v[202:205], off offset:2112
	v_pk_mul_f32 v[206:207], v[92:93], v[184:185] op_sel_hi:[1,0]
	v_cvt_pk_bf16_f32 v208, v208, v209
	v_cvt_pk_bf16_f32 v209, v222, v223
	v_mad_i64_i32 v[222:223], s[12:13], v180, s91, v[200:201]
	v_pk_mul_f32 v[204:205], v[94:95], v[184:185] op_sel_hi:[1,0]
	v_pk_mul_f32 v[216:217], v[106:107], v[184:185] op_sel_hi:[1,0]
	v_pk_mul_f32 v[202:203], v[104:105], v[184:185] op_sel_hi:[1,0]
	v_pk_mul_f32 v[210:211], v[204:205], v[134:135]
	v_pk_mul_f32 v[224:225], v[206:207], v[132:133]
	v_lshl_add_u64 v[222:223], v[222:223], 0, s[72:73]
	v_pk_fma_f32 v[226:227], v[216:217], v[130:131], v[210:211] neg_lo:[0,0,1] neg_hi:[0,0,1]
	v_pk_fma_f32 v[210:211], v[202:203], v[128:129], v[224:225] neg_lo:[0,0,1] neg_hi:[0,0,1]
	v_lshl_add_u64 v[222:223], v[222:223], 0, v[160:161]
	v_pk_mul_f32 v[142:143], v[212:213], v[142:143]
	v_pk_mul_f32 v[140:141], v[214:215], v[140:141]
	v_pk_mul_f32 v[134:135], v[216:217], v[134:135]
	v_pk_mul_f32 v[132:133], v[202:203], v[132:133]
	v_cvt_pk_bf16_f32 v210, v210, v211
	v_cvt_pk_bf16_f32 v211, v226, v227
	global_store_dwordx4 v[222:223], v[208:211], off offset:2048
	v_pk_fma_f32 v[138:139], v[218:219], v[138:139], v[142:143]
	v_pk_fma_f32 v[136:137], v[220:221], v[136:137], v[140:141]
	v_pk_fma_f32 v[134:135], v[204:205], v[130:131], v[134:135]
	v_pk_fma_f32 v[130:131], v[206:207], v[128:129], v[132:133]
	v_cvt_pk_bf16_f32 v128, v136, v137
	v_cvt_pk_bf16_f32 v129, v138, v139
	v_lshlrev_b64 v[136:137], 7, v[158:159]
	v_cvt_pk_bf16_f32 v130, v130, v131
	v_cvt_pk_bf16_f32 v131, v134, v135
	global_store_dwordx4 v[222:223], v[128:131], off offset:2112
	v_or_b32_e32 v136, v136, v189
	v_lshl_add_u64 v[132:133], s[42:43], 0, v[136:137]
	v_lshlrev_b64 v[128:129], 7, v[174:175]
	v_or_b32_e32 v128, v128, v189
	v_lshl_add_u64 v[130:131], s[42:43], 0, v[128:129]
	v_lshl_add_u64 v[128:129], s[26:27], 0, v[128:129]
	global_load_dwordx4 v[202:205], v[130:131], off offset:16
	global_load_dwordx4 v[206:209], v[130:131], off
	global_load_dwordx4 v[210:213], v[128:129], off offset:16
	global_load_dwordx4 v[214:217], v[128:129], off
	v_lshl_add_u64 v[140:141], s[26:27], 0, v[136:137]
	global_load_dwordx4 v[128:131], v[132:133], off offset:16
	s_nop 0
	global_load_dwordx4 v[132:135], v[132:133], off
	s_nop 0
	global_load_dwordx4 v[136:139], v[140:141], off offset:16
	s_nop 0
	global_load_dwordx4 v[140:143], v[140:141], off
	v_pk_mul_f32 v[230:231], v[86:87], v[178:179] op_sel_hi:[1,0]
	v_pk_mul_f32 v[232:233], v[84:85], v[178:179] op_sel_hi:[1,0]
	v_pk_mul_f32 v[222:223], v[98:99], v[178:179] op_sel_hi:[1,0]
	v_pk_mul_f32 v[224:225], v[96:97], v[178:179] op_sel_hi:[1,0]
	v_pk_mul_f32 v[226:227], v[90:91], v[178:179] op_sel_hi:[1,0]
	v_pk_mul_f32 v[228:229], v[88:89], v[178:179] op_sel_hi:[1,0]
	v_pk_mul_f32 v[234:235], v[78:79], v[178:179] op_sel_hi:[1,0]
	v_pk_mul_f32 v[236:237], v[76:77], v[178:179] op_sel_hi:[1,0]
	v_or_b32_e32 v159, 16, v186
	v_writelane_b32 v254, s14, 52
	v_writelane_b32 v254, s15, 53
	v_writelane_b32 v254, s16, 54
	v_writelane_b32 v254, s17, 55
	v_writelane_b32 v254, s18, 56
	v_writelane_b32 v254, s19, 57
	v_writelane_b32 v254, s20, 58
	v_writelane_b32 v254, s21, 59
	v_writelane_b32 v254, s22, 60
	v_writelane_b32 v254, s23, 61
	v_writelane_b32 v254, s24, 62
	v_writelane_b32 v254, s25, 63
	s_waitcnt vmcnt(0)
	v_pk_mul_f32 v[240:241], v[236:237], v[210:211]
	v_pk_mul_f32 v[218:219], v[230:231], v[216:217]
	v_pk_mul_f32 v[220:221], v[232:233], v[214:215]
	v_pk_fma_f32 v[238:239], v[222:223], v[208:209], v[218:219] neg_lo:[0,0,1] neg_hi:[0,0,1]
	v_pk_fma_f32 v[218:219], v[224:225], v[206:207], v[220:221] neg_lo:[0,0,1] neg_hi:[0,0,1]
	v_pk_mul_f32 v[220:221], v[234:235], v[212:213]
	v_cvt_pk_bf16_f32 v218, v218, v219
	v_cvt_pk_bf16_f32 v219, v238, v239
	v_mad_i64_i32 v[238:239], s[12:13], v174, s91, v[200:201]
	v_lshl_add_u64 v[238:239], v[238:239], 0, s[72:73]
	v_pk_mul_f32 v[212:213], v[226:227], v[212:213]
	v_pk_mul_f32 v[210:211], v[228:229], v[210:211]
	v_pk_fma_f32 v[248:249], v[226:227], v[204:205], v[220:221] neg_lo:[0,0,1] neg_hi:[0,0,1]
	v_pk_fma_f32 v[220:221], v[228:229], v[202:203], v[240:241] neg_lo:[0,0,1] neg_hi:[0,0,1]
	v_lshl_add_u64 v[238:239], v[238:239], 0, v[160:161]
	v_pk_mul_f32 v[216:217], v[222:223], v[216:217]
	v_pk_mul_f32 v[214:215], v[224:225], v[214:215]
	v_pk_fma_f32 v[212:213], v[234:235], v[204:205], v[212:213]
	v_pk_fma_f32 v[204:205], v[236:237], v[202:203], v[210:211]
	v_cvt_pk_bf16_f32 v220, v220, v221
	v_cvt_pk_bf16_f32 v221, v248, v249
	global_store_dwordx4 v[238:239], v[218:221], off offset:2048
	v_pk_fma_f32 v[208:209], v[230:231], v[208:209], v[216:217]
	v_pk_fma_f32 v[206:207], v[232:233], v[206:207], v[214:215]
	v_pk_mul_f32 v[210:211], v[70:71], v[172:173] op_sel_hi:[1,0]
	v_cvt_pk_bf16_f32 v202, v206, v207
	v_cvt_pk_bf16_f32 v203, v208, v209
	v_cvt_pk_bf16_f32 v204, v204, v205
	v_cvt_pk_bf16_f32 v205, v212, v213
	v_pk_mul_f32 v[212:213], v[68:69], v[172:173] op_sel_hi:[1,0]
	global_store_dwordx4 v[238:239], v[202:205], off offset:2112
	v_pk_mul_f32 v[218:219], v[210:211], v[142:143]
	v_pk_mul_f32 v[220:221], v[212:213], v[140:141]
	v_pk_mul_f32 v[202:203], v[82:83], v[172:173] op_sel_hi:[1,0]
	v_pk_mul_f32 v[204:205], v[80:81], v[172:173] op_sel_hi:[1,0]
	v_pk_fma_f32 v[222:223], v[202:203], v[134:135], v[218:219] neg_lo:[0,0,1] neg_hi:[0,0,1]
	v_pk_fma_f32 v[218:219], v[204:205], v[132:133], v[220:221] neg_lo:[0,0,1] neg_hi:[0,0,1]
	v_pk_mul_f32 v[214:215], v[66:67], v[172:173] op_sel_hi:[1,0]
	v_pk_mul_f32 v[216:217], v[64:65], v[172:173] op_sel_hi:[1,0]
	v_cvt_pk_bf16_f32 v218, v218, v219
	v_cvt_pk_bf16_f32 v219, v222, v223
	v_mad_i64_i32 v[222:223], s[12:13], v158, s91, v[200:201]
	v_pk_mul_f32 v[206:207], v[74:75], v[172:173] op_sel_hi:[1,0]
	v_pk_mul_f32 v[208:209], v[72:73], v[172:173] op_sel_hi:[1,0]
	v_pk_mul_f32 v[220:221], v[214:215], v[138:139]
	v_pk_mul_f32 v[224:225], v[216:217], v[136:137]
	v_lshl_add_u64 v[222:223], v[222:223], 0, s[72:73]
	v_pk_fma_f32 v[226:227], v[206:207], v[130:131], v[220:221] neg_lo:[0,0,1] neg_hi:[0,0,1]
	v_pk_fma_f32 v[220:221], v[208:209], v[128:129], v[224:225] neg_lo:[0,0,1] neg_hi:[0,0,1]
	v_lshl_add_u64 v[222:223], v[222:223], 0, v[160:161]
	v_pk_mul_f32 v[142:143], v[202:203], v[142:143]
	v_pk_mul_f32 v[140:141], v[204:205], v[140:141]
	v_pk_mul_f32 v[138:139], v[206:207], v[138:139]
	v_pk_mul_f32 v[136:137], v[208:209], v[136:137]
	v_cvt_pk_bf16_f32 v220, v220, v221
	v_cvt_pk_bf16_f32 v221, v226, v227
	global_store_dwordx4 v[222:223], v[218:221], off offset:2048
	v_pk_fma_f32 v[134:135], v[210:211], v[134:135], v[142:143]
	v_pk_fma_f32 v[132:133], v[212:213], v[132:133], v[140:141]
	v_pk_fma_f32 v[138:139], v[214:215], v[130:131], v[138:139]
	v_pk_fma_f32 v[130:131], v[216:217], v[128:129], v[136:137]
	v_cvt_pk_bf16_f32 v128, v132, v133
	v_cvt_pk_bf16_f32 v129, v134, v135
	v_lshlrev_b64 v[136:137], 7, v[182:183]
	v_cvt_pk_bf16_f32 v130, v130, v131
	v_cvt_pk_bf16_f32 v131, v138, v139
	global_store_dwordx4 v[222:223], v[128:131], off offset:2112
	v_or_b32_e32 v136, v136, v189
	v_lshl_add_u64 v[132:133], s[42:43], 0, v[136:137]
	v_lshlrev_b64 v[128:129], 7, v[186:187]
	v_or_b32_e32 v128, v128, v189
	v_lshl_add_u64 v[130:131], s[42:43], 0, v[128:129]
	v_lshl_add_u64 v[128:129], s[26:27], 0, v[128:129]
	global_load_dwordx4 v[202:205], v[130:131], off offset:16
	global_load_dwordx4 v[206:209], v[130:131], off
	global_load_dwordx4 v[210:213], v[128:129], off offset:16
	global_load_dwordx4 v[214:217], v[128:129], off
	v_lshl_add_u64 v[140:141], s[26:27], 0, v[136:137]
	global_load_dwordx4 v[128:131], v[132:133], off offset:16
	s_nop 0
	global_load_dwordx4 v[132:135], v[132:133], off
	s_nop 0
	global_load_dwordx4 v[136:139], v[140:141], off offset:16
	s_nop 0
	global_load_dwordx4 v[140:143], v[140:141], off
	v_pk_mul_f32 v[230:231], v[54:55], v[198:199] op_sel_hi:[1,0]
	v_pk_mul_f32 v[232:233], v[52:53], v[198:199] op_sel_hi:[1,0]
	v_pk_mul_f32 v[222:223], v[62:63], v[198:199] op_sel_hi:[1,0]
	v_pk_mul_f32 v[224:225], v[60:61], v[198:199] op_sel_hi:[1,0]
	v_pk_mul_f32 v[226:227], v[58:59], v[198:199] op_sel_hi:[1,0]
	v_pk_mul_f32 v[228:229], v[56:57], v[198:199] op_sel_hi:[1,0]
	v_pk_mul_f32 v[234:235], v[46:47], v[198:199] op_sel_hi:[1,0]
	v_pk_mul_f32 v[236:237], v[44:45], v[198:199] op_sel_hi:[1,0]
	s_waitcnt vmcnt(0)
	v_pk_mul_f32 v[218:219], v[230:231], v[216:217]
	v_pk_mul_f32 v[220:221], v[232:233], v[214:215]
	v_pk_fma_f32 v[238:239], v[222:223], v[208:209], v[218:219] neg_lo:[0,0,1] neg_hi:[0,0,1]
	v_pk_fma_f32 v[218:219], v[224:225], v[206:207], v[220:221] neg_lo:[0,0,1] neg_hi:[0,0,1]
	v_pk_mul_f32 v[220:221], v[234:235], v[212:213]
	v_cvt_pk_bf16_f32 v218, v218, v219
	v_cvt_pk_bf16_f32 v219, v238, v239
	v_mad_i64_i32 v[238:239], s[12:13], v186, s91, v[200:201]
	v_pk_mul_f32 v[240:241], v[236:237], v[210:211]
	v_lshl_add_u64 v[238:239], v[238:239], 0, s[72:73]
	v_pk_mul_f32 v[212:213], v[226:227], v[212:213]
	v_pk_mul_f32 v[210:211], v[228:229], v[210:211]
	v_pk_fma_f32 v[248:249], v[226:227], v[204:205], v[220:221] neg_lo:[0,0,1] neg_hi:[0,0,1]
	v_pk_fma_f32 v[220:221], v[228:229], v[202:203], v[240:241] neg_lo:[0,0,1] neg_hi:[0,0,1]
	v_lshl_add_u64 v[238:239], v[238:239], 0, v[160:161]
	v_pk_mul_f32 v[216:217], v[222:223], v[216:217]
	v_pk_mul_f32 v[214:215], v[224:225], v[214:215]
	v_pk_fma_f32 v[212:213], v[234:235], v[204:205], v[212:213]
	v_pk_fma_f32 v[204:205], v[236:237], v[202:203], v[210:211]
	v_cvt_pk_bf16_f32 v220, v220, v221
	v_cvt_pk_bf16_f32 v221, v248, v249
	global_store_dwordx4 v[238:239], v[218:221], off offset:2048
	v_pk_fma_f32 v[208:209], v[230:231], v[208:209], v[216:217]
	v_pk_fma_f32 v[206:207], v[232:233], v[206:207], v[214:215]
	v_pk_mul_f32 v[214:215], v[38:39], v[196:197] op_sel_hi:[1,0]
	v_cvt_pk_bf16_f32 v202, v206, v207
	v_cvt_pk_bf16_f32 v203, v208, v209
	v_cvt_pk_bf16_f32 v204, v204, v205
	v_cvt_pk_bf16_f32 v205, v212, v213
	v_pk_mul_f32 v[216:217], v[36:37], v[196:197] op_sel_hi:[1,0]
	global_store_dwordx4 v[238:239], v[202:205], off offset:2112
	v_pk_mul_f32 v[206:207], v[50:51], v[196:197] op_sel_hi:[1,0]
	v_pk_mul_f32 v[208:209], v[48:49], v[196:197] op_sel_hi:[1,0]
	v_pk_mul_f32 v[202:203], v[214:215], v[142:143]
	v_pk_mul_f32 v[204:205], v[216:217], v[140:141]
	v_pk_fma_f32 v[222:223], v[206:207], v[134:135], v[202:203] neg_lo:[0,0,1] neg_hi:[0,0,1]
	v_pk_fma_f32 v[202:203], v[208:209], v[132:133], v[204:205] neg_lo:[0,0,1] neg_hi:[0,0,1]
	v_pk_mul_f32 v[218:219], v[30:31], v[196:197] op_sel_hi:[1,0]
	v_pk_mul_f32 v[220:221], v[28:29], v[196:197] op_sel_hi:[1,0]
	v_cvt_pk_bf16_f32 v202, v202, v203
	v_cvt_pk_bf16_f32 v203, v222, v223
	v_mad_i64_i32 v[222:223], s[12:13], v159, s91, v[200:201]
	v_pk_mul_f32 v[210:211], v[42:43], v[196:197] op_sel_hi:[1,0]
	v_pk_mul_f32 v[212:213], v[40:41], v[196:197] op_sel_hi:[1,0]
	v_pk_mul_f32 v[204:205], v[218:219], v[138:139]
	v_pk_mul_f32 v[224:225], v[220:221], v[136:137]
	v_lshl_add_u64 v[222:223], v[222:223], 0, s[72:73]
	v_pk_fma_f32 v[226:227], v[210:211], v[130:131], v[204:205] neg_lo:[0,0,1] neg_hi:[0,0,1]
	v_pk_fma_f32 v[204:205], v[212:213], v[128:129], v[224:225] neg_lo:[0,0,1] neg_hi:[0,0,1]
	v_lshl_add_u64 v[222:223], v[222:223], 0, v[160:161]
	v_pk_mul_f32 v[142:143], v[206:207], v[142:143]
	v_pk_mul_f32 v[140:141], v[208:209], v[140:141]
	v_pk_mul_f32 v[138:139], v[210:211], v[138:139]
	v_pk_mul_f32 v[136:137], v[212:213], v[136:137]
	v_cvt_pk_bf16_f32 v204, v204, v205
	v_cvt_pk_bf16_f32 v205, v226, v227
	global_store_dwordx4 v[222:223], v[202:205], off offset:2048
	v_pk_fma_f32 v[134:135], v[214:215], v[134:135], v[142:143]
	v_pk_fma_f32 v[132:133], v[216:217], v[132:133], v[140:141]
	v_pk_fma_f32 v[138:139], v[218:219], v[130:131], v[138:139]
	v_pk_fma_f32 v[130:131], v[220:221], v[128:129], v[136:137]
	v_cvt_pk_bf16_f32 v128, v132, v133
	v_cvt_pk_bf16_f32 v129, v134, v135
	v_lshlrev_b64 v[136:137], 7, v[170:171]
	v_cvt_pk_bf16_f32 v130, v130, v131
	v_cvt_pk_bf16_f32 v131, v138, v139
	global_store_dwordx4 v[222:223], v[128:131], off offset:2112
	v_or_b32_e32 v136, v136, v189
	v_lshl_add_u64 v[132:133], s[42:43], 0, v[136:137]
	v_lshlrev_b64 v[128:129], 7, v[176:177]
	v_or_b32_e32 v128, v128, v189
	v_lshl_add_u64 v[130:131], s[42:43], 0, v[128:129]
	v_lshl_add_u64 v[128:129], s[26:27], 0, v[128:129]
	global_load_dwordx4 v[202:205], v[130:131], off offset:16
	global_load_dwordx4 v[206:209], v[130:131], off
	global_load_dwordx4 v[210:213], v[128:129], off offset:16
	global_load_dwordx4 v[214:217], v[128:129], off
	v_lshl_add_u64 v[140:141], s[26:27], 0, v[136:137]
	global_load_dwordx4 v[128:131], v[132:133], off offset:16
	s_nop 0
	global_load_dwordx4 v[132:135], v[132:133], off
	s_nop 0
	global_load_dwordx4 v[136:139], v[140:141], off offset:16
	s_nop 0
	global_load_dwordx4 v[140:143], v[140:141], off
	v_pk_mul_f32 v[230:231], v[22:23], v[194:195] op_sel_hi:[1,0]
	v_pk_mul_f32 v[232:233], v[20:21], v[194:195] op_sel_hi:[1,0]
	v_pk_mul_f32 v[222:223], v[34:35], v[194:195] op_sel_hi:[1,0]
	v_pk_mul_f32 v[224:225], v[32:33], v[194:195] op_sel_hi:[1,0]
	v_or_b32_e32 v159, 32, v186
	v_pk_mul_f32 v[226:227], v[26:27], v[194:195] op_sel_hi:[1,0]
	v_pk_mul_f32 v[228:229], v[24:25], v[194:195] op_sel_hi:[1,0]
	v_pk_mul_f32 v[234:235], v[14:15], v[194:195] op_sel_hi:[1,0]
	v_pk_mul_f32 v[236:237], v[12:13], v[194:195] op_sel_hi:[1,0]
	s_waitcnt vmcnt(0)
	v_pk_mul_f32 v[218:219], v[230:231], v[216:217]
	v_pk_mul_f32 v[220:221], v[232:233], v[214:215]
	v_pk_fma_f32 v[238:239], v[222:223], v[208:209], v[218:219] neg_lo:[0,0,1] neg_hi:[0,0,1]
	v_pk_fma_f32 v[218:219], v[224:225], v[206:207], v[220:221] neg_lo:[0,0,1] neg_hi:[0,0,1]
	v_pk_mul_f32 v[220:221], v[234:235], v[212:213]
	v_cvt_pk_bf16_f32 v218, v218, v219
	v_cvt_pk_bf16_f32 v219, v238, v239
	v_mad_i64_i32 v[238:239], s[12:13], v159, s91, v[200:201]
	v_pk_mul_f32 v[240:241], v[236:237], v[210:211]
	v_lshl_add_u64 v[238:239], v[238:239], 0, s[72:73]
	v_pk_mul_f32 v[212:213], v[226:227], v[212:213]
	v_pk_mul_f32 v[210:211], v[228:229], v[210:211]
	v_pk_fma_f32 v[248:249], v[226:227], v[204:205], v[220:221] neg_lo:[0,0,1] neg_hi:[0,0,1]
	v_pk_fma_f32 v[220:221], v[228:229], v[202:203], v[240:241] neg_lo:[0,0,1] neg_hi:[0,0,1]
	v_lshl_add_u64 v[238:239], v[238:239], 0, v[160:161]
	v_pk_mul_f32 v[216:217], v[222:223], v[216:217]
	v_pk_mul_f32 v[214:215], v[224:225], v[214:215]
	v_pk_fma_f32 v[212:213], v[234:235], v[204:205], v[212:213]
	v_pk_fma_f32 v[204:205], v[236:237], v[202:203], v[210:211]
	v_cvt_pk_bf16_f32 v220, v220, v221
	v_cvt_pk_bf16_f32 v221, v248, v249
	global_store_dwordx4 v[238:239], v[218:221], off offset:2048
	v_pk_fma_f32 v[208:209], v[230:231], v[208:209], v[216:217]
	v_pk_fma_f32 v[206:207], v[232:233], v[206:207], v[214:215]
	v_or_b32_e32 v159, 48, v186
	v_cvt_pk_bf16_f32 v202, v206, v207
	v_cvt_pk_bf16_f32 v203, v208, v209
	v_cvt_pk_bf16_f32 v204, v204, v205
	v_cvt_pk_bf16_f32 v205, v212, v213
	v_pk_mul_f32 v[214:215], v[6:7], v[192:193] op_sel_hi:[1,0]
	v_pk_mul_f32 v[216:217], v[4:5], v[192:193] op_sel_hi:[1,0]
	global_store_dwordx4 v[238:239], v[202:205], off offset:2112
	v_pk_mul_f32 v[206:207], v[18:19], v[192:193] op_sel_hi:[1,0]
	v_pk_mul_f32 v[208:209], v[16:17], v[192:193] op_sel_hi:[1,0]
	v_pk_mul_f32 v[210:211], v[10:11], v[192:193] op_sel_hi:[1,0]
	v_pk_mul_f32 v[212:213], v[8:9], v[192:193] op_sel_hi:[1,0]
	v_pk_mul_f32 v[218:219], v[2:3], v[192:193] op_sel_hi:[1,0]
	v_pk_mul_f32 v[220:221], v[0:1], v[192:193] op_sel_hi:[1,0]
	v_pk_mul_f32 v[202:203], v[214:215], v[142:143]
	v_pk_mul_f32 v[204:205], v[216:217], v[140:141]
	v_mad_i64_i32 v[200:201], s[12:13], v159, s91, v[200:201]
	v_pk_fma_f32 v[222:223], v[206:207], v[134:135], v[202:203] neg_lo:[0,0,1] neg_hi:[0,0,1]
	v_pk_fma_f32 v[202:203], v[208:209], v[132:133], v[204:205] neg_lo:[0,0,1] neg_hi:[0,0,1]
	v_pk_mul_f32 v[204:205], v[218:219], v[138:139]
	v_pk_mul_f32 v[224:225], v[220:221], v[136:137]
	v_lshl_add_u64 v[200:201], v[200:201], 0, s[72:73]
	v_pk_mul_f32 v[138:139], v[210:211], v[138:139]
	v_pk_mul_f32 v[136:137], v[212:213], v[136:137]
	v_pk_fma_f32 v[226:227], v[210:211], v[130:131], v[204:205] neg_lo:[0,0,1] neg_hi:[0,0,1]
	v_pk_fma_f32 v[204:205], v[212:213], v[128:129], v[224:225] neg_lo:[0,0,1] neg_hi:[0,0,1]
	v_lshl_add_u64 v[200:201], v[200:201], 0, v[160:161]
	v_pk_mul_f32 v[142:143], v[206:207], v[142:143]
	v_pk_mul_f32 v[140:141], v[208:209], v[140:141]
	v_pk_fma_f32 v[138:139], v[218:219], v[130:131], v[138:139]
	v_pk_fma_f32 v[130:131], v[220:221], v[128:129], v[136:137]
	v_cvt_pk_bf16_f32 v202, v202, v203
	v_cvt_pk_bf16_f32 v203, v222, v223
	v_cvt_pk_bf16_f32 v204, v204, v205
	v_cvt_pk_bf16_f32 v205, v226, v227
	global_store_dwordx4 v[200:201], v[202:205], off offset:2048
	v_pk_fma_f32 v[134:135], v[214:215], v[134:135], v[142:143]
	v_pk_fma_f32 v[132:133], v[216:217], v[132:133], v[140:141]
	s_mov_b64 s[12:13], 0
	v_cvt_pk_bf16_f32 v128, v132, v133
	v_cvt_pk_bf16_f32 v129, v134, v135
	v_cvt_pk_bf16_f32 v130, v130, v131
	v_cvt_pk_bf16_f32 v131, v138, v139
	global_store_dwordx4 v[200:201], v[128:131], off offset:2112

.LBB0_493:
	s_barrier
	s_add_u32 s0, s76, 0xfffe0080
	s_addc_u32 s1, s77, -1
	s_add_i32 s68, 0, 0x10000
	v_add_u32_e32 v146, s68, v153
	ds_read_b128 v[128:131], v146
	ds_read_b128 v[132:135], v146 offset:1024
	ds_read_b128 v[154:157], v146 offset:2048
	ds_read_b128 v[170:173], v146 offset:3072
	s_cmp_eq_u32 s67, 4
	s_cselect_b32 s79, s12, s1
	s_cselect_b32 s78, s13, s0
	s_cselect_b32 s1, s14, s66
	s_cselect_b32 s0, s15, s47
	ds_read_b128 v[178:181], v177
	ds_read_b128 v[182:185], v177 offset:1024
	ds_read_b128 v[186:189], v177 offset:2048
	ds_read_b128 v[190:193], v177 offset:3072
	ds_read_b128 v[194:197], v177 offset:4096
	ds_read_b128 v[198:201], v177 offset:5120
	ds_read_b128 v[202:205], v177 offset:6144
	ds_read_b128 v[206:209], v177 offset:7168
	s_waitcnt lgkmcnt(8)
	s_barrier
	s_waitcnt lgkmcnt(0)
	s_waitcnt lgkmcnt(0)
	v_mfma_f32_16x16x32_bf16 v[124:127], v[128:131], v[178:181], v[124:127]
	v_mfma_f32_16x16x32_bf16 v[120:123], v[154:157], v[178:181], v[120:123]
	v_mfma_f32_16x16x32_bf16 v[112:115], v[128:131], v[186:189], v[112:115]
	v_mfma_f32_16x16x32_bf16 v[104:107], v[154:157], v[186:189], v[104:107]
	v_mfma_f32_16x16x32_bf16 v[96:99], v[128:131], v[194:197], v[96:99]
	v_mfma_f32_16x16x32_bf16 v[88:91], v[154:157], v[194:197], v[88:91]
	v_mfma_f32_16x16x32_bf16 v[80:83], v[128:131], v[202:205], v[80:83]
	v_mfma_f32_16x16x32_bf16 v[72:75], v[154:157], v[202:205], v[72:75]
	v_mfma_f32_16x16x32_bf16 v[124:127], v[132:135], v[182:185], v[124:127]
	v_mfma_f32_16x16x32_bf16 v[120:123], v[170:173], v[182:185], v[120:123]
	v_mfma_f32_16x16x32_bf16 v[112:115], v[132:135], v[190:193], v[112:115]
	v_mfma_f32_16x16x32_bf16 v[104:107], v[170:173], v[190:193], v[104:107]
	v_mfma_f32_16x16x32_bf16 v[96:99], v[132:135], v[198:201], v[96:99]
	v_mfma_f32_16x16x32_bf16 v[88:91], v[170:173], v[198:201], v[88:91]
	v_mfma_f32_16x16x32_bf16 v[80:83], v[132:135], v[206:209], v[80:83]
	v_mfma_f32_16x16x32_bf16 v[72:75], v[170:173], v[206:209], v[72:75]
	s_barrier
	v_lshl_add_u64 v[146:147], s[76:77], 0, v[142:143]
	s_add_i32 m0, s20, 0xc000
	s_nop 0
	global_load_lds_dwordx4 v[146:147], off
	v_lshl_add_u64 v[146:147], s[76:77], 0, v[144:145]
	s_add_i32 m0, s20, 0xe000
	s_nop 0
	global_load_lds_dwordx4 v[146:147], off
	s_add_i32 s71, 0, 0x14000
	v_add_u32_e32 v146, s71, v153
	s_add_i32 s68, s68, s19
	ds_read_b128 v[210:213], v146
	ds_read_b128 v[214:217], v146 offset:1024
	ds_read_b128 v[218:221], v146 offset:2048
	ds_read_b128 v[222:225], v146 offset:3072
	v_lshl_add_u64 v[146:147], s[0:1], 0, v[160:161]
	s_mov_b32 m0, s68
	v_lshl_add_u64 v[150:151], s[0:1], 0, v[136:137]
	global_load_lds_dwordx4 v[146:147], off
	s_add_i32 m0, s68, 0x2000
	s_nop 0
	global_load_lds_dwordx4 v[150:151], off
	s_barrier
	s_waitcnt lgkmcnt(0)
	s_waitcnt lgkmcnt(0)
	v_mfma_f32_16x16x32_bf16 v[116:119], v[210:213], v[178:181], v[116:119]
	v_mfma_f32_16x16x32_bf16 v[108:111], v[218:221], v[178:181], v[108:111]
	v_mfma_f32_16x16x32_bf16 v[100:103], v[210:213], v[186:189], v[100:103]
	v_mfma_f32_16x16x32_bf16 v[92:95], v[218:221], v[186:189], v[92:95]
	v_mfma_f32_16x16x32_bf16 v[84:87], v[210:213], v[194:197], v[84:87]
	v_mfma_f32_16x16x32_bf16 v[76:79], v[218:221], v[194:197], v[76:79]
	v_mfma_f32_16x16x32_bf16 v[68:71], v[210:213], v[202:205], v[68:71]
	v_mfma_f32_16x16x32_bf16 v[64:67], v[218:221], v[202:205], v[64:67]
	v_mfma_f32_16x16x32_bf16 v[116:119], v[214:217], v[182:185], v[116:119]
	v_mfma_f32_16x16x32_bf16 v[108:111], v[222:225], v[182:185], v[108:111]
	v_mfma_f32_16x16x32_bf16 v[100:103], v[214:217], v[190:193], v[100:103]
	v_mfma_f32_16x16x32_bf16 v[92:95], v[222:225], v[190:193], v[92:95]
	v_mfma_f32_16x16x32_bf16 v[84:87], v[214:217], v[198:201], v[84:87]
	v_mfma_f32_16x16x32_bf16 v[76:79], v[222:225], v[198:201], v[76:79]
	v_mfma_f32_16x16x32_bf16 v[68:71], v[214:217], v[206:209], v[68:71]
	v_mfma_f32_16x16x32_bf16 v[64:67], v[222:225], v[206:209], v[64:67]
	s_mov_b32 m0, s20
	v_lshl_add_u64 v[174:175], s[78:79], 0, v[140:141]
	s_barrier
	ds_read_b128 v[178:181], v177 offset:16384
	ds_read_b128 v[182:185], v177 offset:17408
	ds_read_b128 v[186:189], v177 offset:18432
	ds_read_b128 v[190:193], v177 offset:19456
	ds_read_b128 v[194:197], v177 offset:20480
	ds_read_b128 v[198:201], v177 offset:21504
	ds_read_b128 v[202:205], v177 offset:22528
	ds_read_b128 v[206:209], v177 offset:23552
	global_load_lds_dwordx4 v[174:175], off
	v_lshl_add_u64 v[226:227], s[78:79], 0, v[138:139]
	s_mov_b32 m0, s21
	s_nop 0
	global_load_lds_dwordx4 v[226:227], off
	s_barrier
	s_waitcnt lgkmcnt(0)
	s_waitcnt lgkmcnt(0)
	v_mfma_f32_16x16x32_bf16 v[60:63], v[128:131], v[178:181], v[60:63]
	v_mfma_f32_16x16x32_bf16 v[56:59], v[154:157], v[178:181], v[56:59]
	v_mfma_f32_16x16x32_bf16 v[48:51], v[128:131], v[186:189], v[48:51]
	v_mfma_f32_16x16x32_bf16 v[40:43], v[154:157], v[186:189], v[40:43]
	v_mfma_f32_16x16x32_bf16 v[32:35], v[128:131], v[194:197], v[32:35]
	v_mfma_f32_16x16x32_bf16 v[24:27], v[154:157], v[194:197], v[24:27]
	v_mfma_f32_16x16x32_bf16 v[16:19], v[128:131], v[202:205], v[16:19]
	v_mfma_f32_16x16x32_bf16 v[8:11], v[154:157], v[202:205], v[8:11]
	v_mfma_f32_16x16x32_bf16 v[60:63], v[132:135], v[182:185], v[60:63]
	v_mfma_f32_16x16x32_bf16 v[56:59], v[170:173], v[182:185], v[56:59]
	v_mfma_f32_16x16x32_bf16 v[48:51], v[132:135], v[190:193], v[48:51]
	v_mfma_f32_16x16x32_bf16 v[40:43], v[170:173], v[190:193], v[40:43]
	v_mfma_f32_16x16x32_bf16 v[32:35], v[132:135], v[198:201], v[32:35]
	v_mfma_f32_16x16x32_bf16 v[24:27], v[170:173], v[198:201], v[24:27]
	v_mfma_f32_16x16x32_bf16 v[16:19], v[132:135], v[206:209], v[16:19]
	v_mfma_f32_16x16x32_bf16 v[8:11], v[170:173], v[206:209], v[8:11]
	s_barrier
	s_add_u32 s80, s0, 0x20000
	s_addc_u32 s81, s1, 0
	s_add_i32 s68, s71, s19
	v_lshl_add_u64 v[128:129], s[80:81], 0, v[160:161]
	s_mov_b32 m0, s68
	s_nop 0
	global_load_lds_dwordx4 v[128:129], off
	v_lshl_add_u64 v[128:129], s[80:81], 0, v[136:137]
	s_add_i32 m0, s68, 0x2000
	s_nop 0
	global_load_lds_dwordx4 v[128:129], off
	s_waitcnt vmcnt(6)
	s_barrier
	v_mfma_f32_16x16x32_bf16 v[52:55], v[210:213], v[178:181], v[52:55]
	v_mfma_f32_16x16x32_bf16 v[44:47], v[218:221], v[178:181], v[44:47]
	v_mfma_f32_16x16x32_bf16 v[36:39], v[210:213], v[186:189], v[36:39]
	v_mfma_f32_16x16x32_bf16 v[28:31], v[218:221], v[186:189], v[28:31]
	v_mfma_f32_16x16x32_bf16 v[20:23], v[210:213], v[194:197], v[20:23]
	v_mfma_f32_16x16x32_bf16 v[12:15], v[218:221], v[194:197], v[12:15]
	v_mfma_f32_16x16x32_bf16 v[4:7], v[210:213], v[202:205], v[4:7]
	v_mfma_f32_16x16x32_bf16 v[0:3], v[218:221], v[202:205], v[0:3]
	v_mfma_f32_16x16x32_bf16 v[52:55], v[214:217], v[182:185], v[52:55]
	v_mfma_f32_16x16x32_bf16 v[44:47], v[222:225], v[182:185], v[44:47]
	v_mfma_f32_16x16x32_bf16 v[36:39], v[214:217], v[190:193], v[36:39]
	v_mfma_f32_16x16x32_bf16 v[28:31], v[222:225], v[190:193], v[28:31]
	v_mfma_f32_16x16x32_bf16 v[20:23], v[214:217], v[198:201], v[20:23]
	v_mfma_f32_16x16x32_bf16 v[12:15], v[222:225], v[198:201], v[12:15]
	v_mfma_f32_16x16x32_bf16 v[4:7], v[214:217], v[206:209], v[4:7]
	v_mfma_f32_16x16x32_bf16 v[0:3], v[222:225], v[206:209], v[0:3]
	s_add_i32 s68, 0, 0x18000
	v_add_u32_e32 v148, s68, v153
	s_barrier
	ds_read_b128 v[128:131], v148
	ds_read_b128 v[132:135], v148 offset:1024
	ds_read_b128 v[154:157], v148 offset:2048
	ds_read_b128 v[170:173], v148 offset:3072
	ds_read_b128 v[178:181], v177 offset:32768
	ds_read_b128 v[182:185], v177 offset:33792
	ds_read_b128 v[186:189], v177 offset:34816
	ds_read_b128 v[190:193], v177 offset:35840
	ds_read_b128 v[194:197], v177 offset:36864
	ds_read_b128 v[198:201], v177 offset:37888
	ds_read_b128 v[202:205], v177 offset:38912
	ds_read_b128 v[206:209], v177 offset:39936
	s_waitcnt lgkmcnt(8)
	s_barrier
	s_waitcnt lgkmcnt(0)
	s_waitcnt lgkmcnt(0)
	v_mfma_f32_16x16x32_bf16 v[124:127], v[128:131], v[178:181], v[124:127]
	v_mfma_f32_16x16x32_bf16 v[120:123], v[154:157], v[178:181], v[120:123]
	v_mfma_f32_16x16x32_bf16 v[112:115], v[128:131], v[186:189], v[112:115]
	v_mfma_f32_16x16x32_bf16 v[104:107], v[154:157], v[186:189], v[104:107]
	v_mfma_f32_16x16x32_bf16 v[96:99], v[128:131], v[194:197], v[96:99]
	v_mfma_f32_16x16x32_bf16 v[88:91], v[154:157], v[194:197], v[88:91]
	v_mfma_f32_16x16x32_bf16 v[80:83], v[128:131], v[202:205], v[80:83]
	v_mfma_f32_16x16x32_bf16 v[72:75], v[154:157], v[202:205], v[72:75]
	v_mfma_f32_16x16x32_bf16 v[124:127], v[132:135], v[182:185], v[124:127]
	v_mfma_f32_16x16x32_bf16 v[120:123], v[170:173], v[182:185], v[120:123]
	v_mfma_f32_16x16x32_bf16 v[112:115], v[132:135], v[190:193], v[112:115]
	v_mfma_f32_16x16x32_bf16 v[104:107], v[170:173], v[190:193], v[104:107]
	v_mfma_f32_16x16x32_bf16 v[96:99], v[132:135], v[198:201], v[96:99]
	v_mfma_f32_16x16x32_bf16 v[88:91], v[170:173], v[198:201], v[88:91]
	v_mfma_f32_16x16x32_bf16 v[80:83], v[132:135], v[206:209], v[80:83]
	v_mfma_f32_16x16x32_bf16 v[72:75], v[170:173], v[206:209], v[72:75]
	s_barrier
	s_add_u32 s78, s78, 0x20000
	s_addc_u32 s79, s79, 0
	v_lshl_add_u64 v[210:211], s[78:79], 0, v[140:141]
	s_mov_b32 m0, s22
	s_nop 0
	global_load_lds_dwordx4 v[210:211], off
	v_lshl_add_u64 v[210:211], s[78:79], 0, v[138:139]
	s_mov_b32 m0, s23
	s_nop 0
	global_load_lds_dwordx4 v[210:211], off
	s_add_i32 s71, 0, 0x1c000
	s_add_i32 s68, s68, s19
	v_add_u32_e32 v148, s71, v153
	v_lshl_add_u64 v[146:147], v[146:147], 0, s[92:93]
	s_mov_b32 m0, s68
	ds_read_b128 v[210:213], v148
	ds_read_b128 v[214:217], v148 offset:1024
	ds_read_b128 v[218:221], v148 offset:2048
	ds_read_b128 v[222:225], v148 offset:3072
	global_load_lds_dwordx4 v[146:147], off
	v_lshl_add_u64 v[146:147], v[150:151], 0, s[92:93]
	s_add_i32 m0, s68, 0x2000
	s_nop 0
	global_load_lds_dwordx4 v[146:147], off
	s_barrier
	s_waitcnt lgkmcnt(0)
	s_waitcnt lgkmcnt(0)
	v_mfma_f32_16x16x32_bf16 v[116:119], v[210:213], v[178:181], v[116:119]
	v_mfma_f32_16x16x32_bf16 v[108:111], v[218:221], v[178:181], v[108:111]
	v_mfma_f32_16x16x32_bf16 v[100:103], v[210:213], v[186:189], v[100:103]
	v_mfma_f32_16x16x32_bf16 v[92:95], v[218:221], v[186:189], v[92:95]
	v_mfma_f32_16x16x32_bf16 v[84:87], v[210:213], v[194:197], v[84:87]
	v_mfma_f32_16x16x32_bf16 v[76:79], v[218:221], v[194:197], v[76:79]
	v_mfma_f32_16x16x32_bf16 v[68:71], v[210:213], v[202:205], v[68:71]
	v_mfma_f32_16x16x32_bf16 v[64:67], v[218:221], v[202:205], v[64:67]
	v_mfma_f32_16x16x32_bf16 v[116:119], v[214:217], v[182:185], v[116:119]
	v_mfma_f32_16x16x32_bf16 v[108:111], v[222:225], v[182:185], v[108:111]
	v_mfma_f32_16x16x32_bf16 v[100:103], v[214:217], v[190:193], v[100:103]
	v_mfma_f32_16x16x32_bf16 v[92:95], v[222:225], v[190:193], v[92:95]
	v_mfma_f32_16x16x32_bf16 v[84:87], v[214:217], v[198:201], v[84:87]
	v_mfma_f32_16x16x32_bf16 v[76:79], v[222:225], v[198:201], v[76:79]
	v_mfma_f32_16x16x32_bf16 v[68:71], v[214:217], v[206:209], v[68:71]
	v_mfma_f32_16x16x32_bf16 v[64:67], v[222:225], v[206:209], v[64:67]
	s_mov_b32 m0, s24
	v_lshl_add_u64 v[146:147], v[174:175], 0, s[92:93]
	s_barrier
	ds_read_b128 v[178:181], v177 offset:49152
	ds_read_b128 v[182:185], v177 offset:50176
	ds_read_b128 v[186:189], v177 offset:51200
	ds_read_b128 v[190:193], v177 offset:52224
	ds_read_b128 v[194:197], v177 offset:53248
	ds_read_b128 v[198:201], v177 offset:54272
	ds_read_b128 v[202:205], v177 offset:55296
	ds_read_b128 v[206:209], v177 offset:56320
	global_load_lds_dwordx4 v[146:147], off
	v_lshl_add_u64 v[146:147], v[226:227], 0, s[92:93]
	s_mov_b32 m0, s25
	s_nop 0
	global_load_lds_dwordx4 v[146:147], off
	s_barrier
	s_waitcnt lgkmcnt(0)
	s_waitcnt lgkmcnt(0)
	v_mfma_f32_16x16x32_bf16 v[60:63], v[128:131], v[178:181], v[60:63]
	v_mfma_f32_16x16x32_bf16 v[56:59], v[154:157], v[178:181], v[56:59]
	v_mfma_f32_16x16x32_bf16 v[48:51], v[128:131], v[186:189], v[48:51]
	v_mfma_f32_16x16x32_bf16 v[40:43], v[154:157], v[186:189], v[40:43]
	v_mfma_f32_16x16x32_bf16 v[32:35], v[128:131], v[194:197], v[32:35]
	v_mfma_f32_16x16x32_bf16 v[24:27], v[154:157], v[194:197], v[24:27]
	v_mfma_f32_16x16x32_bf16 v[16:19], v[128:131], v[202:205], v[16:19]
	v_mfma_f32_16x16x32_bf16 v[8:11], v[154:157], v[202:205], v[8:11]
	v_mfma_f32_16x16x32_bf16 v[60:63], v[132:135], v[182:185], v[60:63]
	v_mfma_f32_16x16x32_bf16 v[56:59], v[170:173], v[182:185], v[56:59]
	v_mfma_f32_16x16x32_bf16 v[48:51], v[132:135], v[190:193], v[48:51]
	v_mfma_f32_16x16x32_bf16 v[40:43], v[170:173], v[190:193], v[40:43]
	v_mfma_f32_16x16x32_bf16 v[32:35], v[132:135], v[198:201], v[32:35]
	v_mfma_f32_16x16x32_bf16 v[24:27], v[170:173], v[198:201], v[24:27]
	v_mfma_f32_16x16x32_bf16 v[16:19], v[132:135], v[206:209], v[16:19]
	v_mfma_f32_16x16x32_bf16 v[8:11], v[170:173], v[206:209], v[8:11]
	s_barrier
	s_add_u32 s0, s0, 0x20080
	s_addc_u32 s1, s1, 0
	s_add_i32 s68, s71, s19
	v_lshl_add_u64 v[128:129], s[0:1], 0, v[160:161]
	s_mov_b32 m0, s68
	s_nop 0
	global_load_lds_dwordx4 v[128:129], off
	v_lshl_add_u64 v[128:129], s[0:1], 0, v[136:137]
	s_add_i32 m0, s68, 0x2000
	s_nop 0
	global_load_lds_dwordx4 v[128:129], off
	s_waitcnt vmcnt(6)
	s_barrier
	v_mfma_f32_16x16x32_bf16 v[52:55], v[210:213], v[178:181], v[52:55]
	v_mfma_f32_16x16x32_bf16 v[44:47], v[218:221], v[178:181], v[44:47]
	v_mfma_f32_16x16x32_bf16 v[36:39], v[210:213], v[186:189], v[36:39]
	v_mfma_f32_16x16x32_bf16 v[28:31], v[218:221], v[186:189], v[28:31]
	v_mfma_f32_16x16x32_bf16 v[20:23], v[210:213], v[194:197], v[20:23]
	v_mfma_f32_16x16x32_bf16 v[12:15], v[218:221], v[194:197], v[12:15]
	v_mfma_f32_16x16x32_bf16 v[4:7], v[210:213], v[202:205], v[4:7]
	v_mfma_f32_16x16x32_bf16 v[0:3], v[218:221], v[202:205], v[0:3]
	v_mfma_f32_16x16x32_bf16 v[52:55], v[214:217], v[182:185], v[52:55]
	v_mfma_f32_16x16x32_bf16 v[44:47], v[222:225], v[182:185], v[44:47]
	v_mfma_f32_16x16x32_bf16 v[36:39], v[214:217], v[190:193], v[36:39]
	v_mfma_f32_16x16x32_bf16 v[28:31], v[222:225], v[190:193], v[28:31]
	v_mfma_f32_16x16x32_bf16 v[20:23], v[214:217], v[198:201], v[20:23]
	v_mfma_f32_16x16x32_bf16 v[12:15], v[222:225], v[198:201], v[12:15]
	v_mfma_f32_16x16x32_bf16 v[4:7], v[214:217], v[206:209], v[4:7]
	v_mfma_f32_16x16x32_bf16 v[0:3], v[222:225], v[206:209], v[0:3]
	s_add_i32 s67, s67, 2
	s_add_u32 s76, s76, 0x100
	s_addc_u32 s77, s77, 0
	s_add_u32 s47, s47, 0x100
	s_addc_u32 s66, s66, 0
	s_cmp_gt_u32 s67, 5
	s_cbranch_scc0 .LBB0_493
	s_barrier
	v_lshl_add_u32 v174, s45, 8, v149
	v_ashrrev_i32_e32 v175, 31, v174
	v_lshlrev_b64 v[128:129], 6, v[174:175]
	v_lshl_add_u64 v[132:133], s[6:7], 0, v[128:129]
	global_load_dwordx4 v[128:131], v[132:133], off
	s_nop 0
	global_load_dwordx4 v[132:135], v[132:133], off offset:16
	v_or_b32_e32 v156, 16, v174
	v_ashrrev_i32_e32 v157, 31, v156
	v_lshlrev_b64 v[146:147], 6, v[156:157]
	v_lshl_add_u64 v[146:147], s[6:7], 0, v[146:147]
	global_load_dwordx4 v[178:181], v[146:147], off
	global_load_dwordx4 v[182:185], v[146:147], off offset:16
	v_or_b32_e32 v150, 32, v174
	v_ashrrev_i32_e32 v151, 31, v150
	v_lshlrev_b64 v[146:147], 6, v[150:151]
	v_lshl_add_u64 v[146:147], s[6:7], 0, v[146:147]
	global_load_dwordx4 v[186:189], v[146:147], off
	global_load_dwordx4 v[190:193], v[146:147], off offset:16
	v_or_b32_e32 v146, 48, v174
	v_ashrrev_i32_e32 v147, 31, v146
	v_lshlrev_b64 v[154:155], 6, v[146:147]
	v_lshl_add_u64 v[154:155], s[6:7], 0, v[154:155]
	global_load_dwordx4 v[194:197], v[154:155], off
	global_load_dwordx4 v[198:201], v[154:155], off offset:16
	v_add_u32_e32 v172, 0xa0, v174
	v_ashrrev_i32_e32 v173, 31, v172
	v_lshl_or_b32 v170, s27, 8, v159
	s_and_b64 vcc, exec, s[4:5]
	s_mov_b32 s27, s70
	s_mov_b32 s45, s46
	s_mov_b64 s[0:1], s[74:75]
	s_mov_b64 s[76:77], s[72:73]
	s_waitcnt vmcnt(0)
	v_mov_b32_e32 v154, v128
	v_mov_b32_e32 v155, v132
	v_mov_b32_e32 v132, v129
	v_pk_add_f32 v[128:129], v[154:155], v[132:133]
	v_mov_b32_e32 v132, v130
	v_mov_b32_e32 v133, v134
	v_mov_b32_e32 v134, v131
	v_pk_add_f32 v[130:131], v[132:133], v[134:135]
	v_add_u32_e32 v154, 0xb0, v174
	v_pk_add_f32 v[128:129], v[128:129], v[130:131]
	v_mov_b32_e32 v130, v180
	v_add_f32_e32 v128, v128, v129
	v_fmamk_f32 v128, v128, 0x3b000000, v246
	v_rsq_f32_e32 v176, v128
	v_mov_b32_e32 v128, v178
	v_mov_b32_e32 v129, v182
	v_mov_b32_e32 v182, v179
	v_mov_b32_e32 v131, v184
	v_mov_b32_e32 v184, v181
	v_pk_add_f32 v[128:129], v[128:129], v[182:183]
	v_pk_add_f32 v[130:131], v[130:131], v[184:185]
	v_add_u32_e32 v180, 0x80, v174
	v_pk_add_f32 v[128:129], v[128:129], v[130:131]
	v_mov_b32_e32 v130, v188
	v_add_f32_e32 v128, v128, v129
	v_fmamk_f32 v128, v128, 0x3b000000, v246
	v_rsq_f32_e32 v158, v128
	v_mov_b32_e32 v128, v186
	v_mov_b32_e32 v129, v190
	v_mov_b32_e32 v190, v187
	v_mov_b32_e32 v131, v192
	v_mov_b32_e32 v192, v189
	v_pk_add_f32 v[128:129], v[128:129], v[190:191]
	v_pk_add_f32 v[130:131], v[130:131], v[192:193]
	v_ashrrev_i32_e32 v181, 31, v180
	v_pk_add_f32 v[128:129], v[128:129], v[130:131]
	v_mov_b32_e32 v130, v196
	v_add_f32_e32 v128, v128, v129
	v_fmamk_f32 v128, v128, 0x3b000000, v246
	v_rsq_f32_e32 v152, v128
	v_mov_b32_e32 v128, v194
	v_mov_b32_e32 v129, v198
	v_mov_b32_e32 v198, v195
	v_mov_b32_e32 v131, v200
	v_mov_b32_e32 v200, v197
	v_pk_add_f32 v[128:129], v[128:129], v[198:199]
	v_pk_add_f32 v[130:131], v[130:131], v[200:201]
	v_add_u32_e32 v178, 0x90, v174
	v_pk_add_f32 v[128:129], v[128:129], v[130:131]
	v_ashrrev_i32_e32 v179, 31, v178
	v_add_f32_e32 v128, v128, v129
	v_fmamk_f32 v128, v128, 0x3b000000, v246
	v_rsq_f32_e32 v148, v128
	v_lshlrev_b64 v[128:129], 6, v[180:181]
	v_lshl_add_u64 v[128:129], s[6:7], 0, v[128:129]
	global_load_dwordx4 v[182:185], v[128:129], off
	global_load_dwordx4 v[186:189], v[128:129], off offset:16
	v_lshlrev_b64 v[128:129], 6, v[178:179]
	v_lshl_add_u64 v[128:129], s[6:7], 0, v[128:129]
	global_load_dwordx4 v[190:193], v[128:129], off
	global_load_dwordx4 v[194:197], v[128:129], off offset:16
	v_lshlrev_b64 v[128:129], 6, v[172:173]
	v_lshl_add_u64 v[128:129], s[6:7], 0, v[128:129]
	global_load_dwordx4 v[198:201], v[128:129], off
	global_load_dwordx4 v[202:205], v[128:129], off offset:16
	v_ashrrev_i32_e32 v155, 31, v154
	v_lshlrev_b64 v[128:129], 6, v[154:155]
	v_lshl_add_u64 v[128:129], s[6:7], 0, v[128:129]
	global_load_dwordx4 v[132:135], v[128:129], off
	s_nop 0
	global_load_dwordx4 v[128:131], v[128:129], off offset:16
	v_pk_mul_f32 v[126:127], v[126:127], v[176:177] op_sel_hi:[1,0]
	v_pk_mul_f32 v[124:125], v[124:125], v[176:177] op_sel_hi:[1,0]
	v_pk_mul_f32 v[120:121], v[120:121], v[176:177] op_sel_hi:[1,0]
	v_pk_mul_f32 v[118:119], v[118:119], v[176:177] op_sel_hi:[1,0]
	v_pk_mul_f32 v[116:117], v[116:117], v[176:177] op_sel_hi:[1,0]
	v_pk_mul_f32 v[112:113], v[112:113], v[158:159] op_sel_hi:[1,0]
	v_pk_mul_f32 v[102:103], v[102:103], v[158:159] op_sel_hi:[1,0]
	v_pk_mul_f32 v[100:101], v[100:101], v[158:159] op_sel_hi:[1,0]
	v_pk_mul_f32 v[96:97], v[96:97], v[152:153] op_sel_hi:[1,0]
	v_pk_mul_f32 v[86:87], v[86:87], v[152:153] op_sel_hi:[1,0]
	v_pk_mul_f32 v[84:85], v[84:85], v[152:153] op_sel_hi:[1,0]
	v_pk_mul_f32 v[80:81], v[80:81], v[148:149] op_sel_hi:[1,0]
	v_pk_mul_f32 v[70:71], v[70:71], v[148:149] op_sel_hi:[1,0]
	v_pk_mul_f32 v[68:69], v[68:69], v[148:149] op_sel_hi:[1,0]
	s_waitcnt vmcnt(0)
	v_mov_b32_e32 v206, v182
	v_mov_b32_e32 v207, v186
	v_mov_b32_e32 v186, v183
	v_pk_add_f32 v[182:183], v[206:207], v[186:187]
	v_mov_b32_e32 v186, v184
	v_mov_b32_e32 v187, v188
	v_mov_b32_e32 v188, v185
	v_pk_add_f32 v[184:185], v[186:187], v[188:189]
	v_mov_b32_e32 v188, v200
	v_pk_add_f32 v[182:183], v[182:183], v[184:185]
	v_mov_b32_e32 v184, v192
	v_add_f32_e32 v171, v182, v183
	v_mov_b32_e32 v182, v190
	v_mov_b32_e32 v183, v194
	v_mov_b32_e32 v194, v191
	v_mov_b32_e32 v185, v196
	v_mov_b32_e32 v196, v193
	v_pk_add_f32 v[182:183], v[182:183], v[194:195]
	v_pk_add_f32 v[184:185], v[184:185], v[196:197]
	v_fmamk_f32 v171, v171, 0x3b000000, v246
	v_pk_add_f32 v[182:183], v[182:183], v[184:185]
	v_rsq_f32_e32 v186, v171
	v_add_f32_e32 v171, v182, v183
	v_mov_b32_e32 v182, v198
	v_mov_b32_e32 v183, v202
	v_mov_b32_e32 v202, v199
	v_mov_b32_e32 v189, v204
	v_mov_b32_e32 v204, v201
	v_pk_add_f32 v[182:183], v[182:183], v[202:203]
	v_pk_add_f32 v[188:189], v[188:189], v[204:205]
	v_fmamk_f32 v171, v171, 0x3b000000, v246
	v_pk_add_f32 v[182:183], v[182:183], v[188:189]
	v_rsq_f32_e32 v184, v171
	v_add_f32_e32 v171, v182, v183
	v_mov_b32_e32 v188, v132
	v_mov_b32_e32 v189, v128
	v_mov_b32_e32 v128, v133
	v_mov_b32_e32 v132, v134
	v_mov_b32_e32 v133, v130
	v_mov_b32_e32 v130, v135
	v_fmamk_f32 v171, v171, 0x3b000000, v246
	v_pk_add_f32 v[128:129], v[188:189], v[128:129]
	v_pk_add_f32 v[130:131], v[132:133], v[130:131]
	v_rsq_f32_e32 v182, v171
	v_pk_add_f32 v[128:129], v[128:129], v[130:131]
	v_ashrrev_i32_e32 v171, 31, v170
	v_lshlrev_b64 v[130:131], 12, v[174:175]
	v_pk_mul_f32 v[132:133], v[122:123], v[176:177] op_sel_hi:[1,0]
	v_cvt_pk_bf16_f32 v122, v124, v125
	v_cvt_pk_bf16_f32 v123, v126, v127
	v_cvt_pk_bf16_f32 v124, v120, v121
	v_lshl_add_u64 v[126:127], s[50:51], 0, v[130:131]
	v_lshlrev_b64 v[120:121], 1, v[170:171]
	v_lshl_add_u64 v[126:127], v[126:127], 0, v[120:121]
	v_cvt_pk_bf16_f32 v125, v132, v133
	global_store_dwordx4 v[126:127], v[122:125], off
	v_pk_mul_f32 v[60:61], v[60:61], v[186:187] op_sel_hi:[1,0]
	v_pk_mul_f32 v[62:63], v[62:63], v[186:187] op_sel_hi:[1,0]
	v_pk_mul_f32 v[122:123], v[110:111], v[176:177] op_sel_hi:[1,0]
	v_pk_mul_f32 v[110:111], v[108:109], v[176:177] op_sel_hi:[1,0]
	v_cvt_pk_bf16_f32 v108, v116, v117
	v_cvt_pk_bf16_f32 v109, v118, v119
	v_pk_mul_f32 v[54:55], v[54:55], v[186:187] op_sel_hi:[1,0]
	v_cvt_pk_bf16_f32 v110, v110, v111
	v_cvt_pk_bf16_f32 v111, v122, v123
	global_store_dwordx4 v[126:127], v[108:111], off offset:256
	v_pk_mul_f32 v[52:53], v[52:53], v[186:187] op_sel_hi:[1,0]
	v_pk_mul_f32 v[48:49], v[48:49], v[184:185] op_sel_hi:[1,0]
	v_lshlrev_b64 v[108:109], 12, v[156:157]
	v_lshl_add_u64 v[108:109], s[50:51], 0, v[108:109]
	v_pk_mul_f32 v[110:111], v[114:115], v[158:159] op_sel_hi:[1,0]
	v_pk_mul_f32 v[114:115], v[106:107], v[158:159] op_sel_hi:[1,0]
	v_pk_mul_f32 v[106:107], v[104:105], v[158:159] op_sel_hi:[1,0]
	v_cvt_pk_bf16_f32 v104, v112, v113
	v_cvt_pk_bf16_f32 v105, v110, v111
	v_lshl_add_u64 v[108:109], v[108:109], 0, v[120:121]
	v_cvt_pk_bf16_f32 v106, v106, v107
	v_cvt_pk_bf16_f32 v107, v114, v115
	global_store_dwordx4 v[108:109], v[104:107], off
	v_pk_mul_f32 v[38:39], v[38:39], v[184:185] op_sel_hi:[1,0]
	v_pk_mul_f32 v[36:37], v[36:37], v[184:185] op_sel_hi:[1,0]
	v_pk_mul_f32 v[104:105], v[94:95], v[158:159] op_sel_hi:[1,0]
	v_pk_mul_f32 v[94:95], v[92:93], v[158:159] op_sel_hi:[1,0]
	v_cvt_pk_bf16_f32 v92, v100, v101
	v_cvt_pk_bf16_f32 v93, v102, v103
	v_add_f32_e32 v128, v128, v129
	v_cvt_pk_bf16_f32 v94, v94, v95
	v_cvt_pk_bf16_f32 v95, v104, v105
	global_store_dwordx4 v[108:109], v[92:95], off offset:256
	v_fmamk_f32 v128, v128, 0x3b000000, v246
	v_rsq_f32_e32 v128, v128
	v_lshlrev_b64 v[92:93], 12, v[150:151]
	v_lshl_add_u64 v[92:93], s[50:51], 0, v[92:93]
	v_pk_mul_f32 v[94:95], v[98:99], v[152:153] op_sel_hi:[1,0]
	v_pk_mul_f32 v[98:99], v[90:91], v[152:153] op_sel_hi:[1,0]
	v_pk_mul_f32 v[90:91], v[88:89], v[152:153] op_sel_hi:[1,0]
	v_cvt_pk_bf16_f32 v88, v96, v97
	v_cvt_pk_bf16_f32 v89, v94, v95
	v_lshl_add_u64 v[92:93], v[92:93], 0, v[120:121]
	v_cvt_pk_bf16_f32 v90, v90, v91
	v_cvt_pk_bf16_f32 v91, v98, v99
	global_store_dwordx4 v[92:93], v[88:91], off
	v_pk_mul_f32 v[32:33], v[32:33], v[182:183] op_sel_hi:[1,0]
	v_pk_mul_f32 v[22:23], v[22:23], v[182:183] op_sel_hi:[1,0]
	v_pk_mul_f32 v[88:89], v[78:79], v[152:153] op_sel_hi:[1,0]
	v_pk_mul_f32 v[78:79], v[76:77], v[152:153] op_sel_hi:[1,0]
	v_cvt_pk_bf16_f32 v76, v84, v85
	v_cvt_pk_bf16_f32 v77, v86, v87
	v_pk_mul_f32 v[20:21], v[20:21], v[182:183] op_sel_hi:[1,0]
	v_cvt_pk_bf16_f32 v78, v78, v79
	v_cvt_pk_bf16_f32 v79, v88, v89
	global_store_dwordx4 v[92:93], v[76:79], off offset:256
	v_pk_mul_f32 v[16:17], v[16:17], v[128:129] op_sel_hi:[1,0]
	v_pk_mul_f32 v[6:7], v[6:7], v[128:129] op_sel_hi:[1,0]
	v_lshlrev_b64 v[76:77], 12, v[146:147]
	v_lshl_add_u64 v[76:77], s[50:51], 0, v[76:77]
	v_pk_mul_f32 v[78:79], v[82:83], v[148:149] op_sel_hi:[1,0]
	v_pk_mul_f32 v[82:83], v[74:75], v[148:149] op_sel_hi:[1,0]
	v_pk_mul_f32 v[74:75], v[72:73], v[148:149] op_sel_hi:[1,0]
	v_cvt_pk_bf16_f32 v72, v80, v81
	v_cvt_pk_bf16_f32 v73, v78, v79
	v_lshl_add_u64 v[76:77], v[76:77], 0, v[120:121]
	v_cvt_pk_bf16_f32 v74, v74, v75
	v_cvt_pk_bf16_f32 v75, v82, v83
	global_store_dwordx4 v[76:77], v[72:75], off
	v_pk_mul_f32 v[4:5], v[4:5], v[128:129] op_sel_hi:[1,0]
	s_nop 0
	v_pk_mul_f32 v[72:73], v[66:67], v[148:149] op_sel_hi:[1,0]
	v_pk_mul_f32 v[66:67], v[64:65], v[148:149] op_sel_hi:[1,0]
	v_cvt_pk_bf16_f32 v64, v68, v69
	v_cvt_pk_bf16_f32 v65, v70, v71
	s_nop 0
	v_cvt_pk_bf16_f32 v66, v66, v67
	v_cvt_pk_bf16_f32 v67, v72, v73
	global_store_dwordx4 v[76:77], v[64:67], off offset:256
	s_nop 1
	v_lshlrev_b64 v[64:65], 12, v[180:181]
	v_pk_mul_f32 v[66:67], v[58:59], v[186:187] op_sel_hi:[1,0]
	v_pk_mul_f32 v[58:59], v[56:57], v[186:187] op_sel_hi:[1,0]
	v_cvt_pk_bf16_f32 v56, v60, v61
	v_lshl_add_u64 v[60:61], s[50:51], 0, v[64:65]
	v_cvt_pk_bf16_f32 v57, v62, v63
	v_lshl_add_u64 v[60:61], v[60:61], 0, v[120:121]
	v_cvt_pk_bf16_f32 v58, v58, v59
	v_cvt_pk_bf16_f32 v59, v66, v67
	global_store_dwordx4 v[60:61], v[56:59], off
	s_nop 1
	v_pk_mul_f32 v[56:57], v[46:47], v[186:187] op_sel_hi:[1,0]
	v_pk_mul_f32 v[46:47], v[44:45], v[186:187] op_sel_hi:[1,0]
	v_cvt_pk_bf16_f32 v44, v52, v53
	v_cvt_pk_bf16_f32 v45, v54, v55
	s_nop 0
	v_cvt_pk_bf16_f32 v46, v46, v47
	v_cvt_pk_bf16_f32 v47, v56, v57
	global_store_dwordx4 v[60:61], v[44:47], off offset:256
	s_nop 1
	v_lshlrev_b64 v[44:45], 12, v[178:179]
	v_lshl_add_u64 v[44:45], s[50:51], 0, v[44:45]
	v_pk_mul_f32 v[46:47], v[50:51], v[184:185] op_sel_hi:[1,0]
	v_pk_mul_f32 v[50:51], v[42:43], v[184:185] op_sel_hi:[1,0]
	v_pk_mul_f32 v[42:43], v[40:41], v[184:185] op_sel_hi:[1,0]
	v_cvt_pk_bf16_f32 v40, v48, v49
	v_cvt_pk_bf16_f32 v41, v46, v47
	v_lshl_add_u64 v[44:45], v[44:45], 0, v[120:121]
	v_cvt_pk_bf16_f32 v42, v42, v43
	v_cvt_pk_bf16_f32 v43, v50, v51
	global_store_dwordx4 v[44:45], v[40:43], off
	s_nop 1
	v_pk_mul_f32 v[40:41], v[30:31], v[184:185] op_sel_hi:[1,0]
	v_pk_mul_f32 v[30:31], v[28:29], v[184:185] op_sel_hi:[1,0]
	v_cvt_pk_bf16_f32 v28, v36, v37
	v_cvt_pk_bf16_f32 v29, v38, v39
	s_nop 0
	v_cvt_pk_bf16_f32 v30, v30, v31
	v_cvt_pk_bf16_f32 v31, v40, v41
	global_store_dwordx4 v[44:45], v[28:31], off offset:256
	s_nop 1
	v_lshlrev_b64 v[28:29], 12, v[172:173]
	v_lshl_add_u64 v[28:29], s[50:51], 0, v[28:29]
	v_pk_mul_f32 v[30:31], v[34:35], v[182:183] op_sel_hi:[1,0]
	v_pk_mul_f32 v[34:35], v[26:27], v[182:183] op_sel_hi:[1,0]
	v_pk_mul_f32 v[26:27], v[24:25], v[182:183] op_sel_hi:[1,0]
	v_cvt_pk_bf16_f32 v24, v32, v33
	v_cvt_pk_bf16_f32 v25, v30, v31
	v_lshl_add_u64 v[28:29], v[28:29], 0, v[120:121]
	v_cvt_pk_bf16_f32 v26, v26, v27
	v_cvt_pk_bf16_f32 v27, v34, v35
	global_store_dwordx4 v[28:29], v[24:27], off
	s_nop 1
	v_pk_mul_f32 v[24:25], v[14:15], v[182:183] op_sel_hi:[1,0]
	v_pk_mul_f32 v[14:15], v[12:13], v[182:183] op_sel_hi:[1,0]
	v_cvt_pk_bf16_f32 v12, v20, v21
	v_cvt_pk_bf16_f32 v13, v22, v23
	s_nop 0
	v_cvt_pk_bf16_f32 v14, v14, v15
	v_cvt_pk_bf16_f32 v15, v24, v25
	global_store_dwordx4 v[28:29], v[12:15], off offset:256
	s_nop 1
	v_lshlrev_b64 v[12:13], 12, v[154:155]
	v_lshl_add_u64 v[12:13], s[50:51], 0, v[12:13]
	v_pk_mul_f32 v[14:15], v[18:19], v[128:129] op_sel_hi:[1,0]
	v_pk_mul_f32 v[18:19], v[10:11], v[128:129] op_sel_hi:[1,0]
	v_pk_mul_f32 v[10:11], v[8:9], v[128:129] op_sel_hi:[1,0]
	v_cvt_pk_bf16_f32 v8, v16, v17
	v_cvt_pk_bf16_f32 v9, v14, v15
	v_lshl_add_u64 v[12:13], v[12:13], 0, v[120:121]
	v_cvt_pk_bf16_f32 v10, v10, v11
	v_cvt_pk_bf16_f32 v11, v18, v19
	global_store_dwordx4 v[12:13], v[8:11], off
	s_nop 1
	v_pk_mul_f32 v[8:9], v[2:3], v[128:129] op_sel_hi:[1,0]
	v_pk_mul_f32 v[2:3], v[0:1], v[128:129] op_sel_hi:[1,0]
	v_cvt_pk_bf16_f32 v0, v4, v5
	v_cvt_pk_bf16_f32 v1, v6, v7
	s_nop 0
	v_cvt_pk_bf16_f32 v2, v2, v3
	v_cvt_pk_bf16_f32 v3, v8, v9
	global_store_dwordx4 v[12:13], v[0:3], off offset:256
	s_cbranch_vccz .LBB0_486
	s_waitcnt vmcnt(0)
	s_cmpk_gt_u32 s16, 0xff
	s_cbranch_scc1 .LBB0_497
	s_barrier

.LBB0_859:
	s_barrier
	s_add_u32 s0, s8, 0xfff80080
	s_addc_u32 s1, s9, -1
	s_add_i32 s51, 0, 0x10000
	v_add_u32_e32 v60, s51, v249
	ds_read_b128 v[48:51], v60
	ds_read_b128 v[52:55], v60 offset:1024
	ds_read_b128 v[56:59], v60 offset:2048
	ds_read_b128 v[60:63], v60 offset:3072
	s_cmp_eq_u32 s50, 28
	s_cselect_b32 s81, s12, s1
	s_cselect_b32 s80, s13, s0
	s_cselect_b32 s1, s14, s49
	s_cselect_b32 s0, s15, s48
	ds_read_b128 v[64:67], v251
	ds_read_b128 v[68:71], v251 offset:1024
	ds_read_b128 v[72:75], v251 offset:2048
	ds_read_b128 v[76:79], v251 offset:3072
	ds_read_b128 v[176:179], v251 offset:4096
	ds_read_b128 v[180:183], v251 offset:5120
	ds_read_b128 v[184:187], v251 offset:6144
	ds_read_b128 v[188:191], v251 offset:7168
	s_waitcnt lgkmcnt(8)
	s_barrier
	s_waitcnt lgkmcnt(0)
	s_waitcnt lgkmcnt(0)
	v_mfma_f32_16x16x32_bf16 v[156:159], v[48:51], v[64:67], v[156:159]
	v_mfma_f32_16x16x32_bf16 v[152:155], v[56:59], v[64:67], v[152:155]
	v_mfma_f32_16x16x32_bf16 v[140:143], v[48:51], v[72:75], v[140:143]
	v_mfma_f32_16x16x32_bf16 v[136:139], v[56:59], v[72:75], v[136:139]
	v_mfma_f32_16x16x32_bf16 v[124:127], v[48:51], v[176:179], v[124:127]
	v_mfma_f32_16x16x32_bf16 v[120:123], v[56:59], v[176:179], v[120:123]
	v_mfma_f32_16x16x32_bf16 v[108:111], v[48:51], v[184:187], v[108:111]
	v_mfma_f32_16x16x32_bf16 v[104:107], v[56:59], v[184:187], v[104:107]
	v_mfma_f32_16x16x32_bf16 v[156:159], v[52:55], v[68:71], v[156:159]
	v_mfma_f32_16x16x32_bf16 v[152:155], v[60:63], v[68:71], v[152:155]
	v_mfma_f32_16x16x32_bf16 v[140:143], v[52:55], v[76:79], v[140:143]
	v_mfma_f32_16x16x32_bf16 v[136:139], v[60:63], v[76:79], v[136:139]
	v_mfma_f32_16x16x32_bf16 v[124:127], v[52:55], v[180:183], v[124:127]
	v_mfma_f32_16x16x32_bf16 v[120:123], v[60:63], v[180:183], v[120:123]
	v_mfma_f32_16x16x32_bf16 v[108:111], v[52:55], v[188:191], v[108:111]
	v_mfma_f32_16x16x32_bf16 v[104:107], v[60:63], v[188:191], v[104:107]
	s_barrier
	v_lshl_add_u64 v[192:193], s[8:9], 0, v[172:173]
	s_add_i32 m0, s20, 0xc000
	s_nop 0
	global_load_lds_dwordx4 v[192:193], off
	v_lshl_add_u64 v[192:193], s[8:9], 0, v[174:175]
	s_add_i32 m0, s20, 0xe000
	s_nop 0
	global_load_lds_dwordx4 v[192:193], off
	s_add_i32 s68, 0, 0x14000
	s_add_i32 s51, s51, s19
	v_add_u32_e32 v204, s68, v249
	v_lshl_add_u64 v[216:217], s[0:1], 0, v[160:161]
	s_mov_b32 m0, s51
	ds_read_b128 v[192:195], v204
	ds_read_b128 v[196:199], v204 offset:1024
	ds_read_b128 v[200:203], v204 offset:2048
	ds_read_b128 v[204:207], v204 offset:3072
	global_load_lds_dwordx4 v[216:217], off
	v_lshl_add_u64 v[218:219], s[0:1], 0, v[170:171]
	s_add_i32 m0, s51, 0x2000
	s_nop 0
	global_load_lds_dwordx4 v[218:219], off
	s_barrier
	s_waitcnt lgkmcnt(0)
	s_waitcnt lgkmcnt(0)
	v_mfma_f32_16x16x32_bf16 v[148:151], v[192:195], v[64:67], v[148:151]
	v_mfma_f32_16x16x32_bf16 v[64:67], v[200:203], v[64:67], v[144:147]
	v_mfma_f32_16x16x32_bf16 v[148:151], v[196:199], v[68:71], v[148:151]
	v_mfma_f32_16x16x32_bf16 v[64:67], v[204:207], v[68:71], v[64:67]
	v_mfma_f32_16x16x32_bf16 v[68:71], v[192:195], v[72:75], v[132:135]
	v_mfma_f32_16x16x32_bf16 v[72:75], v[200:203], v[72:75], v[128:131]
	v_mfma_f32_16x16x32_bf16 v[112:115], v[200:203], v[176:179], v[112:115]
	v_mfma_f32_16x16x32_bf16 v[100:103], v[192:195], v[184:187], v[100:103]
	v_mfma_f32_16x16x32_bf16 v[96:99], v[200:203], v[184:187], v[96:99]
	v_mfma_f32_16x16x32_bf16 v[68:71], v[196:199], v[76:79], v[68:71]
	v_mfma_f32_16x16x32_bf16 v[72:75], v[204:207], v[76:79], v[72:75]
	v_mfma_f32_16x16x32_bf16 v[76:79], v[192:195], v[176:179], v[116:119]
	v_mfma_f32_16x16x32_bf16 v[112:115], v[204:207], v[180:183], v[112:115]
	v_mfma_f32_16x16x32_bf16 v[100:103], v[196:199], v[188:191], v[100:103]
	v_mfma_f32_16x16x32_bf16 v[96:99], v[204:207], v[188:191], v[96:99]
	v_mfma_f32_16x16x32_bf16 v[76:79], v[196:199], v[180:183], v[76:79]
	s_mov_b32 m0, s20
	v_lshl_add_u64 v[220:221], s[80:81], 0, v[160:161]
	s_barrier
	ds_read_b128 v[116:119], v251 offset:16384
	ds_read_b128 v[128:131], v251 offset:17408
	ds_read_b128 v[132:135], v251 offset:18432
	ds_read_b128 v[144:147], v251 offset:19456
	ds_read_b128 v[176:179], v251 offset:20480
	ds_read_b128 v[180:183], v251 offset:21504
	ds_read_b128 v[184:187], v251 offset:22528
	ds_read_b128 v[188:191], v251 offset:23552
	global_load_lds_dwordx4 v[220:221], off
	v_lshl_add_u64 v[222:223], s[80:81], 0, v[170:171]
	s_mov_b32 m0, s21
	s_nop 0
	global_load_lds_dwordx4 v[222:223], off
	s_barrier
	s_waitcnt lgkmcnt(0)
	s_waitcnt lgkmcnt(0)
	v_mfma_f32_16x16x32_bf16 v[92:95], v[48:51], v[116:119], v[92:95]
	v_mfma_f32_16x16x32_bf16 v[88:91], v[56:59], v[116:119], v[88:91]
	v_mfma_f32_16x16x32_bf16 v[44:47], v[48:51], v[132:135], v[44:47]
	v_mfma_f32_16x16x32_bf16 v[40:43], v[56:59], v[132:135], v[40:43]
	v_mfma_f32_16x16x32_bf16 v[28:31], v[48:51], v[176:179], v[28:31]
	v_mfma_f32_16x16x32_bf16 v[24:27], v[56:59], v[176:179], v[24:27]
	v_mfma_f32_16x16x32_bf16 v[12:15], v[48:51], v[184:187], v[12:15]
	v_mfma_f32_16x16x32_bf16 v[8:11], v[56:59], v[184:187], v[8:11]
	v_mfma_f32_16x16x32_bf16 v[92:95], v[52:55], v[128:131], v[92:95]
	v_mfma_f32_16x16x32_bf16 v[88:91], v[60:63], v[128:131], v[88:91]
	v_mfma_f32_16x16x32_bf16 v[44:47], v[52:55], v[144:147], v[44:47]
	v_mfma_f32_16x16x32_bf16 v[40:43], v[60:63], v[144:147], v[40:43]
	v_mfma_f32_16x16x32_bf16 v[28:31], v[52:55], v[180:183], v[28:31]
	v_mfma_f32_16x16x32_bf16 v[24:27], v[60:63], v[180:183], v[24:27]
	v_mfma_f32_16x16x32_bf16 v[12:15], v[52:55], v[188:191], v[12:15]
	v_mfma_f32_16x16x32_bf16 v[8:11], v[60:63], v[188:191], v[8:11]
	s_barrier
	s_add_u32 s66, s0, 0x80000
	s_addc_u32 s67, s1, 0
	s_add_i32 s51, s68, s19
	v_lshl_add_u64 v[48:49], s[66:67], 0, v[160:161]
	s_mov_b32 m0, s51
	s_nop 0
	global_load_lds_dwordx4 v[48:49], off
	v_lshl_add_u64 v[48:49], s[66:67], 0, v[170:171]
	s_add_i32 m0, s51, 0x2000
	s_nop 0
	global_load_lds_dwordx4 v[48:49], off
	s_waitcnt vmcnt(6)
	s_barrier
	v_mfma_f32_16x16x32_bf16 v[36:39], v[192:195], v[132:135], v[36:39]
	v_mfma_f32_16x16x32_bf16 v[32:35], v[200:203], v[132:135], v[32:35]
	v_mfma_f32_16x16x32_bf16 v[20:23], v[192:195], v[176:179], v[20:23]
	v_mfma_f32_16x16x32_bf16 v[16:19], v[200:203], v[176:179], v[16:19]
	v_mfma_f32_16x16x32_bf16 v[4:7], v[192:195], v[184:187], v[4:7]
	v_mfma_f32_16x16x32_bf16 v[0:3], v[200:203], v[184:187], v[0:3]
	v_mfma_f32_16x16x32_bf16 v[48:51], v[192:195], v[116:119], v[84:87]
	v_mfma_f32_16x16x32_bf16 v[52:55], v[200:203], v[116:119], v[80:83]
	v_mfma_f32_16x16x32_bf16 v[36:39], v[196:199], v[144:147], v[36:39]
	v_mfma_f32_16x16x32_bf16 v[32:35], v[204:207], v[144:147], v[32:35]
	v_mfma_f32_16x16x32_bf16 v[20:23], v[196:199], v[180:183], v[20:23]
	v_mfma_f32_16x16x32_bf16 v[16:19], v[204:207], v[180:183], v[16:19]
	v_mfma_f32_16x16x32_bf16 v[4:7], v[196:199], v[188:191], v[4:7]
	v_mfma_f32_16x16x32_bf16 v[0:3], v[204:207], v[188:191], v[0:3]
	v_mfma_f32_16x16x32_bf16 v[48:51], v[196:199], v[128:131], v[48:51]
	v_mfma_f32_16x16x32_bf16 v[52:55], v[204:207], v[128:131], v[52:55]
	s_add_i32 s51, 0, 0x18000
	v_add_u32_e32 v84, s51, v249
	s_barrier
	ds_read_b128 v[56:59], v84
	ds_read_b128 v[60:63], v84 offset:1024
	ds_read_b128 v[80:83], v84 offset:2048
	ds_read_b128 v[84:87], v84 offset:3072
	ds_read_b128 v[116:119], v251 offset:32768
	ds_read_b128 v[128:131], v251 offset:33792
	ds_read_b128 v[176:179], v251 offset:34816
	ds_read_b128 v[180:183], v251 offset:35840
	ds_read_b128 v[184:187], v251 offset:36864
	ds_read_b128 v[188:191], v251 offset:37888
	ds_read_b128 v[192:195], v251 offset:38912
	ds_read_b128 v[196:199], v251 offset:39936
	s_waitcnt lgkmcnt(8)
	s_barrier
	s_waitcnt lgkmcnt(0)
	s_waitcnt lgkmcnt(0)
	v_mfma_f32_16x16x32_bf16 v[132:135], v[56:59], v[116:119], v[156:159]
	v_mfma_f32_16x16x32_bf16 v[156:159], v[60:63], v[128:131], v[132:135]
	v_mfma_f32_16x16x32_bf16 v[132:135], v[80:83], v[116:119], v[152:155]
	v_mfma_f32_16x16x32_bf16 v[152:155], v[84:87], v[128:131], v[132:135]
	v_mfma_f32_16x16x32_bf16 v[132:135], v[56:59], v[176:179], v[140:143]
	v_mfma_f32_16x16x32_bf16 v[140:143], v[60:63], v[180:183], v[132:135]
	v_mfma_f32_16x16x32_bf16 v[132:135], v[80:83], v[176:179], v[136:139]
	v_mfma_f32_16x16x32_bf16 v[124:127], v[56:59], v[184:187], v[124:127]
	v_mfma_f32_16x16x32_bf16 v[120:123], v[80:83], v[184:187], v[120:123]
	v_mfma_f32_16x16x32_bf16 v[108:111], v[56:59], v[192:195], v[108:111]
	v_mfma_f32_16x16x32_bf16 v[104:107], v[80:83], v[192:195], v[104:107]
	v_mfma_f32_16x16x32_bf16 v[136:139], v[84:87], v[180:183], v[132:135]
	v_mfma_f32_16x16x32_bf16 v[124:127], v[60:63], v[188:191], v[124:127]
	v_mfma_f32_16x16x32_bf16 v[120:123], v[84:87], v[188:191], v[120:123]
	v_mfma_f32_16x16x32_bf16 v[108:111], v[60:63], v[196:199], v[108:111]
	v_mfma_f32_16x16x32_bf16 v[104:107], v[84:87], v[196:199], v[104:107]
	s_barrier
	s_add_u32 s66, s80, 0x80000
	s_addc_u32 s67, s81, 0
	v_lshl_add_u64 v[132:133], s[66:67], 0, v[160:161]
	s_mov_b32 m0, s22
	s_nop 0
	global_load_lds_dwordx4 v[132:133], off
	v_lshl_add_u64 v[132:133], s[66:67], 0, v[170:171]
	s_mov_b32 m0, s23
	s_nop 0
	global_load_lds_dwordx4 v[132:133], off
	s_add_i32 s66, 0, 0x1c000
	v_add_u32_e32 v132, s66, v249
	s_add_i32 s51, s51, s19
	ds_read_b128 v[200:203], v132
	ds_read_b128 v[204:207], v132 offset:1024
	ds_read_b128 v[208:211], v132 offset:2048
	ds_read_b128 v[212:215], v132 offset:3072
	v_lshl_add_u64 v[132:133], v[216:217], 0, s[92:93]
	s_mov_b32 m0, s51
	s_nop 0
	global_load_lds_dwordx4 v[132:133], off
	v_lshl_add_u64 v[132:133], v[218:219], 0, s[92:93]
	s_add_i32 m0, s51, 0x2000
	s_nop 0
	global_load_lds_dwordx4 v[132:133], off
	s_barrier
	s_waitcnt lgkmcnt(0)
	s_waitcnt lgkmcnt(0)
	v_mfma_f32_16x16x32_bf16 v[64:67], v[208:211], v[116:119], v[64:67]
	v_mfma_f32_16x16x32_bf16 v[132:135], v[200:203], v[116:119], v[148:151]
	v_mfma_f32_16x16x32_bf16 v[144:147], v[212:215], v[128:131], v[64:67]
	v_mfma_f32_16x16x32_bf16 v[64:67], v[200:203], v[176:179], v[68:71]
	v_mfma_f32_16x16x32_bf16 v[148:151], v[204:207], v[128:131], v[132:135]
	v_mfma_f32_16x16x32_bf16 v[132:135], v[204:207], v[180:183], v[64:67]
	v_mfma_f32_16x16x32_bf16 v[64:67], v[208:211], v[176:179], v[72:75]
	v_mfma_f32_16x16x32_bf16 v[128:131], v[212:215], v[180:183], v[64:67]
	v_mfma_f32_16x16x32_bf16 v[64:67], v[200:203], v[184:187], v[76:79]
	v_mfma_f32_16x16x32_bf16 v[116:119], v[204:207], v[188:191], v[64:67]
	v_mfma_f32_16x16x32_bf16 v[64:67], v[208:211], v[184:187], v[112:115]
	v_mfma_f32_16x16x32_bf16 v[112:115], v[212:215], v[188:191], v[64:67]
	v_mfma_f32_16x16x32_bf16 v[64:67], v[200:203], v[192:195], v[100:103]
	v_mfma_f32_16x16x32_bf16 v[100:103], v[204:207], v[196:199], v[64:67]
	v_mfma_f32_16x16x32_bf16 v[64:67], v[208:211], v[192:195], v[96:99]
	v_mfma_f32_16x16x32_bf16 v[96:99], v[212:215], v[196:199], v[64:67]
	s_mov_b32 m0, s24
	v_lshl_add_u64 v[192:193], v[220:221], 0, s[92:93]
	s_barrier
	s_nop 2
	ds_read_b128 v[64:67], v251 offset:49152
	ds_read_b128 v[68:71], v251 offset:50176
	ds_read_b128 v[72:75], v251 offset:51200
	ds_read_b128 v[76:79], v251 offset:52224
	ds_read_b128 v[176:179], v251 offset:53248
	ds_read_b128 v[180:183], v251 offset:54272
	ds_read_b128 v[184:187], v251 offset:55296
	ds_read_b128 v[188:191], v251 offset:56320
	global_load_lds_dwordx4 v[192:193], off
	v_lshl_add_u64 v[192:193], v[222:223], 0, s[92:93]
	s_mov_b32 m0, s25
	s_nop 0
	global_load_lds_dwordx4 v[192:193], off
	s_barrier
	s_waitcnt lgkmcnt(0)
	s_waitcnt lgkmcnt(0)
	v_mfma_f32_16x16x32_bf16 v[92:95], v[56:59], v[64:67], v[92:95]
	v_mfma_f32_16x16x32_bf16 v[88:91], v[80:83], v[64:67], v[88:91]
	v_mfma_f32_16x16x32_bf16 v[44:47], v[56:59], v[72:75], v[44:47]
	v_mfma_f32_16x16x32_bf16 v[40:43], v[80:83], v[72:75], v[40:43]
	v_mfma_f32_16x16x32_bf16 v[28:31], v[56:59], v[176:179], v[28:31]
	v_mfma_f32_16x16x32_bf16 v[24:27], v[80:83], v[176:179], v[24:27]
	v_mfma_f32_16x16x32_bf16 v[12:15], v[56:59], v[184:187], v[12:15]
	v_mfma_f32_16x16x32_bf16 v[8:11], v[80:83], v[184:187], v[8:11]
	v_mfma_f32_16x16x32_bf16 v[92:95], v[60:63], v[68:71], v[92:95]
	v_mfma_f32_16x16x32_bf16 v[88:91], v[84:87], v[68:71], v[88:91]
	v_mfma_f32_16x16x32_bf16 v[44:47], v[60:63], v[76:79], v[44:47]
	v_mfma_f32_16x16x32_bf16 v[40:43], v[84:87], v[76:79], v[40:43]
	v_mfma_f32_16x16x32_bf16 v[28:31], v[60:63], v[180:183], v[28:31]
	v_mfma_f32_16x16x32_bf16 v[24:27], v[84:87], v[180:183], v[24:27]
	v_mfma_f32_16x16x32_bf16 v[12:15], v[60:63], v[188:191], v[12:15]
	v_mfma_f32_16x16x32_bf16 v[8:11], v[84:87], v[188:191], v[8:11]
	s_barrier
	s_add_u32 s0, s0, 0x80080
	s_addc_u32 s1, s1, 0
	s_add_i32 s51, s66, s19
	v_lshl_add_u64 v[56:57], s[0:1], 0, v[160:161]
	s_mov_b32 m0, s51
	s_nop 0
	global_load_lds_dwordx4 v[56:57], off
	v_lshl_add_u64 v[56:57], s[0:1], 0, v[170:171]
	s_add_i32 m0, s51, 0x2000
	s_nop 0
	global_load_lds_dwordx4 v[56:57], off
	s_waitcnt vmcnt(6)
	s_barrier
	v_mfma_f32_16x16x32_bf16 v[48:51], v[200:203], v[64:67], v[48:51]
	v_mfma_f32_16x16x32_bf16 v[84:87], v[204:207], v[68:71], v[48:51]
	v_mfma_f32_16x16x32_bf16 v[48:51], v[208:211], v[64:67], v[52:55]
	v_mfma_f32_16x16x32_bf16 v[36:39], v[200:203], v[72:75], v[36:39]
	v_mfma_f32_16x16x32_bf16 v[32:35], v[208:211], v[72:75], v[32:35]
	v_mfma_f32_16x16x32_bf16 v[20:23], v[200:203], v[176:179], v[20:23]
	v_mfma_f32_16x16x32_bf16 v[16:19], v[208:211], v[176:179], v[16:19]
	v_mfma_f32_16x16x32_bf16 v[4:7], v[200:203], v[184:187], v[4:7]
	v_mfma_f32_16x16x32_bf16 v[0:3], v[208:211], v[184:187], v[0:3]
	v_mfma_f32_16x16x32_bf16 v[80:83], v[212:215], v[68:71], v[48:51]
	v_mfma_f32_16x16x32_bf16 v[36:39], v[204:207], v[76:79], v[36:39]
	v_mfma_f32_16x16x32_bf16 v[32:35], v[212:215], v[76:79], v[32:35]
	v_mfma_f32_16x16x32_bf16 v[20:23], v[204:207], v[180:183], v[20:23]
	v_mfma_f32_16x16x32_bf16 v[16:19], v[212:215], v[180:183], v[16:19]
	v_mfma_f32_16x16x32_bf16 v[4:7], v[204:207], v[188:191], v[4:7]
	v_mfma_f32_16x16x32_bf16 v[0:3], v[212:215], v[188:191], v[0:3]
	s_add_i32 s50, s50, 2
	s_add_u32 s8, s8, 0x100
	s_addc_u32 s9, s9, 0
	s_add_u32 s48, s48, 0x100
	s_addc_u32 s49, s49, 0
	s_cmp_gt_u32 s50, 29
	s_cbranch_scc0 .LBB0_859
	s_barrier
	v_lshl_or_b32 v186, s27, 8, v250
	v_lshl_add_u32 v176, s43, 8, v248
	v_ashrrev_i32_e32 v187, 31, v186
	v_lshlrev_b64 v[218:219], 1, v[186:187]
	v_ashrrev_i32_e32 v177, 31, v176
	v_lshl_add_u64 v[48:49], s[28:29], 0, v[218:219]
	v_lshlrev_b64 v[238:239], 12, v[176:177]
	v_lshl_add_u64 v[50:51], v[48:49], 0, v[238:239]
	global_load_dwordx2 v[240:241], v[50:51], off
	global_load_dwordx2 v[234:235], v[50:51], off offset:32
	global_load_dwordx2 v[232:233], v[50:51], off offset:256
	global_load_dwordx2 v[230:231], v[50:51], off offset:288
	v_or_b32_e32 v50, 16, v176
	v_ashrrev_i32_e32 v51, 31, v50
	v_lshlrev_b64 v[220:221], 12, v[50:51]
	v_lshl_add_u64 v[48:49], v[48:49], 0, v[220:221]
	global_load_dwordx2 v[224:225], v[48:49], off
	global_load_dwordx2 v[216:217], v[48:49], off offset:32
	global_load_dwordx2 v[212:213], v[48:49], off offset:256
	global_load_dwordx2 v[206:207], v[48:49], off offset:288
	v_lshlrev_b64 v[48:49], 2, v[186:187]
	v_lshl_add_u64 v[50:51], s[44:45], 0, v[48:49]
	v_lshl_add_u64 v[52:53], s[46:47], 0, v[48:49]
	v_lshl_add_u64 v[178:179], v[176:177], 3, s[34:35]
	global_load_dwordx4 v[72:75], v[50:51], off
	global_load_dwordx4 v[76:79], v[52:53], off
	global_load_dwordx4 v[64:67], v[50:51], off offset:64
	global_load_dwordx4 v[68:71], v[52:53], off offset:64
	global_load_dwordx4 v[56:59], v[50:51], off offset:512
	global_load_dwordx4 v[60:63], v[52:53], off offset:512
	s_nop 0
	global_load_dwordx4 v[48:51], v[50:51], off offset:576
	s_nop 0
	global_load_dwordx4 v[52:55], v[52:53], off offset:576
	v_add_co_u32_e32 v204, vcc, s89, v178
	global_load_dwordx2 v[180:181], v[178:179], off
	s_nop 0
	v_addc_co_u32_e32 v205, vcc, 0, v179, vcc
	global_load_dwordx2 v[182:183], v[204:205], off
	global_load_dwordx2 v[228:229], v[178:179], off offset:128
	global_load_dwordx2 v[226:227], v[204:205], off offset:128
	global_load_dwordx2 v[202:203], v[178:179], off offset:256
	global_load_dwordx2 v[200:201], v[204:205], off offset:256
	global_load_dwordx2 v[198:199], v[178:179], off offset:384
	global_load_dwordx2 v[196:197], v[204:205], off offset:384
	v_cmp_lt_i32_e64 s[8:9], 0, v247
	s_mov_b64 s[12:13], -1
	v_cmp_eq_u32_e32 vcc, 1, v247
	s_waitcnt vmcnt(0)
	v_lshlrev_b32_e32 v242, 16, v240
	v_and_b32_e32 v240, 0xffff0000, v240
	v_lshlrev_b32_e32 v244, 16, v241
	v_and_b32_e32 v243, 0xffff0000, v241
	v_cvt_f32_u32_e32 v184, v182
	v_cvt_f32_u32_e32 v185, v180
	v_cvt_f32_i32_e32 v180, v183
	v_cvt_f32_i32_e32 v181, v181
	v_pk_fma_f32 v[180:181], v[184:185], s[88:89], v[180:181] op_sel_hi:[1,0,1]
	s_nop 0
	v_pk_mul_f32 v[236:237], v[180:181], s[94:95] op_sel_hi:[1,0]
	s_nop 0
	v_fma_f32 v180, -v237, v237, v236
	v_add_f32_e32 v180, 0x3727c5ac, v180
	v_rsq_f32_e32 v236, v180
	global_load_dwordx2 v[194:195], v[178:179], off offset:1024
	global_load_dwordx2 v[192:193], v[204:205], off offset:1024
	global_load_dwordx2 v[190:191], v[178:179], off offset:1152
	global_load_dwordx2 v[188:189], v[204:205], off offset:1152
	global_load_dwordx2 v[184:185], v[178:179], off offset:1280
	global_load_dwordx2 v[182:183], v[204:205], off offset:1280
	global_load_dwordx2 v[180:181], v[178:179], off offset:1408
	s_nop 0
	global_load_dwordx2 v[178:179], v[204:205], off offset:1408
	v_or_b32_e32 v204, 32, v176
	v_ashrrev_i32_e32 v205, 31, v204
	v_lshlrev_b64 v[204:205], 12, v[204:205]
	v_lshl_add_u64 v[204:205], s[28:29], 0, v[204:205]
	v_lshl_add_u64 v[204:205], v[204:205], 0, v[218:219]
	global_load_dwordx2 v[222:223], v[204:205], off
	global_load_dwordx2 v[214:215], v[204:205], off offset:32
	global_load_dwordx2 v[210:211], v[204:205], off offset:256
	global_load_dwordx2 v[208:209], v[204:205], off offset:288
	v_sub_f32_e32 v241, v240, v237
	v_sub_f32_e32 v240, v242, v237
	v_sub_f32_e32 v243, v243, v237
	v_sub_f32_e32 v242, v244, v237
	v_pk_mul_f32 v[242:243], v[242:243], v[236:237] op_sel_hi:[1,0]
	v_pk_mul_f32 v[240:241], v[240:241], v[236:237] op_sel_hi:[1,0]
	v_pk_fma_f32 v[242:243], v[74:75], v[242:243], v[78:79]
	v_pk_fma_f32 v[240:241], v[72:73], v[240:241], v[76:77]
	v_pk_fma_f32 v[242:243], v[242:243], s[62:63], v[158:159] op_sel_hi:[1,0,1]
	v_lshl_add_u64 v[158:159], s[28:29], 0, v[238:239]
	v_pk_fma_f32 v[240:241], v[240:241], s[62:63], v[156:157] op_sel_hi:[1,0,1]
	v_lshl_add_u64 v[158:159], v[158:159], 0, v[218:219]
	v_cvt_pk_bf16_f32 v156, v240, v241
	v_cvt_pk_bf16_f32 v157, v242, v243
	global_store_dwordx2 v[158:159], v[156:157], off
	v_pk_mov_b32 v[156:157], v[240:241], v[242:243] op_sel:[1,0]
	v_mov_b32_e32 v238, v240
	v_mov_b32_e32 v239, v243
	v_pk_add_f32 v[156:157], v[156:157], v[238:239]
	v_mul_f32_e32 v238, v243, v243
	v_add_f32_e32 v156, v156, v157
	v_add_f32_e32 v157, 0, v156
	v_mul_f32_e32 v156, v241, v241
	v_fmac_f32_e32 v156, v240, v240
	v_fmac_f32_e32 v238, v242, v242
	v_add_f32_e32 v156, v156, v238
	v_lshlrev_b32_e32 v238, 16, v234
	v_and_b32_e32 v234, 0xffff0000, v234
	v_lshlrev_b32_e32 v240, 16, v235
	v_and_b32_e32 v239, 0xffff0000, v235
	v_sub_f32_e32 v235, v234, v237
	v_sub_f32_e32 v234, v238, v237
	v_sub_f32_e32 v239, v239, v237
	v_sub_f32_e32 v238, v240, v237
	v_pk_mul_f32 v[238:239], v[238:239], v[236:237] op_sel_hi:[1,0]
	v_pk_mul_f32 v[234:235], v[234:235], v[236:237] op_sel_hi:[1,0]
	v_pk_fma_f32 v[238:239], v[66:67], v[238:239], v[70:71]
	v_pk_fma_f32 v[234:235], v[64:65], v[234:235], v[68:69]
	v_pk_fma_f32 v[154:155], v[238:239], s[62:63], v[154:155] op_sel_hi:[1,0,1]
	v_pk_fma_f32 v[152:153], v[234:235], s[62:63], v[152:153] op_sel_hi:[1,0,1]
	v_mov_b32_e32 v239, v155
	v_cvt_pk_bf16_f32 v234, v152, v153
	v_cvt_pk_bf16_f32 v235, v154, v155
	global_store_dwordx2 v[158:159], v[234:235], off offset:32
	v_pk_mov_b32 v[234:235], v[152:153], v[154:155] op_sel:[1,0]
	v_mul_f32_e32 v153, v153, v153
	v_mov_b32_e32 v238, v152
	v_fmac_f32_e32 v153, v152, v152
	v_mul_f32_e32 v152, v155, v155
	v_fmac_f32_e32 v152, v154, v154
	v_add_f32_e32 v152, v153, v152
	v_add_f32_e32 v156, v156, v152
	v_lshlrev_b32_e32 v152, 16, v232
	v_and_b32_e32 v153, 0xffff0000, v232
	v_lshlrev_b32_e32 v154, 16, v233
	v_and_b32_e32 v155, 0xffff0000, v233
	v_sub_f32_e32 v153, v153, v237
	v_sub_f32_e32 v152, v152, v237
	v_sub_f32_e32 v155, v155, v237
	v_sub_f32_e32 v154, v154, v237
	v_pk_mul_f32 v[154:155], v[154:155], v[236:237] op_sel_hi:[1,0]
	v_pk_mul_f32 v[152:153], v[152:153], v[236:237] op_sel_hi:[1,0]
	v_pk_fma_f32 v[154:155], v[58:59], v[154:155], v[62:63]
	v_pk_fma_f32 v[152:153], v[56:57], v[152:153], v[60:61]
	v_pk_fma_f32 v[150:151], v[154:155], s[62:63], v[150:151] op_sel_hi:[1,0,1]
	v_pk_fma_f32 v[148:149], v[152:153], s[62:63], v[148:149] op_sel_hi:[1,0,1]
	v_add_f32_e32 v155, v150, v151
	v_cvt_pk_bf16_f32 v152, v148, v149
	v_cvt_pk_bf16_f32 v153, v150, v151
	global_store_dwordx2 v[158:159], v[152:153], off offset:256
	v_add_f32_e32 v153, v148, v149
	v_mul_f32_e32 v149, v149, v149
	v_fmac_f32_e32 v149, v148, v148
	v_mul_f32_e32 v148, v151, v151
	v_fmac_f32_e32 v148, v150, v150
	v_add_f32_e32 v148, v149, v148
	v_add_f32_e32 v232, v148, v156
	v_lshlrev_b32_e32 v148, 16, v230
	v_and_b32_e32 v149, 0xffff0000, v230
	v_lshlrev_b32_e32 v150, 16, v231
	v_and_b32_e32 v151, 0xffff0000, v231
	v_sub_f32_e32 v149, v149, v237
	v_sub_f32_e32 v148, v148, v237
	v_sub_f32_e32 v151, v151, v237
	v_sub_f32_e32 v150, v150, v237
	v_pk_mul_f32 v[150:151], v[150:151], v[236:237] op_sel_hi:[1,0]
	v_pk_mul_f32 v[148:149], v[148:149], v[236:237] op_sel_hi:[1,0]
	v_pk_add_f32 v[234:235], v[234:235], v[238:239]
	v_pk_fma_f32 v[148:149], v[48:49], v[148:149], v[52:53]
	v_pk_fma_f32 v[150:151], v[50:51], v[150:151], v[54:55]
	v_pk_add_f32 v[234:235], v[234:235], v[234:235] op_sel_hi:[0,1]
	v_pk_fma_f32 v[146:147], v[150:151], s[62:63], v[146:147] op_sel_hi:[1,0,1]
	v_pk_fma_f32 v[144:145], v[148:149], s[62:63], v[144:145] op_sel_hi:[1,0,1]
	v_mov_b32_e32 v234, v146
	v_cvt_pk_bf16_f32 v148, v144, v145
	v_cvt_pk_bf16_f32 v149, v146, v147
	v_mov_b32_e32 v152, v144
	v_mov_b32_e32 v154, v145
	v_mov_b32_e32 v156, v147
	global_store_dwordx2 v[158:159], v[148:149], off offset:288
	v_pk_add_f32 v[148:149], v[152:153], v[154:155]
	v_pk_add_f32 v[150:151], v[234:235], v[156:157]
	v_mul_f32_e32 v145, v145, v145
	v_pk_add_f32 v[148:149], v[148:149], v[150:151]
	v_fmac_f32_e32 v145, v144, v144
	v_mul_f32_e32 v144, v147, v147
	v_pk_add_f32 v[148:149], v[148:149], v[148:149] op_sel:[0,1] op_sel_hi:[1,0]
	v_fmac_f32_e32 v144, v146, v146
	v_add_f32_e32 v144, v145, v144
	v_mov_b32_e32 v145, v148
	v_add_f32_e32 v144, v144, v232
	s_nop 0
	v_permlane16_swap_b32_e32 v148, v145
	v_add_f32_e32 v148, v148, v145
	v_mov_b32_e32 v145, v144
	s_nop 1
	v_permlane16_swap_b32_e32 v144, v145
	v_add_f32_e32 v146, v144, v145
	v_mov_b32_e32 v149, v148
	v_mov_b32_e32 v147, v146
	s_nop 0
	v_permlane32_swap_b32_e32 v148, v149
	v_permlane32_swap_b32_e32 v146, v147
	v_mov_b64_e32 v[144:145], 0x80000
	s_and_saveexec_b64 s[0:1], s[8:9]
	s_cbranch_execz .LBB0_864
	v_cmp_eq_u32_e64 s[8:9], 1, v247
	s_mov_b64 s[12:13], 0
	v_mov_b64_e32 v[144:145], 0x80000
	s_and_saveexec_b64 s[14:15], s[8:9]
	s_mov_b64 s[12:13], exec
	v_mov_b64_e32 v[144:145], 0xc0000
	s_or_b64 exec, exec, s[14:15]
	s_orn2_b64 s[12:13], s[12:13], exec
	v_mov_b32_e32 v148, v146
	v_mov_b32_e32 v149, v147

.LBB0_1056:
	s_barrier
	s_add_u32 s0, s78, 0xfff80080
	s_addc_u32 s1, s79, -1
	s_add_i32 s50, 0, 0x10000
	v_add_u32_e32 v76, s50, v205
	ds_read_b128 v[64:67], v76
	ds_read_b128 v[68:71], v76 offset:1024
	ds_read_b128 v[72:75], v76 offset:2048
	ds_read_b128 v[76:79], v76 offset:3072
	s_cmp_eq_u32 s47, 28
	s_cselect_b32 s81, s14, s1
	s_cselect_b32 s80, s15, s0
	s_cselect_b32 s1, s16, s13
	s_cselect_b32 s0, s17, s12
	ds_read_b128 v[80:83], v207
	ds_read_b128 v[84:87], v207 offset:1024
	ds_read_b128 v[88:91], v207 offset:2048
	ds_read_b128 v[92:95], v207 offset:3072
	ds_read_b128 v[180:183], v207 offset:4096
	ds_read_b128 v[184:187], v207 offset:5120
	ds_read_b128 v[188:191], v207 offset:6144
	ds_read_b128 v[192:195], v207 offset:7168
	s_waitcnt lgkmcnt(8)
	s_barrier
	s_waitcnt lgkmcnt(0)
	s_waitcnt lgkmcnt(0)
	v_mfma_f32_16x16x32_bf16 v[156:159], v[64:67], v[80:83], v[156:159]
	v_mfma_f32_16x16x32_bf16 v[152:155], v[72:75], v[80:83], v[152:155]
	v_mfma_f32_16x16x32_bf16 v[148:151], v[64:67], v[88:91], v[148:151]
	v_mfma_f32_16x16x32_bf16 v[140:143], v[72:75], v[88:91], v[140:143]
	v_mfma_f32_16x16x32_bf16 v[132:135], v[64:67], v[180:183], v[132:135]
	v_mfma_f32_16x16x32_bf16 v[124:127], v[72:75], v[180:183], v[124:127]
	v_mfma_f32_16x16x32_bf16 v[116:119], v[64:67], v[188:191], v[116:119]
	v_mfma_f32_16x16x32_bf16 v[108:111], v[72:75], v[188:191], v[108:111]
	v_mfma_f32_16x16x32_bf16 v[156:159], v[68:71], v[84:87], v[156:159]
	v_mfma_f32_16x16x32_bf16 v[152:155], v[76:79], v[84:87], v[152:155]
	v_mfma_f32_16x16x32_bf16 v[148:151], v[68:71], v[92:95], v[148:151]
	v_mfma_f32_16x16x32_bf16 v[140:143], v[76:79], v[92:95], v[140:143]
	v_mfma_f32_16x16x32_bf16 v[132:135], v[68:71], v[184:187], v[132:135]
	v_mfma_f32_16x16x32_bf16 v[124:127], v[76:79], v[184:187], v[124:127]
	v_mfma_f32_16x16x32_bf16 v[116:119], v[68:71], v[192:195], v[116:119]
	v_mfma_f32_16x16x32_bf16 v[108:111], v[76:79], v[192:195], v[108:111]
	s_barrier
	v_lshl_add_u64 v[196:197], s[78:79], 0, v[176:177]
	s_add_i32 m0, s22, 0xc000
	s_nop 0
	global_load_lds_dwordx4 v[196:197], off
	v_lshl_add_u64 v[196:197], s[78:79], 0, v[178:179]
	s_add_i32 m0, s22, 0xe000
	s_nop 0
	global_load_lds_dwordx4 v[196:197], off
	s_add_i32 s66, 0, 0x14000
	s_add_i32 s50, s50, s21
	v_add_u32_e32 v212, s66, v205
	v_lshl_add_u64 v[224:225], s[0:1], 0, v[160:161]
	s_mov_b32 m0, s50
	ds_read_b128 v[196:199], v212
	ds_read_b128 v[200:203], v212 offset:1024
	ds_read_b128 v[208:211], v212 offset:2048
	ds_read_b128 v[212:215], v212 offset:3072
	global_load_lds_dwordx4 v[224:225], off
	v_lshl_add_u64 v[226:227], s[0:1], 0, v[170:171]
	s_add_i32 m0, s50, 0x2000
	s_nop 0
	global_load_lds_dwordx4 v[226:227], off
	s_barrier
	s_waitcnt lgkmcnt(0)
	s_waitcnt lgkmcnt(0)
	v_mfma_f32_16x16x32_bf16 v[144:147], v[196:199], v[80:83], v[144:147]
	v_mfma_f32_16x16x32_bf16 v[80:83], v[208:211], v[80:83], v[136:139]
	v_mfma_f32_16x16x32_bf16 v[144:147], v[200:203], v[84:87], v[144:147]
	v_mfma_f32_16x16x32_bf16 v[80:83], v[212:215], v[84:87], v[80:83]
	v_mfma_f32_16x16x32_bf16 v[84:87], v[196:199], v[88:91], v[128:131]
	v_mfma_f32_16x16x32_bf16 v[88:91], v[208:211], v[88:91], v[120:123]
	v_mfma_f32_16x16x32_bf16 v[104:107], v[208:211], v[180:183], v[104:107]
	v_mfma_f32_16x16x32_bf16 v[100:103], v[196:199], v[188:191], v[100:103]
	v_mfma_f32_16x16x32_bf16 v[96:99], v[208:211], v[188:191], v[96:99]
	v_mfma_f32_16x16x32_bf16 v[84:87], v[200:203], v[92:95], v[84:87]
	v_mfma_f32_16x16x32_bf16 v[88:91], v[212:215], v[92:95], v[88:91]
	v_mfma_f32_16x16x32_bf16 v[92:95], v[196:199], v[180:183], v[112:115]
	v_mfma_f32_16x16x32_bf16 v[104:107], v[212:215], v[184:187], v[104:107]
	v_mfma_f32_16x16x32_bf16 v[100:103], v[200:203], v[192:195], v[100:103]
	v_mfma_f32_16x16x32_bf16 v[96:99], v[212:215], v[192:195], v[96:99]
	v_mfma_f32_16x16x32_bf16 v[92:95], v[200:203], v[184:187], v[92:95]
	s_mov_b32 m0, s22
	v_lshl_add_u64 v[228:229], s[80:81], 0, v[174:175]
	s_barrier
	ds_read_b128 v[112:115], v207 offset:16384
	ds_read_b128 v[120:123], v207 offset:17408
	ds_read_b128 v[128:131], v207 offset:18432
	ds_read_b128 v[136:139], v207 offset:19456
	ds_read_b128 v[180:183], v207 offset:20480
	ds_read_b128 v[184:187], v207 offset:21504
	ds_read_b128 v[188:191], v207 offset:22528
	ds_read_b128 v[192:195], v207 offset:23552
	global_load_lds_dwordx4 v[228:229], off
	v_lshl_add_u64 v[230:231], s[80:81], 0, v[172:173]
	s_mov_b32 m0, s23
	s_nop 0
	global_load_lds_dwordx4 v[230:231], off
	s_waitcnt vmcnt(10)
	s_barrier
	s_waitcnt lgkmcnt(0)
	s_waitcnt lgkmcnt(0)
	v_mfma_f32_16x16x32_bf16 v[60:63], v[64:67], v[112:115], v[60:63]
	v_mfma_f32_16x16x32_bf16 v[56:59], v[72:75], v[112:115], v[56:59]
	v_mfma_f32_16x16x32_bf16 v[44:47], v[64:67], v[128:131], v[44:47]
	v_mfma_f32_16x16x32_bf16 v[40:43], v[72:75], v[128:131], v[40:43]
	v_mfma_f32_16x16x32_bf16 v[28:31], v[64:67], v[180:183], v[28:31]
	v_mfma_f32_16x16x32_bf16 v[24:27], v[72:75], v[180:183], v[24:27]
	v_mfma_f32_16x16x32_bf16 v[12:15], v[64:67], v[188:191], v[12:15]
	v_mfma_f32_16x16x32_bf16 v[8:11], v[72:75], v[188:191], v[8:11]
	v_mfma_f32_16x16x32_bf16 v[60:63], v[68:71], v[120:123], v[60:63]
	v_mfma_f32_16x16x32_bf16 v[56:59], v[76:79], v[120:123], v[56:59]
	v_mfma_f32_16x16x32_bf16 v[44:47], v[68:71], v[136:139], v[44:47]
	v_mfma_f32_16x16x32_bf16 v[40:43], v[76:79], v[136:139], v[40:43]
	v_mfma_f32_16x16x32_bf16 v[28:31], v[68:71], v[184:187], v[28:31]
	v_mfma_f32_16x16x32_bf16 v[24:27], v[76:79], v[184:187], v[24:27]
	v_mfma_f32_16x16x32_bf16 v[12:15], v[68:71], v[192:195], v[12:15]
	v_mfma_f32_16x16x32_bf16 v[8:11], v[76:79], v[192:195], v[8:11]
	s_barrier
	s_add_u32 s50, s0, 0x80000
	s_addc_u32 s51, s1, 0
	s_add_i32 s66, s66, s21
	v_lshl_add_u64 v[64:65], s[50:51], 0, v[160:161]
	s_mov_b32 m0, s66
	s_nop 0
	global_load_lds_dwordx4 v[64:65], off
	v_lshl_add_u64 v[64:65], s[50:51], 0, v[170:171]
	s_add_i32 m0, s66, 0x2000
	s_nop 0
	global_load_lds_dwordx4 v[64:65], off
	v_add_u32_e32 v76, 0x18000, v205
	ds_read_b128 v[64:67], v76
	ds_read_b128 v[68:71], v76 offset:1024
	ds_read_b128 v[72:75], v76 offset:2048
	ds_read_b128 v[76:79], v76 offset:3072
	s_waitcnt vmcnt(6)
	s_barrier
	v_mfma_f32_16x16x32_bf16 v[52:55], v[196:199], v[112:115], v[52:55]
	v_mfma_f32_16x16x32_bf16 v[48:51], v[208:211], v[112:115], v[48:51]
	v_mfma_f32_16x16x32_bf16 v[36:39], v[196:199], v[128:131], v[36:39]
	v_mfma_f32_16x16x32_bf16 v[32:35], v[208:211], v[128:131], v[32:35]
	v_mfma_f32_16x16x32_bf16 v[20:23], v[196:199], v[180:183], v[20:23]
	v_mfma_f32_16x16x32_bf16 v[16:19], v[208:211], v[180:183], v[16:19]
	v_mfma_f32_16x16x32_bf16 v[4:7], v[196:199], v[188:191], v[4:7]
	v_mfma_f32_16x16x32_bf16 v[0:3], v[208:211], v[188:191], v[0:3]
	v_mfma_f32_16x16x32_bf16 v[52:55], v[200:203], v[120:123], v[52:55]
	v_mfma_f32_16x16x32_bf16 v[48:51], v[212:215], v[120:123], v[48:51]
	v_mfma_f32_16x16x32_bf16 v[36:39], v[200:203], v[136:139], v[36:39]
	v_mfma_f32_16x16x32_bf16 v[32:35], v[212:215], v[136:139], v[32:35]
	v_mfma_f32_16x16x32_bf16 v[20:23], v[200:203], v[184:187], v[20:23]
	v_mfma_f32_16x16x32_bf16 v[16:19], v[212:215], v[184:187], v[16:19]
	v_mfma_f32_16x16x32_bf16 v[4:7], v[200:203], v[192:195], v[4:7]
	v_mfma_f32_16x16x32_bf16 v[0:3], v[212:215], v[192:195], v[0:3]
	s_add_i32 s66, 0, 0x18000
	s_barrier
	ds_read_b128 v[112:115], v207 offset:32768
	ds_read_b128 v[120:123], v207 offset:33792
	ds_read_b128 v[180:183], v207 offset:34816
	ds_read_b128 v[184:187], v207 offset:35840
	ds_read_b128 v[188:191], v207 offset:36864
	ds_read_b128 v[192:195], v207 offset:37888
	ds_read_b128 v[196:199], v207 offset:38912
	ds_read_b128 v[200:203], v207 offset:39936
	s_waitcnt lgkmcnt(8)
	s_barrier
	s_waitcnt lgkmcnt(0)
	s_waitcnt lgkmcnt(0)
	v_mfma_f32_16x16x32_bf16 v[128:131], v[64:67], v[112:115], v[156:159]
	v_mfma_f32_16x16x32_bf16 v[156:159], v[68:71], v[120:123], v[128:131]
	v_mfma_f32_16x16x32_bf16 v[128:131], v[72:75], v[112:115], v[152:155]
	v_mfma_f32_16x16x32_bf16 v[152:155], v[76:79], v[120:123], v[128:131]
	v_mfma_f32_16x16x32_bf16 v[128:131], v[64:67], v[180:183], v[148:151]
	v_mfma_f32_16x16x32_bf16 v[148:151], v[68:71], v[184:187], v[128:131]
	v_mfma_f32_16x16x32_bf16 v[128:131], v[72:75], v[180:183], v[140:143]
	v_mfma_f32_16x16x32_bf16 v[140:143], v[76:79], v[184:187], v[128:131]
	v_mfma_f32_16x16x32_bf16 v[128:131], v[64:67], v[188:191], v[132:135]
	v_mfma_f32_16x16x32_bf16 v[124:127], v[72:75], v[188:191], v[124:127]
	v_mfma_f32_16x16x32_bf16 v[116:119], v[64:67], v[196:199], v[116:119]
	v_mfma_f32_16x16x32_bf16 v[108:111], v[72:75], v[196:199], v[108:111]
	v_mfma_f32_16x16x32_bf16 v[132:135], v[68:71], v[192:195], v[128:131]
	v_mfma_f32_16x16x32_bf16 v[124:127], v[76:79], v[192:195], v[124:127]
	v_mfma_f32_16x16x32_bf16 v[116:119], v[68:71], v[200:203], v[116:119]
	v_mfma_f32_16x16x32_bf16 v[108:111], v[76:79], v[200:203], v[108:111]
	s_barrier
	s_add_u32 s50, s80, 0x80000
	s_addc_u32 s51, s81, 0
	v_lshl_add_u64 v[128:129], s[50:51], 0, v[174:175]
	s_mov_b32 m0, s24
	s_nop 0
	global_load_lds_dwordx4 v[128:129], off
	v_lshl_add_u64 v[128:129], s[50:51], 0, v[172:173]
	s_mov_b32 m0, s25
	s_nop 0
	global_load_lds_dwordx4 v[128:129], off
	s_add_i32 s50, 0, 0x1c000
	v_add_u32_e32 v128, s50, v205
	s_add_i32 s51, s66, s21
	ds_read_b128 v[208:211], v128
	ds_read_b128 v[212:215], v128 offset:1024
	ds_read_b128 v[216:219], v128 offset:2048
	ds_read_b128 v[220:223], v128 offset:3072
	v_lshl_add_u64 v[128:129], v[224:225], 0, s[92:93]
	s_mov_b32 m0, s51
	s_nop 0
	global_load_lds_dwordx4 v[128:129], off
	v_lshl_add_u64 v[128:129], v[226:227], 0, s[92:93]
	s_add_i32 m0, s51, 0x2000
	s_nop 0
	global_load_lds_dwordx4 v[128:129], off
	s_barrier
	s_waitcnt lgkmcnt(0)
	s_waitcnt lgkmcnt(0)
	v_mfma_f32_16x16x32_bf16 v[80:83], v[216:219], v[112:115], v[80:83]
	v_mfma_f32_16x16x32_bf16 v[128:131], v[208:211], v[112:115], v[144:147]
	v_mfma_f32_16x16x32_bf16 v[136:139], v[220:223], v[120:123], v[80:83]
	v_mfma_f32_16x16x32_bf16 v[80:83], v[208:211], v[180:183], v[84:87]
	v_mfma_f32_16x16x32_bf16 v[144:147], v[212:215], v[120:123], v[128:131]
	v_mfma_f32_16x16x32_bf16 v[128:131], v[212:215], v[184:187], v[80:83]
	v_mfma_f32_16x16x32_bf16 v[80:83], v[216:219], v[180:183], v[88:91]
	v_mfma_f32_16x16x32_bf16 v[120:123], v[220:223], v[184:187], v[80:83]
	v_mfma_f32_16x16x32_bf16 v[80:83], v[208:211], v[188:191], v[92:95]
	v_mfma_f32_16x16x32_bf16 v[112:115], v[212:215], v[192:195], v[80:83]
	v_mfma_f32_16x16x32_bf16 v[80:83], v[216:219], v[188:191], v[104:107]
	v_mfma_f32_16x16x32_bf16 v[104:107], v[220:223], v[192:195], v[80:83]
	v_mfma_f32_16x16x32_bf16 v[80:83], v[208:211], v[196:199], v[100:103]
	v_mfma_f32_16x16x32_bf16 v[100:103], v[212:215], v[200:203], v[80:83]
	v_mfma_f32_16x16x32_bf16 v[80:83], v[216:219], v[196:199], v[96:99]
	v_mfma_f32_16x16x32_bf16 v[96:99], v[220:223], v[200:203], v[80:83]
	s_mov_b32 m0, s26
	v_lshl_add_u64 v[196:197], v[228:229], 0, s[92:93]
	s_barrier
	s_nop 2
	ds_read_b128 v[80:83], v207 offset:49152
	ds_read_b128 v[84:87], v207 offset:50176
	ds_read_b128 v[88:91], v207 offset:51200
	ds_read_b128 v[92:95], v207 offset:52224
	ds_read_b128 v[180:183], v207 offset:53248
	ds_read_b128 v[184:187], v207 offset:54272
	ds_read_b128 v[188:191], v207 offset:55296
	ds_read_b128 v[192:195], v207 offset:56320
	global_load_lds_dwordx4 v[196:197], off
	v_lshl_add_u64 v[196:197], v[230:231], 0, s[92:93]
	s_mov_b32 m0, s27
	s_nop 0
	global_load_lds_dwordx4 v[196:197], off
	s_barrier
	s_waitcnt lgkmcnt(0)
	s_waitcnt lgkmcnt(0)
	v_mfma_f32_16x16x32_bf16 v[60:63], v[64:67], v[80:83], v[60:63]
	v_mfma_f32_16x16x32_bf16 v[56:59], v[72:75], v[80:83], v[56:59]
	v_mfma_f32_16x16x32_bf16 v[44:47], v[64:67], v[88:91], v[44:47]
	v_mfma_f32_16x16x32_bf16 v[40:43], v[72:75], v[88:91], v[40:43]
	v_mfma_f32_16x16x32_bf16 v[28:31], v[64:67], v[180:183], v[28:31]
	v_mfma_f32_16x16x32_bf16 v[24:27], v[72:75], v[180:183], v[24:27]
	v_mfma_f32_16x16x32_bf16 v[12:15], v[64:67], v[188:191], v[12:15]
	v_mfma_f32_16x16x32_bf16 v[8:11], v[72:75], v[188:191], v[8:11]
	v_mfma_f32_16x16x32_bf16 v[60:63], v[68:71], v[84:87], v[60:63]
	v_mfma_f32_16x16x32_bf16 v[56:59], v[76:79], v[84:87], v[56:59]
	v_mfma_f32_16x16x32_bf16 v[44:47], v[68:71], v[92:95], v[44:47]
	v_mfma_f32_16x16x32_bf16 v[40:43], v[76:79], v[92:95], v[40:43]
	v_mfma_f32_16x16x32_bf16 v[28:31], v[68:71], v[184:187], v[28:31]
	v_mfma_f32_16x16x32_bf16 v[24:27], v[76:79], v[184:187], v[24:27]
	v_mfma_f32_16x16x32_bf16 v[12:15], v[68:71], v[192:195], v[12:15]
	v_mfma_f32_16x16x32_bf16 v[8:11], v[76:79], v[192:195], v[8:11]
	s_barrier
	s_add_u32 s0, s0, 0x80080
	s_addc_u32 s1, s1, 0
	s_add_i32 s50, s50, s21
	v_lshl_add_u64 v[64:65], s[0:1], 0, v[160:161]
	s_mov_b32 m0, s50
	s_nop 0
	global_load_lds_dwordx4 v[64:65], off
	v_lshl_add_u64 v[64:65], s[0:1], 0, v[170:171]
	s_add_i32 m0, s50, 0x2000
	s_nop 0
	global_load_lds_dwordx4 v[64:65], off
	s_waitcnt vmcnt(6)
	s_barrier
	v_mfma_f32_16x16x32_bf16 v[52:55], v[208:211], v[80:83], v[52:55]
	v_mfma_f32_16x16x32_bf16 v[48:51], v[216:219], v[80:83], v[48:51]
	v_mfma_f32_16x16x32_bf16 v[36:39], v[208:211], v[88:91], v[36:39]
	v_mfma_f32_16x16x32_bf16 v[32:35], v[216:219], v[88:91], v[32:35]
	v_mfma_f32_16x16x32_bf16 v[20:23], v[208:211], v[180:183], v[20:23]
	v_mfma_f32_16x16x32_bf16 v[16:19], v[216:219], v[180:183], v[16:19]
	v_mfma_f32_16x16x32_bf16 v[4:7], v[208:211], v[188:191], v[4:7]
	v_mfma_f32_16x16x32_bf16 v[0:3], v[216:219], v[188:191], v[0:3]
	v_mfma_f32_16x16x32_bf16 v[52:55], v[212:215], v[84:87], v[52:55]
	v_mfma_f32_16x16x32_bf16 v[48:51], v[220:223], v[84:87], v[48:51]
	v_mfma_f32_16x16x32_bf16 v[36:39], v[212:215], v[92:95], v[36:39]
	v_mfma_f32_16x16x32_bf16 v[32:35], v[220:223], v[92:95], v[32:35]
	v_mfma_f32_16x16x32_bf16 v[20:23], v[212:215], v[184:187], v[20:23]
	v_mfma_f32_16x16x32_bf16 v[16:19], v[220:223], v[184:187], v[16:19]
	v_mfma_f32_16x16x32_bf16 v[4:7], v[212:215], v[192:195], v[4:7]
	v_mfma_f32_16x16x32_bf16 v[0:3], v[220:223], v[192:195], v[0:3]
	s_add_i32 s47, s47, 2
	s_add_u32 s78, s78, 0x100
	s_addc_u32 s79, s79, 0
	s_add_u32 s12, s12, 0x100
	s_addc_u32 s13, s13, 0
	s_cmp_gt_u32 s47, 29
	s_cbranch_scc0 .LBB0_1056
	s_barrier
	v_lshl_or_b32 v182, s48, 8, v206
	v_ashrrev_i32_e32 v183, 31, v182
	v_lshlrev_b64 v[64:65], 2, v[182:183]
	v_lshl_add_u64 v[66:67], s[44:45], 0, v[64:65]
	v_lshl_add_u64 v[64:65], s[42:43], 0, v[64:65]
	global_load_dwordx4 v[72:75], v[66:67], off offset:16
	global_load_dwordx4 v[92:95], v[66:67], off
	global_load_dwordx4 v[68:71], v[64:65], off offset:16
	global_load_dwordx4 v[88:91], v[64:65], off
	v_or_b32_e32 v64, 0x80, v182
	v_lshl_add_u32 v180, s49, 8, v204
	v_ashrrev_i32_e32 v65, 31, v64
	v_or_b32_e32 v84, 0x84, v182
	v_lshlrev_b64 v[64:65], 2, v[64:65]
	v_ashrrev_i32_e32 v85, 31, v84
	v_ashrrev_i32_e32 v181, 31, v180
	v_lshl_add_u64 v[66:67], s[44:45], 0, v[64:65]
	v_lshl_add_u64 v[76:77], s[42:43], 0, v[64:65]
	v_lshl_add_u64 v[84:85], v[84:85], 2, s[44:45]
	v_lshl_add_u64 v[202:203], v[180:181], 3, s[8:9]
	global_load_dwordx4 v[80:83], v[66:67], off
	s_nop 0
	global_load_dwordx4 v[64:67], v[76:77], off offset:16
	s_nop 0
	global_load_dwordx4 v[76:79], v[76:77], off
	v_add_co_u32_e32 v200, vcc, s89, v202
	global_load_dwordx4 v[84:87], v[84:85], off
	s_nop 0
	v_addc_co_u32_e32 v201, vcc, 0, v203, vcc
	global_load_dwordx2 v[184:185], v[202:203], off
	global_load_dwordx2 v[186:187], v[200:201], off
	global_load_dwordx2 v[208:209], v[202:203], off offset:128
	global_load_dwordx2 v[210:211], v[200:201], off offset:128
	global_load_dwordx2 v[212:213], v[202:203], off offset:256
	global_load_dwordx2 v[214:215], v[200:201], off offset:256
	global_load_dwordx2 v[216:217], v[202:203], off offset:384
	global_load_dwordx2 v[218:219], v[200:201], off offset:384
	global_load_dwordx2 v[232:233], v[202:203], off offset:1024
	global_load_dwordx2 v[234:235], v[200:201], off offset:1024
	global_load_dwordx2 v[236:237], v[202:203], off offset:1152
	global_load_dwordx2 v[238:239], v[200:201], off offset:1152
	global_load_dwordx2 v[240:241], v[202:203], off offset:1280
	global_load_dwordx2 v[242:243], v[200:201], off offset:1280
	global_load_dwordx2 v[248:249], v[202:203], off offset:1408
	global_load_dwordx2 v[250:251], v[200:201], off offset:1408
	s_mov_b64 s[0:1], 0x200000
	v_readlane_b32 s66, v255, 7
	s_mov_b32 s48, s72
	s_mov_b32 s49, s46
	s_mov_b64 s[12:13], s[74:75]
	v_readlane_b32 s67, v255, 8
	s_waitcnt vmcnt(0)
	v_xor_b32_e32 v197, 0x80000000, v75
	v_xor_b32_e32 v196, 0x80000000, v74
	v_xor_b32_e32 v199, 0x80000000, v95
	v_xor_b32_e32 v198, 0x80000000, v94
	v_xor_b32_e32 v195, 0x80000000, v83
	v_xor_b32_e32 v194, 0x80000000, v82
	v_cvt_f32_u32_e32 v188, v186
	v_xor_b32_e32 v193, 0x80000000, v87
	v_xor_b32_e32 v192, 0x80000000, v86
	v_cvt_f32_u32_e32 v189, v184
	v_cvt_f32_i32_e32 v184, v187
	v_cvt_f32_i32_e32 v185, v185
	v_pk_fma_f32 v[184:185], v[188:189], s[88:89], v[184:185] op_sel_hi:[1,0,1]
	s_nop 0
	v_pk_mul_f32 v[220:221], v[184:185], s[94:95] op_sel_hi:[1,0]
	s_nop 0
	v_fma_f32 v184, -v221, v221, v220
	v_add_f32_e32 v184, 0x3727c5ac, v184
	v_rsq_f32_e32 v222, v184
	v_pk_fma_f32 v[74:75], v[196:197], v[220:221], v[154:155] op_sel:[0,1,0]
	v_pk_fma_f32 v[156:157], v[92:93], v[220:221], v[156:157] op_sel:[0,1,0] neg_lo:[1,0,0] neg_hi:[1,0,0]
	v_pk_fma_f32 v[94:95], v[198:199], v[220:221], v[158:159] op_sel:[0,1,0]
	v_pk_fma_f32 v[186:187], v[74:75], v[222:223], v[70:71] op_sel_hi:[1,0,1]
	v_pk_fma_f32 v[74:75], v[80:81], v[220:221], v[144:145] op_sel:[0,1,0] neg_lo:[1,0,0] neg_hi:[1,0,0]
	v_pk_fma_f32 v[82:83], v[194:195], v[220:221], v[146:147] op_sel:[0,1,0]
	v_pk_fma_f32 v[184:185], v[94:95], v[222:223], v[90:91] op_sel_hi:[1,0,1]
	v_pk_fma_f32 v[188:189], v[156:157], v[222:223], v[88:89] op_sel_hi:[1,0,1]
	v_pk_fma_f32 v[94:95], v[72:73], v[220:221], v[152:153] op_sel:[0,1,0] neg_lo:[1,0,0] neg_hi:[1,0,0]
	v_pk_fma_f32 v[152:153], v[82:83], v[222:223], v[78:79] op_sel_hi:[1,0,1]
	v_pk_fma_f32 v[156:157], v[74:75], v[222:223], v[76:77] op_sel_hi:[1,0,1]
	v_pk_fma_f32 v[74:75], v[84:85], v[220:221], v[136:137] op_sel:[0,1,0] neg_lo:[1,0,0] neg_hi:[1,0,0]
	v_pk_fma_f32 v[82:83], v[192:193], v[220:221], v[138:139] op_sel:[0,1,0]
	v_pk_fma_f32 v[158:159], v[74:75], v[222:223], v[64:65] op_sel_hi:[1,0,1]
	v_pk_fma_f32 v[154:155], v[82:83], v[222:223], v[66:67] op_sel_hi:[1,0,1]
	v_cvt_f32_u32_e32 v74, v210
	v_cvt_f32_u32_e32 v75, v208
	v_cvt_f32_i32_e32 v82, v211
	v_cvt_f32_i32_e32 v83, v209
	v_pk_fma_f32 v[190:191], v[94:95], v[222:223], v[68:69] op_sel_hi:[1,0,1]
	v_pk_fma_f32 v[74:75], v[74:75], s[88:89], v[82:83] op_sel_hi:[1,0,1]
	s_nop 0
	v_pk_mul_f32 v[74:75], v[74:75], s[94:95] op_sel_hi:[1,0]
	s_nop 0
	v_fma_f32 v82, -v75, v75, v74
	v_add_f32_e32 v82, 0x3727c5ac, v82
	v_rsq_f32_e32 v82, v82
	v_pk_fma_f32 v[86:87], v[92:93], v[74:75], v[148:149] op_sel:[0,1,0] neg_lo:[1,0,0] neg_hi:[1,0,0]
	v_pk_fma_f32 v[94:95], v[198:199], v[74:75], v[150:151] op_sel:[0,1,0]
	v_pk_fma_f32 v[148:149], v[86:87], v[82:83], v[88:89] op_sel_hi:[1,0,1]
	v_pk_fma_f32 v[86:87], v[72:73], v[74:75], v[140:141] op_sel:[0,1,0] neg_lo:[1,0,0] neg_hi:[1,0,0]
	v_pk_fma_f32 v[144:145], v[94:95], v[82:83], v[90:91] op_sel_hi:[1,0,1]
	v_pk_fma_f32 v[94:95], v[196:197], v[74:75], v[142:143] op_sel:[0,1,0]
	v_pk_fma_f32 v[150:151], v[86:87], v[82:83], v[68:69] op_sel_hi:[1,0,1]
	v_pk_fma_f32 v[86:87], v[80:81], v[74:75], v[128:129] op_sel:[0,1,0] neg_lo:[1,0,0] neg_hi:[1,0,0]
	v_pk_fma_f32 v[146:147], v[94:95], v[82:83], v[70:71] op_sel_hi:[1,0,1]
	v_pk_fma_f32 v[94:95], v[194:195], v[74:75], v[130:131] op_sel:[0,1,0]
	v_pk_fma_f32 v[140:141], v[86:87], v[82:83], v[76:77] op_sel_hi:[1,0,1]
	v_pk_fma_f32 v[86:87], v[84:85], v[74:75], v[120:121] op_sel:[0,1,0] neg_lo:[1,0,0] neg_hi:[1,0,0]
	v_pk_fma_f32 v[74:75], v[192:193], v[74:75], v[122:123] op_sel:[0,1,0]
	v_pk_fma_f32 v[136:137], v[94:95], v[82:83], v[78:79] op_sel_hi:[1,0,1]
	v_pk_fma_f32 v[138:139], v[74:75], v[82:83], v[66:67] op_sel_hi:[1,0,1]
	v_pk_fma_f32 v[142:143], v[86:87], v[82:83], v[64:65] op_sel_hi:[1,0,1]
	v_cvt_f32_u32_e32 v74, v214
	v_cvt_f32_u32_e32 v75, v212
	v_cvt_f32_i32_e32 v82, v215
	v_cvt_f32_i32_e32 v83, v213
	v_pk_fma_f32 v[74:75], v[74:75], s[88:89], v[82:83] op_sel_hi:[1,0,1]
	s_nop 0
	v_pk_mul_f32 v[74:75], v[74:75], s[94:95] op_sel_hi:[1,0]
	s_nop 0
	v_fma_f32 v82, -v75, v75, v74
	v_add_f32_e32 v82, 0x3727c5ac, v82
	v_rsq_f32_e32 v82, v82
	v_pk_fma_f32 v[86:87], v[92:93], v[74:75], v[132:133] op_sel:[0,1,0] neg_lo:[1,0,0] neg_hi:[1,0,0]
	v_pk_fma_f32 v[94:95], v[198:199], v[74:75], v[134:135] op_sel:[0,1,0]
	v_pk_fma_f32 v[130:131], v[86:87], v[82:83], v[88:89] op_sel_hi:[1,0,1]
	v_pk_fma_f32 v[86:87], v[72:73], v[74:75], v[124:125] op_sel:[0,1,0] neg_lo:[1,0,0] neg_hi:[1,0,0]
	v_pk_fma_f32 v[128:129], v[94:95], v[82:83], v[90:91] op_sel_hi:[1,0,1]
	v_pk_fma_f32 v[94:95], v[196:197], v[74:75], v[126:127] op_sel:[0,1,0]
	v_pk_fma_f32 v[132:133], v[86:87], v[82:83], v[68:69] op_sel_hi:[1,0,1]
	v_pk_fma_f32 v[86:87], v[80:81], v[74:75], v[112:113] op_sel:[0,1,0] neg_lo:[1,0,0] neg_hi:[1,0,0]
	v_pk_fma_f32 v[126:127], v[94:95], v[82:83], v[70:71] op_sel_hi:[1,0,1]
	v_pk_fma_f32 v[94:95], v[194:195], v[74:75], v[114:115] op_sel:[0,1,0]
	v_pk_fma_f32 v[122:123], v[86:87], v[82:83], v[76:77] op_sel_hi:[1,0,1]
	v_pk_fma_f32 v[86:87], v[84:85], v[74:75], v[104:105] op_sel:[0,1,0] neg_lo:[1,0,0] neg_hi:[1,0,0]
	v_pk_fma_f32 v[74:75], v[192:193], v[74:75], v[106:107] op_sel:[0,1,0]
	v_pk_fma_f32 v[114:115], v[94:95], v[82:83], v[78:79] op_sel_hi:[1,0,1]
	v_pk_fma_f32 v[120:121], v[74:75], v[82:83], v[66:67] op_sel_hi:[1,0,1]
	v_pk_fma_f32 v[124:125], v[86:87], v[82:83], v[64:65] op_sel_hi:[1,0,1]
	v_cvt_f32_u32_e32 v74, v218
	v_cvt_f32_u32_e32 v75, v216
	v_cvt_f32_i32_e32 v82, v219
	v_cvt_f32_i32_e32 v83, v217
	v_pk_fma_f32 v[74:75], v[74:75], s[88:89], v[82:83] op_sel_hi:[1,0,1]
	s_nop 0
	v_pk_mul_f32 v[82:83], v[74:75], s[94:95] op_sel_hi:[1,0]
	s_nop 0
	v_fma_f32 v74, -v83, v83, v82
	v_add_f32_e32 v74, 0x3727c5ac, v74
	v_rsq_f32_e32 v94, v74
	v_pk_fma_f32 v[74:75], v[92:93], v[82:83], v[116:117] op_sel:[0,1,0] neg_lo:[1,0,0] neg_hi:[1,0,0]
	v_pk_fma_f32 v[86:87], v[198:199], v[82:83], v[118:119] op_sel:[0,1,0]
	v_pk_fma_f32 v[96:97], v[84:85], v[82:83], v[96:97] op_sel:[0,1,0] neg_lo:[1,0,0] neg_hi:[1,0,0]
	v_pk_fma_f32 v[104:105], v[86:87], v[94:95], v[90:91] op_sel_hi:[1,0,1]
	v_pk_fma_f32 v[112:113], v[74:75], v[94:95], v[88:89] op_sel_hi:[1,0,1]
	v_pk_fma_f32 v[74:75], v[72:73], v[82:83], v[108:109] op_sel:[0,1,0] neg_lo:[1,0,0] neg_hi:[1,0,0]
	v_pk_fma_f32 v[86:87], v[196:197], v[82:83], v[110:111] op_sel:[0,1,0]
	v_pk_fma_f32 v[108:109], v[74:75], v[94:95], v[68:69] op_sel_hi:[1,0,1]
	v_pk_fma_f32 v[106:107], v[86:87], v[94:95], v[70:71] op_sel_hi:[1,0,1]
	v_pk_fma_f32 v[86:87], v[80:81], v[82:83], v[100:101] op_sel:[0,1,0] neg_lo:[1,0,0] neg_hi:[1,0,0]
	v_pk_fma_f32 v[74:75], v[194:195], v[82:83], v[102:103] op_sel:[0,1,0]
	v_pk_fma_f32 v[82:83], v[192:193], v[82:83], v[98:99] op_sel:[0,1,0]
	v_pk_fma_f32 v[74:75], v[74:75], v[94:95], v[78:79] op_sel_hi:[1,0,1]
	v_pk_fma_f32 v[86:87], v[86:87], v[94:95], v[76:77] op_sel_hi:[1,0,1]
	v_pk_fma_f32 v[82:83], v[82:83], v[94:95], v[66:67] op_sel_hi:[1,0,1]
	v_pk_fma_f32 v[94:95], v[96:97], v[94:95], v[64:65] op_sel_hi:[1,0,1]
	v_cvt_f32_u32_e32 v201, v232
	v_cvt_f32_u32_e32 v200, v234
	v_cvt_f32_i32_e32 v102, v235
	v_cvt_f32_i32_e32 v103, v233
	v_cvt_f32_i32_e32 v99, v237
	v_cvt_f32_i32_e32 v97, v241
	v_pk_fma_f32 v[102:103], v[200:201], s[88:89], v[102:103] op_sel_hi:[1,0,1]
	s_nop 0
	v_pk_mul_f32 v[102:103], v[102:103], s[94:95] op_sel_hi:[1,0]
	s_nop 0
	v_fma_f32 v110, -v103, v103, v102
	v_add_f32_e32 v110, 0x3727c5ac, v110
	v_rsq_f32_e32 v110, v110
	v_pk_fma_f32 v[200:201], v[92:93], v[102:103], v[60:61] op_sel:[0,1,0] neg_lo:[1,0,0] neg_hi:[1,0,0]
	v_pk_fma_f32 v[60:61], v[198:199], v[102:103], v[62:63] op_sel:[0,1,0]
	v_pk_fma_f32 v[62:63], v[200:201], v[110:111], v[88:89] op_sel_hi:[1,0,1]
	v_pk_fma_f32 v[200:201], v[72:73], v[102:103], v[56:57] op_sel:[0,1,0] neg_lo:[1,0,0] neg_hi:[1,0,0]
	v_pk_fma_f32 v[56:57], v[196:197], v[102:103], v[58:59] op_sel:[0,1,0]
	v_pk_fma_f32 v[58:59], v[200:201], v[110:111], v[68:69] op_sel_hi:[1,0,1]
	v_pk_fma_f32 v[200:201], v[80:81], v[102:103], v[52:53] op_sel:[0,1,0] neg_lo:[1,0,0] neg_hi:[1,0,0]
	v_pk_fma_f32 v[52:53], v[194:195], v[102:103], v[54:55] op_sel:[0,1,0]
	v_pk_fma_f32 v[54:55], v[200:201], v[110:111], v[76:77] op_sel_hi:[1,0,1]
	v_pk_fma_f32 v[200:201], v[84:85], v[102:103], v[48:49] op_sel:[0,1,0] neg_lo:[1,0,0] neg_hi:[1,0,0]
	v_pk_fma_f32 v[48:49], v[192:193], v[102:103], v[50:51] op_sel:[0,1,0]
	v_cvt_f32_u32_e32 v102, v238
	v_cvt_f32_u32_e32 v103, v236
	v_cvt_f32_i32_e32 v98, v239
	v_pk_fma_f32 v[48:49], v[48:49], v[110:111], v[66:67] op_sel_hi:[1,0,1]
	v_pk_fma_f32 v[56:57], v[56:57], v[110:111], v[70:71] op_sel_hi:[1,0,1]
	v_pk_fma_f32 v[50:51], v[200:201], v[110:111], v[64:65] op_sel_hi:[1,0,1]
	v_pk_fma_f32 v[98:99], v[102:103], s[88:89], v[98:99] op_sel_hi:[1,0,1]
	v_pk_fma_f32 v[52:53], v[52:53], v[110:111], v[78:79] op_sel_hi:[1,0,1]
	v_pk_mul_f32 v[98:99], v[98:99], s[94:95] op_sel_hi:[1,0]
	v_pk_fma_f32 v[60:61], v[60:61], v[110:111], v[90:91] op_sel_hi:[1,0,1]
	v_fma_f32 v100, -v99, v99, v98
	v_add_f32_e32 v100, 0x3727c5ac, v100
	v_rsq_f32_e32 v100, v100
	v_pk_fma_f32 v[102:103], v[92:93], v[98:99], v[44:45] op_sel:[0,1,0] neg_lo:[1,0,0] neg_hi:[1,0,0]
	v_pk_fma_f32 v[44:45], v[198:199], v[98:99], v[46:47] op_sel:[0,1,0]
	v_max_f32_e32 v56, 0, v56
	v_pk_fma_f32 v[46:47], v[102:103], v[100:101], v[88:89] op_sel_hi:[1,0,1]
	v_pk_fma_f32 v[102:103], v[72:73], v[98:99], v[40:41] op_sel:[0,1,0] neg_lo:[1,0,0] neg_hi:[1,0,0]
	v_pk_fma_f32 v[40:41], v[196:197], v[98:99], v[42:43] op_sel:[0,1,0]
	v_pk_fma_f32 v[42:43], v[102:103], v[100:101], v[68:69] op_sel_hi:[1,0,1]
	v_pk_fma_f32 v[102:103], v[80:81], v[98:99], v[36:37] op_sel:[0,1,0] neg_lo:[1,0,0] neg_hi:[1,0,0]
	v_pk_fma_f32 v[36:37], v[194:195], v[98:99], v[38:39] op_sel:[0,1,0]
	v_pk_fma_f32 v[38:39], v[102:103], v[100:101], v[76:77] op_sel_hi:[1,0,1]
	v_pk_fma_f32 v[102:103], v[84:85], v[98:99], v[32:33] op_sel:[0,1,0] neg_lo:[1,0,0] neg_hi:[1,0,0]
	v_pk_fma_f32 v[32:33], v[192:193], v[98:99], v[34:35] op_sel:[0,1,0]
	v_cvt_f32_u32_e32 v98, v242
	v_cvt_f32_u32_e32 v99, v240
	v_cvt_f32_i32_e32 v96, v243
	v_pk_fma_f32 v[44:45], v[44:45], v[100:101], v[90:91] op_sel_hi:[1,0,1]
	v_pk_fma_f32 v[40:41], v[40:41], v[100:101], v[70:71] op_sel_hi:[1,0,1]
	v_pk_fma_f32 v[36:37], v[36:37], v[100:101], v[78:79] op_sel_hi:[1,0,1]
	v_pk_fma_f32 v[96:97], v[98:99], s[88:89], v[96:97] op_sel_hi:[1,0,1]
	v_pk_fma_f32 v[32:33], v[32:33], v[100:101], v[66:67] op_sel_hi:[1,0,1]
	v_pk_mul_f32 v[96:97], v[96:97], s[94:95] op_sel_hi:[1,0]
	v_pk_fma_f32 v[34:35], v[102:103], v[100:101], v[64:65] op_sel_hi:[1,0,1]
	v_fma_f32 v98, -v97, v97, v96
	v_add_f32_e32 v98, 0x3727c5ac, v98
	v_rsq_f32_e32 v98, v98
	v_pk_fma_f32 v[100:101], v[92:93], v[96:97], v[28:29] op_sel:[0,1,0] neg_lo:[1,0,0] neg_hi:[1,0,0]
	v_pk_fma_f32 v[28:29], v[198:199], v[96:97], v[30:31] op_sel:[0,1,0]
	v_max_f32_e32 v60, 0, v60
	v_pk_fma_f32 v[30:31], v[100:101], v[98:99], v[88:89] op_sel_hi:[1,0,1]
	v_pk_fma_f32 v[100:101], v[72:73], v[96:97], v[24:25] op_sel:[0,1,0] neg_lo:[1,0,0] neg_hi:[1,0,0]
	v_pk_fma_f32 v[24:25], v[196:197], v[96:97], v[26:27] op_sel:[0,1,0]
	v_pk_fma_f32 v[26:27], v[100:101], v[98:99], v[68:69] op_sel_hi:[1,0,1]
	v_pk_fma_f32 v[100:101], v[80:81], v[96:97], v[20:21] op_sel:[0,1,0] neg_lo:[1,0,0] neg_hi:[1,0,0]
	v_pk_fma_f32 v[20:21], v[194:195], v[96:97], v[22:23] op_sel:[0,1,0]
	v_pk_fma_f32 v[22:23], v[100:101], v[98:99], v[76:77] op_sel_hi:[1,0,1]
	v_pk_fma_f32 v[100:101], v[84:85], v[96:97], v[16:17] op_sel:[0,1,0] neg_lo:[1,0,0] neg_hi:[1,0,0]
	v_pk_fma_f32 v[16:17], v[192:193], v[96:97], v[18:19] op_sel:[0,1,0]
	v_pk_fma_f32 v[28:29], v[28:29], v[98:99], v[90:91] op_sel_hi:[1,0,1]
	v_pk_fma_f32 v[24:25], v[24:25], v[98:99], v[70:71] op_sel_hi:[1,0,1]
	v_pk_fma_f32 v[20:21], v[20:21], v[98:99], v[78:79] op_sel_hi:[1,0,1]
	v_pk_fma_f32 v[16:17], v[16:17], v[98:99], v[66:67] op_sel_hi:[1,0,1]
	v_pk_fma_f32 v[18:19], v[100:101], v[98:99], v[64:65] op_sel_hi:[1,0,1]
	v_cvt_f32_u32_e32 v96, v250
	v_cvt_f32_u32_e32 v97, v248
	v_cvt_f32_i32_e32 v98, v251
	v_cvt_f32_i32_e32 v99, v249
	v_max_f32_e32 v62, 0, v62
	v_max_f32_e32 v63, 0, v63
	v_mul_f32_e32 v60, v60, v60
	v_pk_fma_f32 v[96:97], v[96:97], s[88:89], v[98:99] op_sel_hi:[1,0,1]
	v_max_f32_e32 v57, 0, v57
	v_pk_mul_f32 v[96:97], v[96:97], s[94:95] op_sel_hi:[1,0]
	v_mul_f32_e32 v62, v62, v62
	v_fma_f32 v98, -v97, v97, v96
	v_add_f32_e32 v98, 0x3727c5ac, v98
	v_rsq_f32_e32 v98, v98
	v_pk_fma_f32 v[72:73], v[72:73], v[96:97], v[8:9] op_sel:[0,1,0] neg_lo:[1,0,0] neg_hi:[1,0,0]
	v_pk_fma_f32 v[8:9], v[196:197], v[96:97], v[10:11] op_sel:[0,1,0]
	v_mul_f32_e32 v63, v63, v63
	v_pk_fma_f32 v[10:11], v[72:73], v[98:99], v[68:69] op_sel_hi:[1,0,1]
	v_pk_fma_f32 v[68:69], v[80:81], v[96:97], v[4:5] op_sel:[0,1,0] neg_lo:[1,0,0] neg_hi:[1,0,0]
	v_pk_fma_f32 v[4:5], v[194:195], v[96:97], v[6:7] op_sel:[0,1,0]
	v_pk_fma_f32 v[6:7], v[68:69], v[98:99], v[76:77] op_sel_hi:[1,0,1]
	v_pk_fma_f32 v[68:69], v[84:85], v[96:97], v[0:1] op_sel:[0,1,0] neg_lo:[1,0,0] neg_hi:[1,0,0]
	v_pk_fma_f32 v[0:1], v[192:193], v[96:97], v[2:3] op_sel:[0,1,0]
	v_pk_fma_f32 v[8:9], v[8:9], v[98:99], v[70:71] op_sel_hi:[1,0,1]
	v_pk_fma_f32 v[0:1], v[0:1], v[98:99], v[66:67] op_sel_hi:[1,0,1]
	v_max_f32_e32 v67, 0, v190
	v_pk_fma_f32 v[2:3], v[68:69], v[98:99], v[64:65] op_sel_hi:[1,0,1]
	v_max_f32_e32 v66, 0, v188
	v_mul_f32_e32 v68, v67, v67
	v_max_f32_e32 v67, 0, v189
	v_max_f32_e32 v69, 0, v191
	v_max_f32_e32 v70, 0, v184
	v_max_f32_e32 v71, 0, v186
	v_lshlrev_b64 v[64:65], 14, v[180:181]
	v_mul_f32_e32 v66, v66, v66
	v_mul_f32_e32 v67, v67, v67
	v_mul_f32_e32 v69, v69, v69
	v_mul_f32_e32 v70, v70, v70
	v_mul_f32_e32 v71, v71, v71
	v_max_f32_e32 v72, 0, v185
	v_max_f32_e32 v73, 0, v187
	v_mul_f32_e32 v72, v72, v72
	v_mul_f32_e32 v73, v73, v73
	v_cvt_pk_bf16_f32 v66, v66, v67
	v_cvt_pk_bf16_f32 v67, v70, v72
	v_cvt_pk_bf16_f32 v68, v68, v69
	v_cvt_pk_bf16_f32 v69, v71, v73
	v_lshl_add_u64 v[64:65], s[36:37], 0, v[64:65]
	v_lshlrev_b64 v[70:71], 1, v[182:183]
	v_lshl_add_u64 v[64:65], v[64:65], 0, v[70:71]
	global_store_dwordx4 v[64:65], v[66:69], off nt
	v_max_f32_e32 v72, 0, v152
	v_max_f32_e32 v73, 0, v154
	v_max_f32_e32 v66, 0, v156
	v_max_f32_e32 v67, 0, v158
	v_mul_f32_e32 v66, v66, v66
	v_mul_f32_e32 v68, v67, v67
	v_max_f32_e32 v67, 0, v157
	v_max_f32_e32 v69, 0, v159
	v_mul_f32_e32 v67, v67, v67
	v_mul_f32_e32 v69, v69, v69
	v_max_f32_e32 v76, 0, v153
	v_max_f32_e32 v77, 0, v155
	v_cvt_pk_bf16_f32 v66, v66, v67
	v_mul_f32_e32 v72, v72, v72
	v_mul_f32_e32 v73, v73, v73
	v_mul_f32_e32 v76, v76, v76
	v_mul_f32_e32 v77, v77, v77
	v_cvt_pk_bf16_f32 v67, v72, v76
	v_cvt_pk_bf16_f32 v68, v68, v69
	v_cvt_pk_bf16_f32 v69, v73, v77
	global_store_dwordx4 v[64:65], v[66:69], off offset:256 nt
	v_pk_fma_f32 v[4:5], v[4:5], v[98:99], v[78:79] op_sel_hi:[1,0,1]
	v_max_f32_e32 v76, 0, v144
	v_or_b32_e32 v66, 16, v180
	v_ashrrev_i32_e32 v67, 31, v66
	v_lshlrev_b64 v[72:73], 14, v[66:67]
	v_max_f32_e32 v67, 0, v150
	v_max_f32_e32 v66, 0, v148
	v_mul_f32_e32 v68, v67, v67
	v_max_f32_e32 v67, 0, v149
	v_mul_f32_e32 v66, v66, v66
	v_max_f32_e32 v69, 0, v151
	v_mul_f32_e32 v67, v67, v67
	v_max_f32_e32 v78, 0, v145
	v_lshl_add_u64 v[72:73], s[36:37], 0, v[72:73]
	v_mul_f32_e32 v69, v69, v69
	v_max_f32_e32 v77, 0, v146
	v_mul_f32_e32 v76, v76, v76
	v_max_f32_e32 v79, 0, v147
	v_mul_f32_e32 v78, v78, v78
	v_cvt_pk_bf16_f32 v66, v66, v67
	v_cvt_pk_bf16_f32 v67, v76, v78
	v_lshl_add_u64 v[72:73], v[72:73], 0, v[70:71]
	v_mul_f32_e32 v77, v77, v77
	v_mul_f32_e32 v79, v79, v79
	v_cvt_pk_bf16_f32 v68, v68, v69
	v_cvt_pk_bf16_f32 v69, v77, v79
	global_store_dwordx4 v[72:73], v[66:69], off nt
	v_max_f32_e32 v76, 0, v136
	v_max_f32_e32 v77, 0, v138
	v_max_f32_e32 v66, 0, v140
	v_max_f32_e32 v67, 0, v142
	v_mul_f32_e32 v66, v66, v66
	v_mul_f32_e32 v68, v67, v67
	v_max_f32_e32 v67, 0, v141
	v_max_f32_e32 v69, 0, v143
	v_mul_f32_e32 v67, v67, v67
	v_mul_f32_e32 v69, v69, v69
	v_max_f32_e32 v78, 0, v137
	v_max_f32_e32 v79, 0, v139
	v_cvt_pk_bf16_f32 v66, v66, v67
	v_mul_f32_e32 v76, v76, v76
	v_mul_f32_e32 v77, v77, v77
	v_mul_f32_e32 v78, v78, v78
	v_mul_f32_e32 v79, v79, v79
	v_cvt_pk_bf16_f32 v67, v76, v78
	v_cvt_pk_bf16_f32 v68, v68, v69
	v_cvt_pk_bf16_f32 v69, v77, v79
	global_store_dwordx4 v[72:73], v[66:69], off offset:256 nt
	v_max_f32_e32 v76, 0, v128
	v_max_f32_e32 v78, 0, v129
	v_or_b32_e32 v66, 32, v180
	v_ashrrev_i32_e32 v67, 31, v66
	v_lshlrev_b64 v[72:73], 14, v[66:67]
	v_max_f32_e32 v67, 0, v132
	v_max_f32_e32 v66, 0, v130
	v_mul_f32_e32 v68, v67, v67
	v_max_f32_e32 v67, 0, v131
	v_mul_f32_e32 v66, v66, v66
	v_max_f32_e32 v69, 0, v133
	v_mul_f32_e32 v67, v67, v67
	v_lshl_add_u64 v[72:73], s[36:37], 0, v[72:73]
	v_mul_f32_e32 v69, v69, v69
	v_max_f32_e32 v77, 0, v126
	v_mul_f32_e32 v76, v76, v76
	v_max_f32_e32 v79, 0, v127
	v_mul_f32_e32 v78, v78, v78
	v_cvt_pk_bf16_f32 v66, v66, v67
	v_cvt_pk_bf16_f32 v67, v76, v78
	v_lshl_add_u64 v[72:73], v[72:73], 0, v[70:71]
	v_mul_f32_e32 v77, v77, v77
	v_mul_f32_e32 v79, v79, v79
	v_cvt_pk_bf16_f32 v68, v68, v69
	v_cvt_pk_bf16_f32 v69, v77, v79
	global_store_dwordx4 v[72:73], v[66:69], off nt
	v_max_f32_e32 v76, 0, v114
	v_max_f32_e32 v77, 0, v120
	v_max_f32_e32 v66, 0, v122
	v_max_f32_e32 v67, 0, v124
	v_mul_f32_e32 v66, v66, v66
	v_mul_f32_e32 v68, v67, v67
	v_max_f32_e32 v67, 0, v123
	v_max_f32_e32 v69, 0, v125
	v_mul_f32_e32 v67, v67, v67
	v_mul_f32_e32 v69, v69, v69
	v_max_f32_e32 v78, 0, v115
	v_max_f32_e32 v79, 0, v121
	v_cvt_pk_bf16_f32 v66, v66, v67
	v_mul_f32_e32 v76, v76, v76
	v_mul_f32_e32 v77, v77, v77
	v_mul_f32_e32 v78, v78, v78
	v_mul_f32_e32 v79, v79, v79
	v_cvt_pk_bf16_f32 v67, v76, v78
	v_cvt_pk_bf16_f32 v68, v68, v69
	v_cvt_pk_bf16_f32 v69, v77, v79
	global_store_dwordx4 v[72:73], v[66:69], off offset:256 nt
	v_max_f32_e32 v76, 0, v104
	v_max_f32_e32 v78, 0, v105
	v_or_b32_e32 v66, 48, v180
	v_ashrrev_i32_e32 v67, 31, v66
	v_lshlrev_b64 v[72:73], 14, v[66:67]
	v_max_f32_e32 v67, 0, v108
	v_max_f32_e32 v66, 0, v112
	v_mul_f32_e32 v68, v67, v67
	v_max_f32_e32 v67, 0, v113
	v_mul_f32_e32 v66, v66, v66
	v_max_f32_e32 v69, 0, v109
	v_mul_f32_e32 v67, v67, v67
	v_lshl_add_u64 v[72:73], s[36:37], 0, v[72:73]
	v_mul_f32_e32 v69, v69, v69
	v_max_f32_e32 v77, 0, v106
	v_mul_f32_e32 v76, v76, v76
	v_max_f32_e32 v79, 0, v107
	v_mul_f32_e32 v78, v78, v78
	v_cvt_pk_bf16_f32 v66, v66, v67
	v_cvt_pk_bf16_f32 v67, v76, v78
	v_lshl_add_u64 v[70:71], v[72:73], 0, v[70:71]
	v_mul_f32_e32 v77, v77, v77
	v_mul_f32_e32 v79, v79, v79
	v_cvt_pk_bf16_f32 v68, v68, v69
	v_cvt_pk_bf16_f32 v69, v77, v79
	global_store_dwordx4 v[70:71], v[66:69], off nt
	v_max_f32_e32 v72, 0, v74
	v_max_f32_e32 v73, 0, v82
	v_max_f32_e32 v66, 0, v86
	v_max_f32_e32 v67, 0, v94
	v_mul_f32_e32 v66, v66, v66
	v_mul_f32_e32 v68, v67, v67
	v_max_f32_e32 v67, 0, v87
	v_max_f32_e32 v69, 0, v95
	v_mul_f32_e32 v67, v67, v67
	v_mul_f32_e32 v69, v69, v69
	v_max_f32_e32 v74, 0, v75
	v_max_f32_e32 v75, 0, v83
	v_cvt_pk_bf16_f32 v66, v66, v67
	v_mul_f32_e32 v72, v72, v72
	v_mul_f32_e32 v73, v73, v73
	v_mul_f32_e32 v74, v74, v74
	v_mul_f32_e32 v75, v75, v75
	v_cvt_pk_bf16_f32 v67, v72, v74
	v_cvt_pk_bf16_f32 v68, v68, v69
	v_cvt_pk_bf16_f32 v69, v73, v75
	global_store_dwordx4 v[70:71], v[66:69], off offset:256 nt
	v_max_f32_e32 v58, 0, v58
	v_max_f32_e32 v59, 0, v59
	v_mul_f32_e32 v66, v56, v56
	v_max_f32_e32 v56, 0, v61
	v_mul_f32_e32 v61, v56, v56
	v_mul_f32_e32 v67, v57, v57
	v_cvt_pk_bf16_f32 v56, v62, v63
	v_cvt_pk_bf16_f32 v57, v60, v61
	v_lshl_add_u64 v[60:61], v[64:65], 0, s[0:1]
	s_mov_b32 s0, 0x200000
	v_add_co_u32_e32 v62, vcc, s0, v64
	v_mul_f32_e32 v58, v58, v58
	v_mul_f32_e32 v59, v59, v59
	v_addc_co_u32_e32 v63, vcc, 0, v65, vcc
	v_max_f32_e32 v48, 0, v48
	v_cvt_pk_bf16_f32 v58, v58, v59
	v_cvt_pk_bf16_f32 v59, v66, v67
	global_store_dwordx4 v[62:63], v[56:59], off nt
	v_max_f32_e32 v54, 0, v54
	v_max_f32_e32 v50, 0, v50
	v_max_f32_e32 v55, 0, v55
	v_max_f32_e32 v51, 0, v51
	v_mul_f32_e32 v56, v48, v48
	v_max_f32_e32 v48, 0, v53
	v_mul_f32_e32 v54, v54, v54
	v_mul_f32_e32 v50, v50, v50
	v_mul_f32_e32 v55, v55, v55
	v_mul_f32_e32 v51, v51, v51
	v_max_f32_e32 v52, 0, v52
	v_max_f32_e32 v49, 0, v49
	v_mul_f32_e32 v53, v48, v48
	v_cvt_pk_bf16_f32 v48, v54, v55
	v_max_f32_e32 v40, 0, v40
	v_mul_f32_e32 v52, v52, v52
	v_mul_f32_e32 v57, v49, v49
	v_cvt_pk_bf16_f32 v49, v52, v53
	v_cvt_pk_bf16_f32 v50, v50, v51
	v_cvt_pk_bf16_f32 v51, v56, v57
	global_store_dwordx4 v[60:61], v[48:51], off offset:256 nt
	v_max_f32_e32 v44, 0, v44
	v_max_f32_e32 v46, 0, v46
	v_mul_f32_e32 v48, v40, v40
	v_max_f32_e32 v40, 0, v45
	v_max_f32_e32 v47, 0, v47
	v_mul_f32_e32 v44, v44, v44
	v_max_f32_e32 v41, 0, v41
	v_mul_f32_e32 v45, v40, v40
	s_mov_b64 s[0:1], 0x240000
	v_mul_f32_e32 v46, v46, v46
	v_mul_f32_e32 v47, v47, v47
	v_mul_f32_e32 v49, v41, v41
	v_cvt_pk_bf16_f32 v40, v46, v47
	v_cvt_pk_bf16_f32 v41, v44, v45
	v_lshl_add_u64 v[44:45], v[64:65], 0, s[0:1]
	s_mov_b32 s0, 0x240000
	v_max_f32_e32 v42, 0, v42
	v_max_f32_e32 v43, 0, v43
	v_add_co_u32_e32 v46, vcc, s0, v64
	v_mul_f32_e32 v42, v42, v42
	v_mul_f32_e32 v43, v43, v43
	v_addc_co_u32_e32 v47, vcc, 0, v65, vcc
	v_max_f32_e32 v32, 0, v32
	v_cvt_pk_bf16_f32 v42, v42, v43
	v_cvt_pk_bf16_f32 v43, v48, v49
	global_store_dwordx4 v[46:47], v[40:43], off nt
	v_max_f32_e32 v38, 0, v38
	v_max_f32_e32 v34, 0, v34
	v_max_f32_e32 v39, 0, v39
	v_max_f32_e32 v35, 0, v35
	v_mul_f32_e32 v40, v32, v32
	v_max_f32_e32 v32, 0, v37
	v_mul_f32_e32 v38, v38, v38
	v_mul_f32_e32 v34, v34, v34
	v_mul_f32_e32 v39, v39, v39
	v_mul_f32_e32 v35, v35, v35
	v_max_f32_e32 v36, 0, v36
	v_max_f32_e32 v33, 0, v33
	v_mul_f32_e32 v37, v32, v32
	v_cvt_pk_bf16_f32 v32, v38, v39
	v_max_f32_e32 v24, 0, v24
	v_mul_f32_e32 v36, v36, v36
	v_mul_f32_e32 v41, v33, v33
	v_cvt_pk_bf16_f32 v33, v36, v37
	v_cvt_pk_bf16_f32 v34, v34, v35
	v_cvt_pk_bf16_f32 v35, v40, v41
	global_store_dwordx4 v[44:45], v[32:35], off offset:256 nt
	v_max_f32_e32 v28, 0, v28
	v_max_f32_e32 v30, 0, v30
	v_mul_f32_e32 v32, v24, v24
	v_max_f32_e32 v24, 0, v29
	v_max_f32_e32 v31, 0, v31
	v_mul_f32_e32 v28, v28, v28
	v_max_f32_e32 v25, 0, v25
	v_mul_f32_e32 v29, v24, v24
	s_mov_b64 s[0:1], 0x280000
	v_mul_f32_e32 v30, v30, v30
	v_mul_f32_e32 v31, v31, v31
	v_mul_f32_e32 v33, v25, v25
	v_cvt_pk_bf16_f32 v24, v30, v31
	v_cvt_pk_bf16_f32 v25, v28, v29
	v_lshl_add_u64 v[28:29], v[64:65], 0, s[0:1]
	s_mov_b32 s0, 0x280000
	v_max_f32_e32 v26, 0, v26
	v_max_f32_e32 v27, 0, v27
	v_add_co_u32_e32 v30, vcc, s0, v64
	v_mul_f32_e32 v26, v26, v26
	v_mul_f32_e32 v27, v27, v27
	v_addc_co_u32_e32 v31, vcc, 0, v65, vcc
	v_max_f32_e32 v16, 0, v16
	v_pk_fma_f32 v[92:93], v[92:93], v[96:97], v[12:13] op_sel:[0,1,0] neg_lo:[1,0,0] neg_hi:[1,0,0]
	v_pk_fma_f32 v[12:13], v[198:199], v[96:97], v[14:15] op_sel:[0,1,0]
	v_cvt_pk_bf16_f32 v26, v26, v27
	v_cvt_pk_bf16_f32 v27, v32, v33
	global_store_dwordx4 v[30:31], v[24:27], off nt
	v_max_f32_e32 v22, 0, v22
	v_max_f32_e32 v18, 0, v18
	v_max_f32_e32 v23, 0, v23
	v_max_f32_e32 v19, 0, v19
	v_mul_f32_e32 v24, v16, v16
	v_max_f32_e32 v16, 0, v21
	v_pk_fma_f32 v[12:13], v[12:13], v[98:99], v[90:91] op_sel_hi:[1,0,1]
	v_mul_f32_e32 v22, v22, v22
	v_mul_f32_e32 v18, v18, v18
	v_mul_f32_e32 v23, v23, v23
	v_mul_f32_e32 v19, v19, v19
	v_max_f32_e32 v20, 0, v20
	v_max_f32_e32 v17, 0, v17
	v_mul_f32_e32 v21, v16, v16
	v_cvt_pk_bf16_f32 v16, v22, v23
	v_max_f32_e32 v8, 0, v8
	v_pk_fma_f32 v[14:15], v[92:93], v[98:99], v[88:89] op_sel_hi:[1,0,1]
	v_mul_f32_e32 v20, v20, v20
	v_mul_f32_e32 v25, v17, v17
	v_cvt_pk_bf16_f32 v17, v20, v21
	v_cvt_pk_bf16_f32 v18, v18, v19
	v_cvt_pk_bf16_f32 v19, v24, v25
	global_store_dwordx4 v[28:29], v[16:19], off offset:256 nt
	v_max_f32_e32 v12, 0, v12
	v_max_f32_e32 v14, 0, v14
	v_mul_f32_e32 v16, v8, v8
	v_max_f32_e32 v8, 0, v13
	v_max_f32_e32 v15, 0, v15
	v_mul_f32_e32 v12, v12, v12
	v_max_f32_e32 v9, 0, v9
	v_mul_f32_e32 v13, v8, v8
	s_mov_b64 s[0:1], 0x2c0000
	v_mul_f32_e32 v14, v14, v14
	v_mul_f32_e32 v15, v15, v15
	v_mul_f32_e32 v17, v9, v9
	v_cvt_pk_bf16_f32 v8, v14, v15
	v_cvt_pk_bf16_f32 v9, v12, v13
	v_lshl_add_u64 v[12:13], v[64:65], 0, s[0:1]
	s_mov_b32 s0, 0x2c0000
	v_max_f32_e32 v10, 0, v10
	v_max_f32_e32 v11, 0, v11
	v_add_co_u32_e32 v14, vcc, s0, v64
	v_mul_f32_e32 v10, v10, v10
	v_mul_f32_e32 v11, v11, v11
	v_addc_co_u32_e32 v15, vcc, 0, v65, vcc
	v_max_f32_e32 v2, 0, v2
	v_max_f32_e32 v3, 0, v3
	v_max_f32_e32 v0, 0, v0
	v_cvt_pk_bf16_f32 v10, v10, v11
	v_cvt_pk_bf16_f32 v11, v16, v17
	global_store_dwordx4 v[14:15], v[8:11], off nt
	v_max_f32_e32 v6, 0, v6
	v_mul_f32_e32 v2, v2, v2
	v_max_f32_e32 v7, 0, v7
	v_mul_f32_e32 v3, v3, v3
	v_max_f32_e32 v4, 0, v4
	v_mul_f32_e32 v8, v0, v0
	v_max_f32_e32 v0, 0, v5
	v_max_f32_e32 v1, 0, v1
	s_and_b64 vcc, exec, s[6:7]
	s_mov_b64 s[0:1], s[76:77]
	v_mul_f32_e32 v6, v6, v6
	v_mul_f32_e32 v7, v7, v7
	v_mul_f32_e32 v4, v4, v4
	v_mul_f32_e32 v5, v0, v0
	v_mul_f32_e32 v9, v1, v1
	v_cvt_pk_bf16_f32 v0, v6, v7
	v_cvt_pk_bf16_f32 v1, v4, v5
	v_cvt_pk_bf16_f32 v2, v2, v3
	v_cvt_pk_bf16_f32 v3, v8, v9
	global_store_dwordx4 v[12:13], v[0:3], off offset:256 nt
	s_cbranch_vccz .LBB0_1049
	s_waitcnt vmcnt(0)
	v_readlane_b32 s38, v255, 9
	s_cmpk_gt_u32 s18, 0xff
	v_readlane_b32 s39, v255, 10
	s_cbranch_scc1 .LBB0_1060
	s_barrier

.LBB0_1227:
	s_barrier
	s_add_u32 s67, s4, 0xffe00080
	s_addc_u32 s68, s5, -1
	s_add_i32 s71, 0, 0x10000
	v_add_u32_e32 v60, s71, v249
	ds_read_b128 v[48:51], v60
	ds_read_b128 v[52:55], v60 offset:1024
	ds_read_b128 v[56:59], v60 offset:2048
	ds_read_b128 v[60:63], v60 offset:3072
	s_cmpk_eq_i32 s66, 0x7c
	s_cselect_b32 s75, s12, s68
	s_cselect_b32 s74, s13, s67
	s_cselect_b32 s73, s14, s47
	s_cselect_b32 s72, s15, s45
	ds_read_b128 v[64:67], v251
	ds_read_b128 v[68:71], v251 offset:1024
	ds_read_b128 v[72:75], v251 offset:2048
	ds_read_b128 v[76:79], v251 offset:3072
	ds_read_b128 v[176:179], v251 offset:4096
	ds_read_b128 v[180:183], v251 offset:5120
	ds_read_b128 v[184:187], v251 offset:6144
	ds_read_b128 v[188:191], v251 offset:7168
	s_waitcnt lgkmcnt(8)
	s_barrier
	s_waitcnt lgkmcnt(0)
	s_waitcnt lgkmcnt(0)
	v_mfma_f32_16x16x32_bf16 v[156:159], v[48:51], v[64:67], v[156:159]
	v_mfma_f32_16x16x32_bf16 v[152:155], v[56:59], v[64:67], v[152:155]
	v_mfma_f32_16x16x32_bf16 v[140:143], v[48:51], v[72:75], v[140:143]
	v_mfma_f32_16x16x32_bf16 v[136:139], v[56:59], v[72:75], v[136:139]
	v_mfma_f32_16x16x32_bf16 v[124:127], v[48:51], v[176:179], v[124:127]
	v_mfma_f32_16x16x32_bf16 v[120:123], v[56:59], v[176:179], v[120:123]
	v_mfma_f32_16x16x32_bf16 v[108:111], v[48:51], v[184:187], v[108:111]
	v_mfma_f32_16x16x32_bf16 v[104:107], v[56:59], v[184:187], v[104:107]
	v_mfma_f32_16x16x32_bf16 v[156:159], v[52:55], v[68:71], v[156:159]
	v_mfma_f32_16x16x32_bf16 v[152:155], v[60:63], v[68:71], v[152:155]
	v_mfma_f32_16x16x32_bf16 v[140:143], v[52:55], v[76:79], v[140:143]
	v_mfma_f32_16x16x32_bf16 v[136:139], v[60:63], v[76:79], v[136:139]
	v_mfma_f32_16x16x32_bf16 v[124:127], v[52:55], v[180:183], v[124:127]
	v_mfma_f32_16x16x32_bf16 v[120:123], v[60:63], v[180:183], v[120:123]
	v_mfma_f32_16x16x32_bf16 v[108:111], v[52:55], v[188:191], v[108:111]
	v_mfma_f32_16x16x32_bf16 v[104:107], v[60:63], v[188:191], v[104:107]
	s_barrier
	v_lshl_add_u64 v[192:193], s[4:5], 0, v[172:173]
	s_add_i32 m0, s22, 0xc000
	s_nop 0
	global_load_lds_dwordx4 v[192:193], off
	v_lshl_add_u64 v[192:193], s[4:5], 0, v[174:175]
	s_add_i32 m0, s22, 0xe000
	s_nop 0
	global_load_lds_dwordx4 v[192:193], off
	s_add_i32 s67, 0, 0x14000
	s_add_i32 s68, s71, s21
	v_add_u32_e32 v204, s67, v249
	v_lshl_add_u64 v[216:217], s[72:73], 0, v[160:161]
	s_mov_b32 m0, s68
	ds_read_b128 v[192:195], v204
	ds_read_b128 v[196:199], v204 offset:1024
	ds_read_b128 v[200:203], v204 offset:2048
	ds_read_b128 v[204:207], v204 offset:3072
	global_load_lds_dwordx4 v[216:217], off
	v_lshl_add_u64 v[218:219], s[72:73], 0, v[170:171]
	s_add_i32 m0, s68, 0x2000
	s_nop 0
	global_load_lds_dwordx4 v[218:219], off
	s_barrier
	s_waitcnt lgkmcnt(0)
	s_waitcnt lgkmcnt(0)
	v_mfma_f32_16x16x32_bf16 v[148:151], v[192:195], v[64:67], v[148:151]
	v_mfma_f32_16x16x32_bf16 v[64:67], v[200:203], v[64:67], v[144:147]
	v_mfma_f32_16x16x32_bf16 v[148:151], v[196:199], v[68:71], v[148:151]
	v_mfma_f32_16x16x32_bf16 v[64:67], v[204:207], v[68:71], v[64:67]
	v_mfma_f32_16x16x32_bf16 v[68:71], v[192:195], v[72:75], v[132:135]
	v_mfma_f32_16x16x32_bf16 v[72:75], v[200:203], v[72:75], v[128:131]
	v_mfma_f32_16x16x32_bf16 v[112:115], v[200:203], v[176:179], v[112:115]
	v_mfma_f32_16x16x32_bf16 v[100:103], v[192:195], v[184:187], v[100:103]
	v_mfma_f32_16x16x32_bf16 v[96:99], v[200:203], v[184:187], v[96:99]
	v_mfma_f32_16x16x32_bf16 v[68:71], v[196:199], v[76:79], v[68:71]
	v_mfma_f32_16x16x32_bf16 v[72:75], v[204:207], v[76:79], v[72:75]
	v_mfma_f32_16x16x32_bf16 v[76:79], v[192:195], v[176:179], v[116:119]
	v_mfma_f32_16x16x32_bf16 v[112:115], v[204:207], v[180:183], v[112:115]
	v_mfma_f32_16x16x32_bf16 v[100:103], v[196:199], v[188:191], v[100:103]
	v_mfma_f32_16x16x32_bf16 v[96:99], v[204:207], v[188:191], v[96:99]
	v_mfma_f32_16x16x32_bf16 v[76:79], v[196:199], v[180:183], v[76:79]
	s_mov_b32 m0, s22
	v_lshl_add_u64 v[220:221], s[74:75], 0, v[160:161]
	s_barrier
	ds_read_b128 v[116:119], v251 offset:16384
	ds_read_b128 v[128:131], v251 offset:17408
	ds_read_b128 v[132:135], v251 offset:18432
	ds_read_b128 v[144:147], v251 offset:19456
	ds_read_b128 v[176:179], v251 offset:20480
	ds_read_b128 v[180:183], v251 offset:21504
	ds_read_b128 v[184:187], v251 offset:22528
	ds_read_b128 v[188:191], v251 offset:23552
	global_load_lds_dwordx4 v[220:221], off
	v_lshl_add_u64 v[222:223], s[74:75], 0, v[170:171]
	s_mov_b32 m0, s23
	s_nop 0
	global_load_lds_dwordx4 v[222:223], off
	s_barrier
	s_waitcnt lgkmcnt(0)
	s_waitcnt lgkmcnt(0)
	v_mfma_f32_16x16x32_bf16 v[92:95], v[48:51], v[116:119], v[92:95]
	v_mfma_f32_16x16x32_bf16 v[88:91], v[56:59], v[116:119], v[88:91]
	v_mfma_f32_16x16x32_bf16 v[44:47], v[48:51], v[132:135], v[44:47]
	v_mfma_f32_16x16x32_bf16 v[40:43], v[56:59], v[132:135], v[40:43]
	v_mfma_f32_16x16x32_bf16 v[28:31], v[48:51], v[176:179], v[28:31]
	v_mfma_f32_16x16x32_bf16 v[24:27], v[56:59], v[176:179], v[24:27]
	v_mfma_f32_16x16x32_bf16 v[12:15], v[48:51], v[184:187], v[12:15]
	v_mfma_f32_16x16x32_bf16 v[8:11], v[56:59], v[184:187], v[8:11]
	v_mfma_f32_16x16x32_bf16 v[92:95], v[52:55], v[128:131], v[92:95]
	v_mfma_f32_16x16x32_bf16 v[88:91], v[60:63], v[128:131], v[88:91]
	v_mfma_f32_16x16x32_bf16 v[44:47], v[52:55], v[144:147], v[44:47]
	v_mfma_f32_16x16x32_bf16 v[40:43], v[60:63], v[144:147], v[40:43]
	v_mfma_f32_16x16x32_bf16 v[28:31], v[52:55], v[180:183], v[28:31]
	v_mfma_f32_16x16x32_bf16 v[24:27], v[60:63], v[180:183], v[24:27]
	v_mfma_f32_16x16x32_bf16 v[12:15], v[52:55], v[188:191], v[12:15]
	v_mfma_f32_16x16x32_bf16 v[8:11], v[60:63], v[188:191], v[8:11]
	s_barrier
	s_add_u32 s76, s72, 0x200000
	s_addc_u32 s77, s73, 0
	s_add_i32 s67, s67, s21
	v_lshl_add_u64 v[48:49], s[76:77], 0, v[160:161]
	s_mov_b32 m0, s67
	s_nop 0
	global_load_lds_dwordx4 v[48:49], off
	v_lshl_add_u64 v[48:49], s[76:77], 0, v[170:171]
	s_add_i32 m0, s67, 0x2000
	s_nop 0
	global_load_lds_dwordx4 v[48:49], off
	s_waitcnt vmcnt(6)
	s_barrier
	v_mfma_f32_16x16x32_bf16 v[36:39], v[192:195], v[132:135], v[36:39]
	v_mfma_f32_16x16x32_bf16 v[32:35], v[200:203], v[132:135], v[32:35]
	v_mfma_f32_16x16x32_bf16 v[20:23], v[192:195], v[176:179], v[20:23]
	v_mfma_f32_16x16x32_bf16 v[16:19], v[200:203], v[176:179], v[16:19]
	v_mfma_f32_16x16x32_bf16 v[4:7], v[192:195], v[184:187], v[4:7]
	v_mfma_f32_16x16x32_bf16 v[0:3], v[200:203], v[184:187], v[0:3]
	v_mfma_f32_16x16x32_bf16 v[48:51], v[192:195], v[116:119], v[84:87]
	v_mfma_f32_16x16x32_bf16 v[52:55], v[200:203], v[116:119], v[80:83]
	v_mfma_f32_16x16x32_bf16 v[36:39], v[196:199], v[144:147], v[36:39]
	v_mfma_f32_16x16x32_bf16 v[32:35], v[204:207], v[144:147], v[32:35]
	v_mfma_f32_16x16x32_bf16 v[20:23], v[196:199], v[180:183], v[20:23]
	v_mfma_f32_16x16x32_bf16 v[16:19], v[204:207], v[180:183], v[16:19]
	v_mfma_f32_16x16x32_bf16 v[4:7], v[196:199], v[188:191], v[4:7]
	v_mfma_f32_16x16x32_bf16 v[0:3], v[204:207], v[188:191], v[0:3]
	v_mfma_f32_16x16x32_bf16 v[48:51], v[196:199], v[128:131], v[48:51]
	v_mfma_f32_16x16x32_bf16 v[52:55], v[204:207], v[128:131], v[52:55]
	s_add_i32 s67, 0, 0x18000
	v_add_u32_e32 v84, s67, v249
	s_barrier
	ds_read_b128 v[56:59], v84
	ds_read_b128 v[60:63], v84 offset:1024
	ds_read_b128 v[80:83], v84 offset:2048
	ds_read_b128 v[84:87], v84 offset:3072
	ds_read_b128 v[116:119], v251 offset:32768
	ds_read_b128 v[128:131], v251 offset:33792
	ds_read_b128 v[176:179], v251 offset:34816
	ds_read_b128 v[180:183], v251 offset:35840
	ds_read_b128 v[184:187], v251 offset:36864
	ds_read_b128 v[188:191], v251 offset:37888
	ds_read_b128 v[192:195], v251 offset:38912
	ds_read_b128 v[196:199], v251 offset:39936
	s_waitcnt lgkmcnt(8)
	s_barrier
	s_waitcnt lgkmcnt(0)
	s_waitcnt lgkmcnt(0)
	v_mfma_f32_16x16x32_bf16 v[132:135], v[56:59], v[116:119], v[156:159]
	v_mfma_f32_16x16x32_bf16 v[156:159], v[60:63], v[128:131], v[132:135]
	v_mfma_f32_16x16x32_bf16 v[132:135], v[80:83], v[116:119], v[152:155]
	v_mfma_f32_16x16x32_bf16 v[152:155], v[84:87], v[128:131], v[132:135]
	v_mfma_f32_16x16x32_bf16 v[132:135], v[56:59], v[176:179], v[140:143]
	v_mfma_f32_16x16x32_bf16 v[140:143], v[60:63], v[180:183], v[132:135]
	v_mfma_f32_16x16x32_bf16 v[132:135], v[80:83], v[176:179], v[136:139]
	v_mfma_f32_16x16x32_bf16 v[124:127], v[56:59], v[184:187], v[124:127]
	v_mfma_f32_16x16x32_bf16 v[120:123], v[80:83], v[184:187], v[120:123]
	v_mfma_f32_16x16x32_bf16 v[108:111], v[56:59], v[192:195], v[108:111]
	v_mfma_f32_16x16x32_bf16 v[104:107], v[80:83], v[192:195], v[104:107]
	v_mfma_f32_16x16x32_bf16 v[136:139], v[84:87], v[180:183], v[132:135]
	v_mfma_f32_16x16x32_bf16 v[124:127], v[60:63], v[188:191], v[124:127]
	v_mfma_f32_16x16x32_bf16 v[120:123], v[84:87], v[188:191], v[120:123]
	v_mfma_f32_16x16x32_bf16 v[108:111], v[60:63], v[196:199], v[108:111]
	v_mfma_f32_16x16x32_bf16 v[104:107], v[84:87], v[196:199], v[104:107]
	s_barrier
	s_add_u32 s74, s74, 0x200000
	s_addc_u32 s75, s75, 0
	v_lshl_add_u64 v[132:133], s[74:75], 0, v[160:161]
	s_mov_b32 m0, s24
	s_nop 0
	global_load_lds_dwordx4 v[132:133], off
	v_lshl_add_u64 v[132:133], s[74:75], 0, v[170:171]
	s_mov_b32 m0, s25
	s_nop 0
	global_load_lds_dwordx4 v[132:133], off
	s_add_i32 s68, 0, 0x1c000
	v_add_u32_e32 v132, s68, v249
	s_add_i32 s67, s67, s21
	ds_read_b128 v[200:203], v132
	ds_read_b128 v[204:207], v132 offset:1024
	ds_read_b128 v[208:211], v132 offset:2048
	ds_read_b128 v[212:215], v132 offset:3072
	v_lshl_add_u64 v[132:133], v[216:217], 0, s[92:93]
	s_mov_b32 m0, s67
	s_nop 0
	global_load_lds_dwordx4 v[132:133], off
	v_lshl_add_u64 v[132:133], v[218:219], 0, s[92:93]
	s_add_i32 m0, s67, 0x2000
	s_nop 0
	global_load_lds_dwordx4 v[132:133], off
	s_barrier
	s_waitcnt lgkmcnt(0)
	s_waitcnt lgkmcnt(0)
	v_mfma_f32_16x16x32_bf16 v[64:67], v[208:211], v[116:119], v[64:67]
	v_mfma_f32_16x16x32_bf16 v[132:135], v[200:203], v[116:119], v[148:151]
	v_mfma_f32_16x16x32_bf16 v[144:147], v[212:215], v[128:131], v[64:67]
	v_mfma_f32_16x16x32_bf16 v[64:67], v[200:203], v[176:179], v[68:71]
	v_mfma_f32_16x16x32_bf16 v[148:151], v[204:207], v[128:131], v[132:135]
	v_mfma_f32_16x16x32_bf16 v[132:135], v[204:207], v[180:183], v[64:67]
	v_mfma_f32_16x16x32_bf16 v[64:67], v[208:211], v[176:179], v[72:75]
	v_mfma_f32_16x16x32_bf16 v[128:131], v[212:215], v[180:183], v[64:67]
	v_mfma_f32_16x16x32_bf16 v[64:67], v[200:203], v[184:187], v[76:79]
	v_mfma_f32_16x16x32_bf16 v[116:119], v[204:207], v[188:191], v[64:67]
	v_mfma_f32_16x16x32_bf16 v[64:67], v[208:211], v[184:187], v[112:115]
	v_mfma_f32_16x16x32_bf16 v[112:115], v[212:215], v[188:191], v[64:67]
	v_mfma_f32_16x16x32_bf16 v[64:67], v[200:203], v[192:195], v[100:103]
	v_mfma_f32_16x16x32_bf16 v[100:103], v[204:207], v[196:199], v[64:67]
	v_mfma_f32_16x16x32_bf16 v[64:67], v[208:211], v[192:195], v[96:99]
	v_mfma_f32_16x16x32_bf16 v[96:99], v[212:215], v[196:199], v[64:67]
	s_mov_b32 m0, s26
	v_lshl_add_u64 v[192:193], v[220:221], 0, s[92:93]
	s_barrier
	s_nop 2
	ds_read_b128 v[64:67], v251 offset:49152
	ds_read_b128 v[68:71], v251 offset:50176
	ds_read_b128 v[72:75], v251 offset:51200
	ds_read_b128 v[76:79], v251 offset:52224
	ds_read_b128 v[176:179], v251 offset:53248
	ds_read_b128 v[180:183], v251 offset:54272
	ds_read_b128 v[184:187], v251 offset:55296
	ds_read_b128 v[188:191], v251 offset:56320
	global_load_lds_dwordx4 v[192:193], off
	v_lshl_add_u64 v[192:193], v[222:223], 0, s[92:93]
	s_mov_b32 m0, s27
	s_nop 0
	global_load_lds_dwordx4 v[192:193], off
	s_barrier
	s_waitcnt lgkmcnt(0)
	s_waitcnt lgkmcnt(0)
	v_mfma_f32_16x16x32_bf16 v[92:95], v[56:59], v[64:67], v[92:95]
	v_mfma_f32_16x16x32_bf16 v[88:91], v[80:83], v[64:67], v[88:91]
	v_mfma_f32_16x16x32_bf16 v[44:47], v[56:59], v[72:75], v[44:47]
	v_mfma_f32_16x16x32_bf16 v[40:43], v[80:83], v[72:75], v[40:43]
	v_mfma_f32_16x16x32_bf16 v[28:31], v[56:59], v[176:179], v[28:31]
	v_mfma_f32_16x16x32_bf16 v[24:27], v[80:83], v[176:179], v[24:27]
	v_mfma_f32_16x16x32_bf16 v[12:15], v[56:59], v[184:187], v[12:15]
	v_mfma_f32_16x16x32_bf16 v[8:11], v[80:83], v[184:187], v[8:11]
	v_mfma_f32_16x16x32_bf16 v[92:95], v[60:63], v[68:71], v[92:95]
	v_mfma_f32_16x16x32_bf16 v[88:91], v[84:87], v[68:71], v[88:91]
	v_mfma_f32_16x16x32_bf16 v[44:47], v[60:63], v[76:79], v[44:47]
	v_mfma_f32_16x16x32_bf16 v[40:43], v[84:87], v[76:79], v[40:43]
	v_mfma_f32_16x16x32_bf16 v[28:31], v[60:63], v[180:183], v[28:31]
	v_mfma_f32_16x16x32_bf16 v[24:27], v[84:87], v[180:183], v[24:27]
	v_mfma_f32_16x16x32_bf16 v[12:15], v[60:63], v[188:191], v[12:15]
	v_mfma_f32_16x16x32_bf16 v[8:11], v[84:87], v[188:191], v[8:11]
	s_barrier
	s_add_u32 s72, s72, 0x200080
	s_addc_u32 s73, s73, 0
	s_add_i32 s67, s68, s21
	v_lshl_add_u64 v[56:57], s[72:73], 0, v[160:161]
	s_mov_b32 m0, s67
	s_nop 0
	global_load_lds_dwordx4 v[56:57], off
	v_lshl_add_u64 v[56:57], s[72:73], 0, v[170:171]
	s_add_i32 m0, s67, 0x2000
	s_nop 0
	global_load_lds_dwordx4 v[56:57], off
	s_waitcnt vmcnt(6)
	s_barrier
	v_mfma_f32_16x16x32_bf16 v[48:51], v[200:203], v[64:67], v[48:51]
	v_mfma_f32_16x16x32_bf16 v[84:87], v[204:207], v[68:71], v[48:51]
	v_mfma_f32_16x16x32_bf16 v[48:51], v[208:211], v[64:67], v[52:55]
	v_mfma_f32_16x16x32_bf16 v[36:39], v[200:203], v[72:75], v[36:39]
	v_mfma_f32_16x16x32_bf16 v[32:35], v[208:211], v[72:75], v[32:35]
	v_mfma_f32_16x16x32_bf16 v[20:23], v[200:203], v[176:179], v[20:23]
	v_mfma_f32_16x16x32_bf16 v[16:19], v[208:211], v[176:179], v[16:19]
	v_mfma_f32_16x16x32_bf16 v[4:7], v[200:203], v[184:187], v[4:7]
	v_mfma_f32_16x16x32_bf16 v[0:3], v[208:211], v[184:187], v[0:3]
	v_mfma_f32_16x16x32_bf16 v[80:83], v[212:215], v[68:71], v[48:51]
	v_mfma_f32_16x16x32_bf16 v[36:39], v[204:207], v[76:79], v[36:39]
	v_mfma_f32_16x16x32_bf16 v[32:35], v[212:215], v[76:79], v[32:35]
	v_mfma_f32_16x16x32_bf16 v[20:23], v[204:207], v[180:183], v[20:23]
	v_mfma_f32_16x16x32_bf16 v[16:19], v[212:215], v[180:183], v[16:19]
	v_mfma_f32_16x16x32_bf16 v[4:7], v[204:207], v[188:191], v[4:7]
	v_mfma_f32_16x16x32_bf16 v[0:3], v[212:215], v[188:191], v[0:3]
	s_add_i32 s66, s66, 2
	s_add_u32 s4, s4, 0x100
	s_addc_u32 s5, s5, 0
	s_add_u32 s45, s45, 0x100
	s_addc_u32 s47, s47, 0
	s_cmpk_gt_u32 s66, 0x7d
	s_cbranch_scc0 .LBB0_1227
	s_barrier
	v_lshl_add_u32 v176, s17, 8, v248
	v_lshl_or_b32 v186, s16, 8, v250
	v_ashrrev_i32_e32 v187, 31, v186
	v_or_b32_e32 v178, 16, v176
	v_lshlrev_b64 v[216:217], 1, v[186:187]
	v_ashrrev_i32_e32 v177, 31, v176
	v_ashrrev_i32_e32 v179, 31, v178
	v_lshl_add_u64 v[48:49], s[28:29], 0, v[216:217]
	v_lshlrev_b64 v[238:239], 12, v[176:177]
	v_lshlrev_b64 v[220:221], 12, v[178:179]
	v_lshl_add_u64 v[50:51], v[48:49], 0, v[238:239]
	v_lshl_add_u64 v[48:49], v[48:49], 0, v[220:221]
	v_lshl_add_u64 v[180:181], v[176:177], 3, s[8:9]
	s_mov_b32 s4, 0x40000
	global_load_dwordx2 v[240:241], v[50:51], off
	global_load_dwordx2 v[234:235], v[50:51], off offset:32
	global_load_dwordx2 v[232:233], v[50:51], off offset:256
	global_load_dwordx2 v[230:231], v[50:51], off offset:288
	global_load_dwordx2 v[224:225], v[48:49], off
	global_load_dwordx2 v[214:215], v[48:49], off offset:32
	global_load_dwordx2 v[210:211], v[48:49], off offset:256
	global_load_dwordx2 v[206:207], v[48:49], off offset:288
	v_lshlrev_b64 v[48:49], 2, v[186:187]
	v_add_co_u32_e32 v204, vcc, s4, v180
	v_lshl_add_u64 v[50:51], s[6:7], 0, v[48:49]
	v_lshl_add_u64 v[52:53], s[42:43], 0, v[48:49]
	v_addc_co_u32_e32 v205, vcc, 0, v181, vcc
	global_load_dwordx4 v[72:75], v[50:51], off
	global_load_dwordx4 v[76:79], v[52:53], off
	global_load_dwordx4 v[64:67], v[50:51], off offset:64
	global_load_dwordx4 v[68:71], v[52:53], off offset:64
	global_load_dwordx4 v[56:59], v[50:51], off offset:512
	global_load_dwordx4 v[60:63], v[52:53], off offset:512
	s_nop 0
	global_load_dwordx4 v[48:51], v[50:51], off offset:576
	s_nop 0
	global_load_dwordx4 v[52:55], v[52:53], off offset:576
	v_lshl_add_u64 v[178:179], v[178:179], 3, s[8:9]
	global_load_dwordx2 v[182:183], v[180:181], off
	global_load_dwordx2 v[184:185], v[204:205], off
	global_load_dwordx2 v[228:229], v[178:179], off
	v_add_co_u32_e32 v178, vcc, s4, v178
	s_mov_b32 s89, 0x40000
	s_nop 0
	v_addc_co_u32_e32 v179, vcc, 0, v179, vcc
	global_load_dwordx2 v[226:227], v[178:179], off
	global_load_dwordx2 v[202:203], v[180:181], off offset:256
	global_load_dwordx2 v[200:201], v[204:205], off offset:256
	global_load_dwordx2 v[198:199], v[180:181], off offset:384
	global_load_dwordx2 v[196:197], v[204:205], off offset:384
	v_lshl_add_u64 v[238:239], s[28:29], 0, v[238:239]
	v_lshl_add_u64 v[238:239], v[238:239], 0, v[216:217]
	v_cmp_lt_i32_e64 s[4:5], 0, v247
	s_mov_b64 s[14:15], -1
	v_cmp_eq_u32_e32 vcc, 1, v247
	s_waitcnt vmcnt(0)
	v_lshlrev_b32_e32 v242, 16, v240
	v_and_b32_e32 v240, 0xffff0000, v240
	v_lshlrev_b32_e32 v244, 16, v241
	v_and_b32_e32 v243, 0xffff0000, v241
	v_cvt_f32_u32_e32 v179, v182
	v_cvt_f32_u32_e32 v178, v184
	v_cvt_f32_i32_e32 v182, v185
	v_cvt_f32_i32_e32 v183, v183
	v_pk_fma_f32 v[178:179], v[178:179], s[88:89], v[182:183] op_sel_hi:[1,0,1]
	s_nop 0
	v_pk_mul_f32 v[236:237], v[178:179], s[94:95] op_sel_hi:[1,0]
	s_nop 0
	v_fma_f32 v178, -v237, v237, v236
	v_add_f32_e32 v178, 0x3727c5ac, v178
	v_rsq_f32_e32 v236, v178
	global_load_dwordx2 v[194:195], v[180:181], off offset:1024
	global_load_dwordx2 v[192:193], v[204:205], off offset:1024
	global_load_dwordx2 v[190:191], v[180:181], off offset:1152
	global_load_dwordx2 v[188:189], v[204:205], off offset:1152
	global_load_dwordx2 v[184:185], v[180:181], off offset:1280
	global_load_dwordx2 v[182:183], v[204:205], off offset:1280
	s_nop 0
	global_load_dwordx2 v[180:181], v[180:181], off offset:1408
	s_nop 0
	global_load_dwordx2 v[178:179], v[204:205], off offset:1408
	v_or_b32_e32 v204, 32, v176
	v_ashrrev_i32_e32 v205, 31, v204
	v_lshlrev_b64 v[204:205], 12, v[204:205]
	v_lshl_add_u64 v[204:205], s[28:29], 0, v[204:205]
	v_lshl_add_u64 v[204:205], v[204:205], 0, v[216:217]
	global_load_dwordx2 v[222:223], v[204:205], off
	global_load_dwordx2 v[218:219], v[204:205], off offset:32
	global_load_dwordx2 v[212:213], v[204:205], off offset:256
	global_load_dwordx2 v[208:209], v[204:205], off offset:288
	v_sub_f32_e32 v241, v240, v237
	v_sub_f32_e32 v240, v242, v237
	v_sub_f32_e32 v243, v243, v237
	v_sub_f32_e32 v242, v244, v237
	v_pk_mul_f32 v[242:243], v[242:243], v[236:237] op_sel_hi:[1,0]
	v_pk_mul_f32 v[240:241], v[240:241], v[236:237] op_sel_hi:[1,0]
	v_pk_fma_f32 v[242:243], v[74:75], v[242:243], v[78:79]
	v_pk_fma_f32 v[240:241], v[72:73], v[240:241], v[76:77]
	v_pk_fma_f32 v[158:159], v[242:243], s[62:63], v[158:159] op_sel_hi:[1,0,1]
	v_pk_fma_f32 v[156:157], v[240:241], s[62:63], v[156:157] op_sel_hi:[1,0,1]
	v_mov_b32_e32 v243, v159
	v_cvt_pk_bf16_f32 v240, v156, v157
	v_cvt_pk_bf16_f32 v241, v158, v159
	global_store_dwordx2 v[238:239], v[240:241], off
	v_pk_mov_b32 v[240:241], v[156:157], v[158:159] op_sel:[1,0]
	v_mov_b32_e32 v242, v156
	v_mul_f32_e32 v157, v157, v157
	v_pk_add_f32 v[240:241], v[240:241], v[242:243]
	v_fmac_f32_e32 v157, v156, v156
	v_mul_f32_e32 v156, v159, v159
	v_add_f32_e32 v240, v240, v241
	v_fmac_f32_e32 v156, v158, v158
	v_add_f32_e32 v241, 0, v240
	v_add_f32_e32 v240, v157, v156
	v_lshlrev_b32_e32 v156, 16, v234
	v_and_b32_e32 v157, 0xffff0000, v234
	v_lshlrev_b32_e32 v158, 16, v235
	v_and_b32_e32 v159, 0xffff0000, v235
	v_sub_f32_e32 v157, v157, v237
	v_sub_f32_e32 v156, v156, v237
	v_sub_f32_e32 v159, v159, v237
	v_sub_f32_e32 v158, v158, v237
	v_pk_mul_f32 v[158:159], v[158:159], v[236:237] op_sel_hi:[1,0]
	v_pk_mul_f32 v[156:157], v[156:157], v[236:237] op_sel_hi:[1,0]
	v_pk_fma_f32 v[158:159], v[66:67], v[158:159], v[70:71]
	v_pk_fma_f32 v[156:157], v[64:65], v[156:157], v[68:69]
	v_pk_fma_f32 v[154:155], v[158:159], s[62:63], v[154:155] op_sel_hi:[1,0,1]
	v_pk_fma_f32 v[152:153], v[156:157], s[62:63], v[152:153] op_sel_hi:[1,0,1]
	v_mov_b32_e32 v159, v155
	v_cvt_pk_bf16_f32 v156, v152, v153
	v_cvt_pk_bf16_f32 v157, v154, v155
	global_store_dwordx2 v[238:239], v[156:157], off offset:32
	v_pk_mov_b32 v[156:157], v[152:153], v[154:155] op_sel:[1,0]
	v_mul_f32_e32 v153, v153, v153
	v_mov_b32_e32 v158, v152
	v_fmac_f32_e32 v153, v152, v152
	v_mul_f32_e32 v152, v155, v155
	v_pk_add_f32 v[156:157], v[156:157], v[158:159]
	v_fmac_f32_e32 v152, v154, v154
	v_pk_add_f32 v[156:157], v[156:157], v[156:157] op_sel_hi:[0,1]
	v_add_f32_e32 v152, v153, v152
	v_add_f32_e32 v156, v240, v152
	v_lshlrev_b32_e32 v152, 16, v232
	v_and_b32_e32 v153, 0xffff0000, v232
	v_lshlrev_b32_e32 v154, 16, v233
	v_and_b32_e32 v155, 0xffff0000, v233
	v_sub_f32_e32 v153, v153, v237
	v_sub_f32_e32 v152, v152, v237
	v_sub_f32_e32 v155, v155, v237
	v_sub_f32_e32 v154, v154, v237
	v_pk_mul_f32 v[154:155], v[154:155], v[236:237] op_sel_hi:[1,0]
	v_pk_mul_f32 v[152:153], v[152:153], v[236:237] op_sel_hi:[1,0]
	v_pk_fma_f32 v[154:155], v[58:59], v[154:155], v[62:63]
	v_pk_fma_f32 v[152:153], v[56:57], v[152:153], v[60:61]
	v_pk_fma_f32 v[150:151], v[154:155], s[62:63], v[150:151] op_sel_hi:[1,0,1]
	v_pk_fma_f32 v[148:149], v[152:153], s[62:63], v[148:149] op_sel_hi:[1,0,1]
	v_add_f32_e32 v155, v150, v151
	v_cvt_pk_bf16_f32 v152, v148, v149
	v_cvt_pk_bf16_f32 v153, v150, v151
	global_store_dwordx2 v[238:239], v[152:153], off offset:256
	v_add_f32_e32 v153, v148, v149
	v_mul_f32_e32 v149, v149, v149
	v_fmac_f32_e32 v149, v148, v148
	v_mul_f32_e32 v148, v151, v151
	v_fmac_f32_e32 v148, v150, v150
	v_add_f32_e32 v148, v149, v148
	v_add_f32_e32 v158, v148, v156
	v_lshlrev_b32_e32 v148, 16, v230
	v_and_b32_e32 v149, 0xffff0000, v230
	v_lshlrev_b32_e32 v150, 16, v231
	v_and_b32_e32 v151, 0xffff0000, v231
	v_sub_f32_e32 v149, v149, v237
	v_sub_f32_e32 v148, v148, v237
	v_sub_f32_e32 v151, v151, v237
	v_sub_f32_e32 v150, v150, v237
	v_pk_mul_f32 v[150:151], v[150:151], v[236:237] op_sel_hi:[1,0]
	v_pk_mul_f32 v[148:149], v[148:149], v[236:237] op_sel_hi:[1,0]
	v_pk_fma_f32 v[150:151], v[50:51], v[150:151], v[54:55]
	v_pk_fma_f32 v[148:149], v[48:49], v[148:149], v[52:53]
	v_pk_fma_f32 v[146:147], v[150:151], s[62:63], v[146:147] op_sel_hi:[1,0,1]
	v_pk_fma_f32 v[144:145], v[148:149], s[62:63], v[144:145] op_sel_hi:[1,0,1]
	v_mov_b32_e32 v156, v146
	v_cvt_pk_bf16_f32 v148, v144, v145
	v_cvt_pk_bf16_f32 v149, v146, v147
	v_mov_b32_e32 v152, v144
	v_mov_b32_e32 v154, v145
	v_mov_b32_e32 v240, v147
	global_store_dwordx2 v[238:239], v[148:149], off offset:288
	v_pk_add_f32 v[148:149], v[152:153], v[154:155]
	v_pk_add_f32 v[150:151], v[156:157], v[240:241]
	v_mul_f32_e32 v145, v145, v145
	v_pk_add_f32 v[148:149], v[148:149], v[150:151]
	v_fmac_f32_e32 v145, v144, v144
	v_mul_f32_e32 v144, v147, v147
	v_pk_add_f32 v[148:149], v[148:149], v[148:149] op_sel:[0,1] op_sel_hi:[1,0]
	v_fmac_f32_e32 v144, v146, v146
	v_add_f32_e32 v144, v145, v144
	v_mov_b32_e32 v145, v148
	v_add_f32_e32 v144, v144, v158
	s_nop 0
	v_permlane16_swap_b32_e32 v148, v145
	v_add_f32_e32 v148, v148, v145
	v_mov_b32_e32 v145, v144
	s_nop 1
	v_permlane16_swap_b32_e32 v144, v145
	v_add_f32_e32 v146, v144, v145
	v_mov_b32_e32 v149, v148
	v_mov_b32_e32 v147, v146
	s_nop 0
	v_permlane32_swap_b32_e32 v148, v149
	v_permlane32_swap_b32_e32 v146, v147
	v_mov_b64_e32 v[144:145], 0x100000
	s_and_saveexec_b64 s[12:13], s[4:5]
	v_readlane_b32 s66, v255, 7
	v_readlane_b32 s67, v255, 8
	s_cbranch_execz .LBB0_1232
	v_cmp_eq_u32_e64 s[4:5], 1, v247
	s_mov_b64 s[14:15], 0
	v_mov_b64_e32 v[144:145], 0x100000
	s_and_saveexec_b64 s[16:17], s[4:5]
	s_mov_b64 s[14:15], exec
	v_mov_b64_e32 v[144:145], 0x140000
	s_or_b64 exec, exec, s[16:17]
	s_orn2_b64 s[14:15], s[14:15], exec
	v_mov_b32_e32 v148, v146
	v_mov_b32_e32 v149, v147
